# GEMM K-loops: first two MFMAs of each 32-MFMA block issued before the block's opening barrier
# speedup vs baseline: 1.0038x; 1.0038x over previous
.LBB0_246:
	s_add_u32 s3, s34, 0xfff80080
	s_addc_u32 s6, s35, -1
	s_add_i32 s7, 0, 0x10000
	s_cmp_eq_u32 s2, 28
	s_cselect_b32 s43, s15, s6
	s_cselect_b32 s42, s47, s3
	s_cselect_b32 s39, s13, s50
	s_cselect_b32 s38, s48, s49
	s_add_i32 s3, 0, 0x14000
	v_add_u32_e32 v156, s7, v145
	v_add_u32_e32 v172, s3, v145
	ds_read_b128 v[140:143], v156
	ds_read_b128 v[148:151], v156 offset:1024
	ds_read_b128 v[152:155], v156 offset:2048
	ds_read_b128 v[156:159], v156 offset:3072
	ds_read_b128 v[160:163], v172
	ds_read_b128 v[164:167], v172 offset:1024
	ds_read_b128 v[168:171], v172 offset:2048
	ds_read_b128 v[172:175], v172 offset:3072
	v_lshl_add_u64 v[176:177], s[34:35], 0, v[136:137]
	s_add_i32 m0, s18, 0xc000
	ds_read_b128 v[182:185], v147
	ds_read_b128 v[186:189], v147 offset:1024
	ds_read_b128 v[190:193], v147 offset:2048
	ds_read_b128 v[214:217], v147 offset:3072
	ds_read_b128 v[218:221], v147 offset:4096
	ds_read_b128 v[222:225], v147 offset:5120
	ds_read_b128 v[226:229], v147 offset:6144
	ds_read_b128 v[230:233], v147 offset:7168
	global_load_lds_dwordx4 v[176:177], off
	v_lshl_add_u64 v[176:177], s[34:35], 0, v[138:139]
	s_add_i32 m0, s18, 0xe000
	s_nop 0
	global_load_lds_dwordx4 v[176:177], off
	s_waitcnt vmcnt(8)
	s_waitcnt lgkmcnt(0)
	v_mfma_f32_16x16x32_bf16 v[126:129], v[140:143], v[182:185], v[126:129]
	v_mfma_f32_16x16x32_bf16 v[122:125], v[152:155], v[182:185], v[122:125]
	s_barrier
	s_setprio 1
	s_waitcnt lgkmcnt(0)
	v_mfma_f32_16x16x32_bf16 v[118:121], v[140:143], v[190:193], v[118:121]
	v_mfma_f32_16x16x32_bf16 v[110:113], v[152:155], v[190:193], v[110:113]
	v_mfma_f32_16x16x32_bf16 v[102:105], v[140:143], v[218:221], v[102:105]
	v_mfma_f32_16x16x32_bf16 v[92:95], v[152:155], v[218:221], v[92:95]
	v_mfma_f32_16x16x32_bf16 v[84:87], v[140:143], v[226:229], v[84:87]
	v_mfma_f32_16x16x32_bf16 v[76:79], v[152:155], v[226:229], v[76:79]
	v_mfma_f32_16x16x32_bf16 v[126:129], v[148:151], v[186:189], v[126:129]
	v_mfma_f32_16x16x32_bf16 v[122:125], v[156:159], v[186:189], v[122:125]
	v_mfma_f32_16x16x32_bf16 v[118:121], v[148:151], v[214:217], v[118:121]
	v_mfma_f32_16x16x32_bf16 v[110:113], v[156:159], v[214:217], v[110:113]
	v_mfma_f32_16x16x32_bf16 v[102:105], v[148:151], v[222:225], v[102:105]
	v_mfma_f32_16x16x32_bf16 v[92:95], v[156:159], v[222:225], v[92:95]
	v_mfma_f32_16x16x32_bf16 v[84:87], v[148:151], v[230:233], v[84:87]
	v_mfma_f32_16x16x32_bf16 v[76:79], v[156:159], v[230:233], v[76:79]
	s_setprio 0
	s_setprio 1
	v_mfma_f32_16x16x32_bf16 v[114:117], v[160:163], v[182:185], v[114:117]
	v_mfma_f32_16x16x32_bf16 v[106:109], v[168:171], v[182:185], v[106:109]
	v_mfma_f32_16x16x32_bf16 v[98:101], v[160:163], v[190:193], v[98:101]
	v_mfma_f32_16x16x32_bf16 v[88:91], v[168:171], v[190:193], v[88:91]
	v_mfma_f32_16x16x32_bf16 v[80:83], v[160:163], v[218:221], v[80:83]
	v_mfma_f32_16x16x32_bf16 v[72:75], v[168:171], v[218:221], v[72:75]
	v_mfma_f32_16x16x32_bf16 v[68:71], v[160:163], v[226:229], v[68:71]
	v_mfma_f32_16x16x32_bf16 v[64:67], v[168:171], v[226:229], v[64:67]
	v_mfma_f32_16x16x32_bf16 v[114:117], v[164:167], v[186:189], v[114:117]
	v_mfma_f32_16x16x32_bf16 v[106:109], v[172:175], v[186:189], v[106:109]
	v_mfma_f32_16x16x32_bf16 v[98:101], v[164:167], v[214:217], v[98:101]
	v_mfma_f32_16x16x32_bf16 v[88:91], v[172:175], v[214:217], v[88:91]
	v_mfma_f32_16x16x32_bf16 v[80:83], v[164:167], v[222:225], v[80:83]
	v_mfma_f32_16x16x32_bf16 v[72:75], v[172:175], v[222:225], v[72:75]
	v_mfma_f32_16x16x32_bf16 v[68:71], v[164:167], v[230:233], v[68:71]
	v_mfma_f32_16x16x32_bf16 v[64:67], v[172:175], v[230:233], v[64:67]
	s_setprio 0
	s_barrier
	s_add_i32 s6, s7, s17
	v_lshl_add_u64 v[176:177], s[38:39], 0, v[96:97]
	s_mov_b32 m0, s6
	ds_read_b128 v[182:185], v147 offset:16384
	ds_read_b128 v[186:189], v147 offset:17408
	ds_read_b128 v[190:193], v147 offset:18432
	ds_read_b128 v[214:217], v147 offset:19456
	ds_read_b128 v[218:221], v147 offset:20480
	ds_read_b128 v[222:225], v147 offset:21504
	ds_read_b128 v[226:229], v147 offset:22528
	ds_read_b128 v[230:233], v147 offset:23552
	global_load_lds_dwordx4 v[176:177], off
	s_add_i32 m0, s6, 0x2000
	s_add_u32 s6, s38, 0x80000
	v_lshl_add_u64 v[178:179], s[38:39], 0, v[130:131]
	s_addc_u32 s7, s39, 0
	s_add_i32 s3, s3, s17
	global_load_lds_dwordx4 v[178:179], off
	v_lshl_add_u64 v[180:181], s[6:7], 0, v[96:97]
	s_mov_b32 m0, s3
	v_lshl_add_u64 v[194:195], s[42:43], 0, v[132:133]
	global_load_lds_dwordx4 v[180:181], off
	v_lshl_add_u64 v[180:181], s[6:7], 0, v[130:131]
	s_add_i32 m0, s3, 0x2000
	s_nop 0
	global_load_lds_dwordx4 v[180:181], off
	v_lshl_add_u64 v[180:181], s[42:43], 0, v[134:135]
	s_mov_b32 m0, s18
	s_nop 0
	global_load_lds_dwordx4 v[180:181], off
	s_mov_b32 m0, s19
	s_nop 0
	global_load_lds_dwordx4 v[194:195], off
	s_waitcnt vmcnt(8)
	s_waitcnt lgkmcnt(0)
	v_mfma_f32_16x16x32_bf16 v[60:63], v[140:143], v[182:185], v[60:63]
	v_mfma_f32_16x16x32_bf16 v[56:59], v[152:155], v[182:185], v[56:59]
	s_barrier
	s_setprio 1
	s_waitcnt lgkmcnt(0)
	v_mfma_f32_16x16x32_bf16 v[52:55], v[140:143], v[190:193], v[52:55]
	v_mfma_f32_16x16x32_bf16 v[44:47], v[152:155], v[190:193], v[44:47]
	v_mfma_f32_16x16x32_bf16 v[36:39], v[140:143], v[218:221], v[36:39]
	v_mfma_f32_16x16x32_bf16 v[28:31], v[152:155], v[218:221], v[28:31]
	v_mfma_f32_16x16x32_bf16 v[20:23], v[140:143], v[226:229], v[20:23]
	v_mfma_f32_16x16x32_bf16 v[12:15], v[152:155], v[226:229], v[12:15]
	v_mfma_f32_16x16x32_bf16 v[60:63], v[148:151], v[186:189], v[60:63]
	v_mfma_f32_16x16x32_bf16 v[56:59], v[156:159], v[186:189], v[56:59]
	v_mfma_f32_16x16x32_bf16 v[52:55], v[148:151], v[214:217], v[52:55]
	v_mfma_f32_16x16x32_bf16 v[44:47], v[156:159], v[214:217], v[44:47]
	v_mfma_f32_16x16x32_bf16 v[36:39], v[148:151], v[222:225], v[36:39]
	v_mfma_f32_16x16x32_bf16 v[28:31], v[156:159], v[222:225], v[28:31]
	v_mfma_f32_16x16x32_bf16 v[20:23], v[148:151], v[230:233], v[20:23]
	v_mfma_f32_16x16x32_bf16 v[12:15], v[156:159], v[230:233], v[12:15]
	s_setprio 0
	s_setprio 1
	v_mfma_f32_16x16x32_bf16 v[48:51], v[160:163], v[182:185], v[48:51]
	v_mfma_f32_16x16x32_bf16 v[40:43], v[168:171], v[182:185], v[40:43]
	v_mfma_f32_16x16x32_bf16 v[32:35], v[160:163], v[190:193], v[32:35]
	v_mfma_f32_16x16x32_bf16 v[24:27], v[168:171], v[190:193], v[24:27]
	v_mfma_f32_16x16x32_bf16 v[16:19], v[160:163], v[218:221], v[16:19]
	v_mfma_f32_16x16x32_bf16 v[8:11], v[168:171], v[218:221], v[8:11]
	v_mfma_f32_16x16x32_bf16 v[4:7], v[160:163], v[226:229], v[4:7]
	v_mfma_f32_16x16x32_bf16 v[0:3], v[168:171], v[226:229], v[0:3]
	v_mfma_f32_16x16x32_bf16 v[48:51], v[164:167], v[186:189], v[48:51]
	v_mfma_f32_16x16x32_bf16 v[40:43], v[172:175], v[186:189], v[40:43]
	v_mfma_f32_16x16x32_bf16 v[32:35], v[164:167], v[214:217], v[32:35]
	v_mfma_f32_16x16x32_bf16 v[24:27], v[172:175], v[214:217], v[24:27]
	v_mfma_f32_16x16x32_bf16 v[16:19], v[164:167], v[222:225], v[16:19]
	v_mfma_f32_16x16x32_bf16 v[8:11], v[172:175], v[222:225], v[8:11]
	v_mfma_f32_16x16x32_bf16 v[4:7], v[164:167], v[230:233], v[4:7]
	v_mfma_f32_16x16x32_bf16 v[0:3], v[172:175], v[230:233], v[0:3]
	s_setprio 0
	s_barrier
	s_add_i32 s3, 0, 0x18000
	s_add_i32 s51, 0, 0x1c000
	v_add_u32_e32 v156, s3, v145
	v_add_u32_e32 v172, s51, v145
	ds_read_b128 v[140:143], v156
	ds_read_b128 v[148:151], v156 offset:1024
	ds_read_b128 v[152:155], v156 offset:2048
	ds_read_b128 v[156:159], v156 offset:3072
	ds_read_b128 v[160:163], v172
	ds_read_b128 v[164:167], v172 offset:1024
	ds_read_b128 v[168:171], v172 offset:2048
	ds_read_b128 v[172:175], v172 offset:3072
	s_add_u32 s6, s42, 0x80000
	s_addc_u32 s7, s43, 0
	s_mov_b32 m0, s20
	v_lshl_add_u64 v[202:203], s[6:7], 0, v[134:135]
	ds_read_b128 v[182:185], v147 offset:32768
	ds_read_b128 v[186:189], v147 offset:33792
	ds_read_b128 v[190:193], v147 offset:34816
	ds_read_b128 v[214:217], v147 offset:35840
	ds_read_b128 v[218:221], v147 offset:36864
	ds_read_b128 v[222:225], v147 offset:37888
	ds_read_b128 v[226:229], v147 offset:38912
	ds_read_b128 v[230:233], v147 offset:39936
	global_load_lds_dwordx4 v[202:203], off
	v_lshl_add_u64 v[202:203], s[6:7], 0, v[132:133]
	s_mov_b32 m0, s36
	s_nop 0
	global_load_lds_dwordx4 v[202:203], off
	s_waitcnt vmcnt(8)
	s_waitcnt lgkmcnt(0)
	v_mfma_f32_16x16x32_bf16 v[126:129], v[140:143], v[182:185], v[126:129]
	v_mfma_f32_16x16x32_bf16 v[122:125], v[152:155], v[182:185], v[122:125]
	s_barrier
	s_setprio 1
	s_waitcnt lgkmcnt(0)
	v_mfma_f32_16x16x32_bf16 v[118:121], v[140:143], v[190:193], v[118:121]
	v_mfma_f32_16x16x32_bf16 v[110:113], v[152:155], v[190:193], v[110:113]
	v_mfma_f32_16x16x32_bf16 v[102:105], v[140:143], v[218:221], v[102:105]
	v_mfma_f32_16x16x32_bf16 v[92:95], v[152:155], v[218:221], v[92:95]
	v_mfma_f32_16x16x32_bf16 v[84:87], v[140:143], v[226:229], v[84:87]
	v_mfma_f32_16x16x32_bf16 v[76:79], v[152:155], v[226:229], v[76:79]
	v_mfma_f32_16x16x32_bf16 v[126:129], v[148:151], v[186:189], v[126:129]
	v_mfma_f32_16x16x32_bf16 v[122:125], v[156:159], v[186:189], v[122:125]
	v_mfma_f32_16x16x32_bf16 v[118:121], v[148:151], v[214:217], v[118:121]
	v_mfma_f32_16x16x32_bf16 v[110:113], v[156:159], v[214:217], v[110:113]
	v_mfma_f32_16x16x32_bf16 v[102:105], v[148:151], v[222:225], v[102:105]
	v_mfma_f32_16x16x32_bf16 v[92:95], v[156:159], v[222:225], v[92:95]
	v_mfma_f32_16x16x32_bf16 v[84:87], v[148:151], v[230:233], v[84:87]
	v_mfma_f32_16x16x32_bf16 v[76:79], v[156:159], v[230:233], v[76:79]
	s_setprio 0
	s_setprio 1
	v_mfma_f32_16x16x32_bf16 v[114:117], v[160:163], v[182:185], v[114:117]
	v_mfma_f32_16x16x32_bf16 v[106:109], v[168:171], v[182:185], v[106:109]
	v_mfma_f32_16x16x32_bf16 v[98:101], v[160:163], v[190:193], v[98:101]
	v_mfma_f32_16x16x32_bf16 v[88:91], v[168:171], v[190:193], v[88:91]
	v_mfma_f32_16x16x32_bf16 v[80:83], v[160:163], v[218:221], v[80:83]
	v_mfma_f32_16x16x32_bf16 v[72:75], v[168:171], v[218:221], v[72:75]
	v_mfma_f32_16x16x32_bf16 v[68:71], v[160:163], v[226:229], v[68:71]
	v_mfma_f32_16x16x32_bf16 v[64:67], v[168:171], v[226:229], v[64:67]
	v_mfma_f32_16x16x32_bf16 v[114:117], v[164:167], v[186:189], v[114:117]
	v_mfma_f32_16x16x32_bf16 v[106:109], v[172:175], v[186:189], v[106:109]
	v_mfma_f32_16x16x32_bf16 v[98:101], v[164:167], v[214:217], v[98:101]
	v_mfma_f32_16x16x32_bf16 v[88:91], v[172:175], v[214:217], v[88:91]
	v_mfma_f32_16x16x32_bf16 v[80:83], v[164:167], v[222:225], v[80:83]
	v_mfma_f32_16x16x32_bf16 v[72:75], v[172:175], v[222:225], v[72:75]
	v_mfma_f32_16x16x32_bf16 v[68:71], v[164:167], v[230:233], v[68:71]
	v_mfma_f32_16x16x32_bf16 v[64:67], v[172:175], v[230:233], v[64:67]
	s_setprio 0
	s_barrier
	s_add_i32 s3, s3, s17
	v_lshl_add_u64 v[176:177], v[176:177], 0, s[30:31]
	s_mov_b32 m0, s3
	ds_read_b128 v[182:185], v147 offset:49152
	ds_read_b128 v[186:189], v147 offset:50176
	ds_read_b128 v[190:193], v147 offset:51200
	ds_read_b128 v[214:217], v147 offset:52224
	ds_read_b128 v[218:221], v147 offset:53248
	ds_read_b128 v[222:225], v147 offset:54272
	ds_read_b128 v[226:229], v147 offset:55296
	ds_read_b128 v[230:233], v147 offset:56320
	global_load_lds_dwordx4 v[176:177], off
	s_add_i32 m0, s3, 0x2000
	s_add_u32 s6, s38, 0x80080
	v_lshl_add_u64 v[176:177], v[178:179], 0, s[30:31]
	s_addc_u32 s7, s39, 0
	s_add_i32 s3, s51, s17
	global_load_lds_dwordx4 v[176:177], off
	v_lshl_add_u64 v[176:177], s[6:7], 0, v[96:97]
	s_mov_b32 m0, s3
	s_nop 0
	global_load_lds_dwordx4 v[176:177], off
	v_lshl_add_u64 v[176:177], s[6:7], 0, v[130:131]
	s_add_i32 m0, s3, 0x2000
	s_nop 0
	global_load_lds_dwordx4 v[176:177], off
	v_lshl_add_u64 v[176:177], v[180:181], 0, s[30:31]
	s_mov_b32 m0, s37
	s_nop 0
	global_load_lds_dwordx4 v[176:177], off
	v_lshl_add_u64 v[176:177], v[194:195], 0, s[30:31]
	s_mov_b32 m0, s40
	s_nop 0
	global_load_lds_dwordx4 v[176:177], off
	s_waitcnt vmcnt(8)
	s_waitcnt lgkmcnt(0)
	v_mfma_f32_16x16x32_bf16 v[60:63], v[140:143], v[182:185], v[60:63]
	v_mfma_f32_16x16x32_bf16 v[56:59], v[152:155], v[182:185], v[56:59]
	s_barrier
	s_setprio 1
	s_waitcnt lgkmcnt(0)
	v_mfma_f32_16x16x32_bf16 v[52:55], v[140:143], v[190:193], v[52:55]
	v_mfma_f32_16x16x32_bf16 v[44:47], v[152:155], v[190:193], v[44:47]
	v_mfma_f32_16x16x32_bf16 v[36:39], v[140:143], v[218:221], v[36:39]
	v_mfma_f32_16x16x32_bf16 v[28:31], v[152:155], v[218:221], v[28:31]
	v_mfma_f32_16x16x32_bf16 v[20:23], v[140:143], v[226:229], v[20:23]
	v_mfma_f32_16x16x32_bf16 v[12:15], v[152:155], v[226:229], v[12:15]
	v_mfma_f32_16x16x32_bf16 v[60:63], v[148:151], v[186:189], v[60:63]
	v_mfma_f32_16x16x32_bf16 v[56:59], v[156:159], v[186:189], v[56:59]
	v_mfma_f32_16x16x32_bf16 v[52:55], v[148:151], v[214:217], v[52:55]
	v_mfma_f32_16x16x32_bf16 v[44:47], v[156:159], v[214:217], v[44:47]
	v_mfma_f32_16x16x32_bf16 v[36:39], v[148:151], v[222:225], v[36:39]
	v_mfma_f32_16x16x32_bf16 v[28:31], v[156:159], v[222:225], v[28:31]
	v_mfma_f32_16x16x32_bf16 v[20:23], v[148:151], v[230:233], v[20:23]
	v_mfma_f32_16x16x32_bf16 v[12:15], v[156:159], v[230:233], v[12:15]
	s_setprio 0
	s_setprio 1
	v_mfma_f32_16x16x32_bf16 v[48:51], v[160:163], v[182:185], v[48:51]
	v_mfma_f32_16x16x32_bf16 v[40:43], v[168:171], v[182:185], v[40:43]
	v_mfma_f32_16x16x32_bf16 v[32:35], v[160:163], v[190:193], v[32:35]
	v_mfma_f32_16x16x32_bf16 v[24:27], v[168:171], v[190:193], v[24:27]
	v_mfma_f32_16x16x32_bf16 v[16:19], v[160:163], v[218:221], v[16:19]
	v_mfma_f32_16x16x32_bf16 v[8:11], v[168:171], v[218:221], v[8:11]
	v_mfma_f32_16x16x32_bf16 v[4:7], v[160:163], v[226:229], v[4:7]
	v_mfma_f32_16x16x32_bf16 v[0:3], v[168:171], v[226:229], v[0:3]
	v_mfma_f32_16x16x32_bf16 v[48:51], v[164:167], v[186:189], v[48:51]
	v_mfma_f32_16x16x32_bf16 v[40:43], v[172:175], v[186:189], v[40:43]
	v_mfma_f32_16x16x32_bf16 v[32:35], v[164:167], v[214:217], v[32:35]
	v_mfma_f32_16x16x32_bf16 v[24:27], v[172:175], v[214:217], v[24:27]
	v_mfma_f32_16x16x32_bf16 v[16:19], v[164:167], v[222:225], v[16:19]
	v_mfma_f32_16x16x32_bf16 v[8:11], v[172:175], v[222:225], v[8:11]
	v_mfma_f32_16x16x32_bf16 v[4:7], v[164:167], v[230:233], v[4:7]
	v_mfma_f32_16x16x32_bf16 v[0:3], v[172:175], v[230:233], v[0:3]
	s_setprio 0
	s_barrier
	s_add_i32 s2, s2, 2
	s_add_u32 s34, s34, 0x100
	s_addc_u32 s35, s35, 0
	s_add_u32 s49, s49, 0x100
	s_addc_u32 s50, s50, 0
	s_cmp_gt_u32 s2, 29
	s_cbranch_scc0 .LBB0_246
	s_and_b64 vcc, exec, s[10:11]
	s_cbranch_vccz .LBB0_249
	s_barrier

.LBB0_421:
	s_add_u32 s3, s22, 0xfffe0080
	s_addc_u32 s6, s23, -1
	s_add_i32 s7, 0, 0x10000
	s_cmp_eq_u32 s2, 4
	s_cselect_b32 s35, s4, s6
	s_cselect_b32 s34, s5, s3
	v_add_u32_e32 v96, s7, v176
	s_cselect_b32 s25, s9, s17
	s_cselect_b32 s24, s13, s15
	s_add_i32 s3, 0, 0x14000
	ds_read_b128 v[56:59], v96
	ds_read_b128 v[60:63], v96 offset:1024
	ds_read_b128 v[138:141], v96 offset:2048
	ds_read_b128 v[142:145], v96 offset:3072
	v_add_u32_e32 v96, s3, v176
	ds_read_b128 v[146:149], v96
	ds_read_b128 v[150:153], v96 offset:1024
	ds_read_b128 v[154:157], v96 offset:2048
	ds_read_b128 v[170:173], v96 offset:3072
	v_lshl_add_u64 v[174:175], s[22:23], 0, v[166:167]
	s_add_i32 m0, s75, 0xc000
	ds_read_b128 v[182:185], v177
	ds_read_b128 v[186:189], v177 offset:1024
	ds_read_b128 v[190:193], v177 offset:2048
	ds_read_b128 v[214:217], v177 offset:3072
	ds_read_b128 v[218:221], v177 offset:4096
	ds_read_b128 v[222:225], v177 offset:5120
	ds_read_b128 v[226:229], v177 offset:6144
	ds_read_b128 v[230:233], v177 offset:7168
	global_load_lds_dwordx4 v[174:175], off
	v_lshl_add_u64 v[174:175], s[22:23], 0, v[168:169]
	s_add_i32 m0, s75, 0xe000
	s_nop 0
	global_load_lds_dwordx4 v[174:175], off
	s_waitcnt vmcnt(8)
	s_waitcnt lgkmcnt(0)
	v_mfma_f32_16x16x32_bf16 v[134:137], v[56:59], v[182:185], v[134:137]
	v_mfma_f32_16x16x32_bf16 v[130:133], v[138:141], v[182:185], v[130:133]
	s_barrier
	s_setprio 1
	s_waitcnt lgkmcnt(0)
	v_mfma_f32_16x16x32_bf16 v[118:121], v[56:59], v[190:193], v[118:121]
	v_mfma_f32_16x16x32_bf16 v[114:117], v[138:141], v[190:193], v[114:117]
	v_mfma_f32_16x16x32_bf16 v[102:105], v[56:59], v[218:221], v[102:105]
	v_mfma_f32_16x16x32_bf16 v[98:101], v[138:141], v[218:221], v[98:101]
	v_mfma_f32_16x16x32_bf16 v[84:87], v[56:59], v[226:229], v[84:87]
	v_mfma_f32_16x16x32_bf16 v[80:83], v[138:141], v[226:229], v[80:83]
	v_mfma_f32_16x16x32_bf16 v[134:137], v[60:63], v[186:189], v[134:137]
	v_mfma_f32_16x16x32_bf16 v[130:133], v[142:145], v[186:189], v[130:133]
	v_mfma_f32_16x16x32_bf16 v[118:121], v[60:63], v[214:217], v[118:121]
	v_mfma_f32_16x16x32_bf16 v[114:117], v[142:145], v[214:217], v[114:117]
	v_mfma_f32_16x16x32_bf16 v[102:105], v[60:63], v[222:225], v[102:105]
	v_mfma_f32_16x16x32_bf16 v[98:101], v[142:145], v[222:225], v[98:101]
	v_mfma_f32_16x16x32_bf16 v[84:87], v[60:63], v[230:233], v[84:87]
	v_mfma_f32_16x16x32_bf16 v[80:83], v[142:145], v[230:233], v[80:83]
	s_setprio 0
	s_setprio 1
	v_mfma_f32_16x16x32_bf16 v[126:129], v[146:149], v[182:185], v[126:129]
	v_mfma_f32_16x16x32_bf16 v[122:125], v[154:157], v[182:185], v[122:125]
	v_mfma_f32_16x16x32_bf16 v[110:113], v[146:149], v[190:193], v[110:113]
	v_mfma_f32_16x16x32_bf16 v[106:109], v[154:157], v[190:193], v[106:109]
	v_mfma_f32_16x16x32_bf16 v[92:95], v[146:149], v[218:221], v[92:95]
	v_mfma_f32_16x16x32_bf16 v[88:91], v[154:157], v[218:221], v[88:91]
	v_mfma_f32_16x16x32_bf16 v[76:79], v[146:149], v[226:229], v[76:79]
	v_mfma_f32_16x16x32_bf16 v[72:75], v[154:157], v[226:229], v[72:75]
	v_mfma_f32_16x16x32_bf16 v[126:129], v[150:153], v[186:189], v[126:129]
	v_mfma_f32_16x16x32_bf16 v[122:125], v[170:173], v[186:189], v[122:125]
	v_mfma_f32_16x16x32_bf16 v[110:113], v[150:153], v[214:217], v[110:113]
	v_mfma_f32_16x16x32_bf16 v[106:109], v[170:173], v[214:217], v[106:109]
	v_mfma_f32_16x16x32_bf16 v[92:95], v[150:153], v[222:225], v[92:95]
	v_mfma_f32_16x16x32_bf16 v[88:91], v[170:173], v[222:225], v[88:91]
	v_mfma_f32_16x16x32_bf16 v[76:79], v[150:153], v[230:233], v[76:79]
	v_mfma_f32_16x16x32_bf16 v[72:75], v[170:173], v[230:233], v[72:75]
	s_setprio 0
	s_barrier
	s_add_i32 s6, s7, s74
	v_lshl_add_u64 v[174:175], s[24:25], 0, v[160:161]
	s_mov_b32 m0, s6
	ds_read_b128 v[182:185], v177 offset:16384
	ds_read_b128 v[186:189], v177 offset:17408
	ds_read_b128 v[190:193], v177 offset:18432
	ds_read_b128 v[214:217], v177 offset:19456
	ds_read_b128 v[218:221], v177 offset:20480
	ds_read_b128 v[222:225], v177 offset:21504
	ds_read_b128 v[226:229], v177 offset:22528
	ds_read_b128 v[230:233], v177 offset:23552
	global_load_lds_dwordx4 v[174:175], off
	s_add_i32 m0, s6, 0x2000
	s_add_u32 s6, s24, 0x20000
	v_lshl_add_u64 v[178:179], s[24:25], 0, v[164:165]
	s_addc_u32 s7, s25, 0
	s_add_i32 s3, s3, s74
	global_load_lds_dwordx4 v[178:179], off
	v_lshl_add_u64 v[180:181], s[6:7], 0, v[160:161]
	s_mov_b32 m0, s3
	v_lshl_add_u64 v[194:195], s[34:35], 0, v[162:163]
	global_load_lds_dwordx4 v[180:181], off
	v_lshl_add_u64 v[180:181], s[6:7], 0, v[164:165]
	s_add_i32 m0, s3, 0x2000
	s_nop 0
	global_load_lds_dwordx4 v[180:181], off
	v_lshl_add_u64 v[180:181], s[34:35], 0, v[158:159]
	s_mov_b32 m0, s75
	s_nop 0
	global_load_lds_dwordx4 v[180:181], off
	s_mov_b32 m0, s82
	s_nop 0
	global_load_lds_dwordx4 v[194:195], off
	s_waitcnt vmcnt(8)
	s_waitcnt lgkmcnt(0)
	v_mfma_f32_16x16x32_bf16 v[68:71], v[56:59], v[182:185], v[68:71]
	v_mfma_f32_16x16x32_bf16 v[64:67], v[138:141], v[182:185], v[64:67]
	s_barrier
	s_setprio 1
	s_waitcnt lgkmcnt(0)
	v_mfma_f32_16x16x32_bf16 v[44:47], v[56:59], v[190:193], v[44:47]
	v_mfma_f32_16x16x32_bf16 v[40:43], v[138:141], v[190:193], v[40:43]
	v_mfma_f32_16x16x32_bf16 v[28:31], v[56:59], v[218:221], v[28:31]
	v_mfma_f32_16x16x32_bf16 v[24:27], v[138:141], v[218:221], v[24:27]
	v_mfma_f32_16x16x32_bf16 v[12:15], v[56:59], v[226:229], v[12:15]
	v_mfma_f32_16x16x32_bf16 v[8:11], v[138:141], v[226:229], v[8:11]
	v_mfma_f32_16x16x32_bf16 v[68:71], v[60:63], v[186:189], v[68:71]
	v_mfma_f32_16x16x32_bf16 v[64:67], v[142:145], v[186:189], v[64:67]
	v_mfma_f32_16x16x32_bf16 v[44:47], v[60:63], v[214:217], v[44:47]
	v_mfma_f32_16x16x32_bf16 v[40:43], v[142:145], v[214:217], v[40:43]
	v_mfma_f32_16x16x32_bf16 v[28:31], v[60:63], v[222:225], v[28:31]
	v_mfma_f32_16x16x32_bf16 v[24:27], v[142:145], v[222:225], v[24:27]
	v_mfma_f32_16x16x32_bf16 v[12:15], v[60:63], v[230:233], v[12:15]
	v_mfma_f32_16x16x32_bf16 v[8:11], v[142:145], v[230:233], v[8:11]
	s_setprio 0
	s_setprio 1
	v_mfma_f32_16x16x32_bf16 v[52:55], v[146:149], v[182:185], v[52:55]
	v_mfma_f32_16x16x32_bf16 v[48:51], v[154:157], v[182:185], v[48:51]
	v_mfma_f32_16x16x32_bf16 v[36:39], v[146:149], v[190:193], v[36:39]
	v_mfma_f32_16x16x32_bf16 v[32:35], v[154:157], v[190:193], v[32:35]
	v_mfma_f32_16x16x32_bf16 v[20:23], v[146:149], v[218:221], v[20:23]
	v_mfma_f32_16x16x32_bf16 v[16:19], v[154:157], v[218:221], v[16:19]
	v_mfma_f32_16x16x32_bf16 v[4:7], v[146:149], v[226:229], v[4:7]
	v_mfma_f32_16x16x32_bf16 v[0:3], v[154:157], v[226:229], v[0:3]
	v_mfma_f32_16x16x32_bf16 v[52:55], v[150:153], v[186:189], v[52:55]
	v_mfma_f32_16x16x32_bf16 v[48:51], v[170:173], v[186:189], v[48:51]
	v_mfma_f32_16x16x32_bf16 v[36:39], v[150:153], v[214:217], v[36:39]
	v_mfma_f32_16x16x32_bf16 v[32:35], v[170:173], v[214:217], v[32:35]
	v_mfma_f32_16x16x32_bf16 v[20:23], v[150:153], v[222:225], v[20:23]
	v_mfma_f32_16x16x32_bf16 v[16:19], v[170:173], v[222:225], v[16:19]
	v_mfma_f32_16x16x32_bf16 v[4:7], v[150:153], v[230:233], v[4:7]
	v_mfma_f32_16x16x32_bf16 v[0:3], v[170:173], v[230:233], v[0:3]
	s_setprio 0
	s_barrier
	s_add_i32 s3, 0, 0x18000
	v_add_u32_e32 v96, s3, v176
	s_add_i32 s18, 0, 0x1c000
	ds_read_b128 v[56:59], v96
	ds_read_b128 v[60:63], v96 offset:1024
	ds_read_b128 v[138:141], v96 offset:2048
	ds_read_b128 v[142:145], v96 offset:3072
	v_add_u32_e32 v96, s18, v176
	ds_read_b128 v[146:149], v96
	ds_read_b128 v[150:153], v96 offset:1024
	ds_read_b128 v[154:157], v96 offset:2048
	ds_read_b128 v[170:173], v96 offset:3072
	s_add_u32 s6, s34, 0x20000
	s_addc_u32 s7, s35, 0
	s_mov_b32 m0, s83
	v_lshl_add_u64 v[202:203], s[6:7], 0, v[158:159]
	ds_read_b128 v[182:185], v177 offset:32768
	ds_read_b128 v[186:189], v177 offset:33792
	ds_read_b128 v[190:193], v177 offset:34816
	ds_read_b128 v[214:217], v177 offset:35840
	ds_read_b128 v[218:221], v177 offset:36864
	ds_read_b128 v[222:225], v177 offset:37888
	ds_read_b128 v[226:229], v177 offset:38912
	ds_read_b128 v[230:233], v177 offset:39936
	global_load_lds_dwordx4 v[202:203], off
	v_lshl_add_u64 v[202:203], s[6:7], 0, v[162:163]
	s_mov_b32 m0, s88
	s_nop 0
	global_load_lds_dwordx4 v[202:203], off
	s_waitcnt vmcnt(8)
	s_waitcnt lgkmcnt(0)
	v_mfma_f32_16x16x32_bf16 v[134:137], v[56:59], v[182:185], v[134:137]
	v_mfma_f32_16x16x32_bf16 v[130:133], v[138:141], v[182:185], v[130:133]
	s_barrier
	s_setprio 1
	s_waitcnt lgkmcnt(0)
	v_mfma_f32_16x16x32_bf16 v[118:121], v[56:59], v[190:193], v[118:121]
	v_mfma_f32_16x16x32_bf16 v[114:117], v[138:141], v[190:193], v[114:117]
	v_mfma_f32_16x16x32_bf16 v[102:105], v[56:59], v[218:221], v[102:105]
	v_mfma_f32_16x16x32_bf16 v[98:101], v[138:141], v[218:221], v[98:101]
	v_mfma_f32_16x16x32_bf16 v[84:87], v[56:59], v[226:229], v[84:87]
	v_mfma_f32_16x16x32_bf16 v[80:83], v[138:141], v[226:229], v[80:83]
	v_mfma_f32_16x16x32_bf16 v[134:137], v[60:63], v[186:189], v[134:137]
	v_mfma_f32_16x16x32_bf16 v[130:133], v[142:145], v[186:189], v[130:133]
	v_mfma_f32_16x16x32_bf16 v[118:121], v[60:63], v[214:217], v[118:121]
	v_mfma_f32_16x16x32_bf16 v[114:117], v[142:145], v[214:217], v[114:117]
	v_mfma_f32_16x16x32_bf16 v[102:105], v[60:63], v[222:225], v[102:105]
	v_mfma_f32_16x16x32_bf16 v[98:101], v[142:145], v[222:225], v[98:101]
	v_mfma_f32_16x16x32_bf16 v[84:87], v[60:63], v[230:233], v[84:87]
	v_mfma_f32_16x16x32_bf16 v[80:83], v[142:145], v[230:233], v[80:83]
	s_setprio 0
	s_setprio 1
	v_mfma_f32_16x16x32_bf16 v[126:129], v[146:149], v[182:185], v[126:129]
	v_mfma_f32_16x16x32_bf16 v[122:125], v[154:157], v[182:185], v[122:125]
	v_mfma_f32_16x16x32_bf16 v[110:113], v[146:149], v[190:193], v[110:113]
	v_mfma_f32_16x16x32_bf16 v[106:109], v[154:157], v[190:193], v[106:109]
	v_mfma_f32_16x16x32_bf16 v[92:95], v[146:149], v[218:221], v[92:95]
	v_mfma_f32_16x16x32_bf16 v[88:91], v[154:157], v[218:221], v[88:91]
	v_mfma_f32_16x16x32_bf16 v[76:79], v[146:149], v[226:229], v[76:79]
	v_mfma_f32_16x16x32_bf16 v[72:75], v[154:157], v[226:229], v[72:75]
	v_mfma_f32_16x16x32_bf16 v[126:129], v[150:153], v[186:189], v[126:129]
	v_mfma_f32_16x16x32_bf16 v[122:125], v[170:173], v[186:189], v[122:125]
	v_mfma_f32_16x16x32_bf16 v[110:113], v[150:153], v[214:217], v[110:113]
	v_mfma_f32_16x16x32_bf16 v[106:109], v[170:173], v[214:217], v[106:109]
	v_mfma_f32_16x16x32_bf16 v[92:95], v[150:153], v[222:225], v[92:95]
	v_mfma_f32_16x16x32_bf16 v[88:91], v[170:173], v[222:225], v[88:91]
	v_mfma_f32_16x16x32_bf16 v[76:79], v[150:153], v[230:233], v[76:79]
	v_mfma_f32_16x16x32_bf16 v[72:75], v[170:173], v[230:233], v[72:75]
	s_setprio 0
	s_barrier
	s_add_i32 s3, s3, s74
	v_lshl_add_u64 v[174:175], v[174:175], 0, s[30:31]
	s_mov_b32 m0, s3
	ds_read_b128 v[182:185], v177 offset:49152
	ds_read_b128 v[186:189], v177 offset:50176
	ds_read_b128 v[190:193], v177 offset:51200
	ds_read_b128 v[214:217], v177 offset:52224
	ds_read_b128 v[218:221], v177 offset:53248
	ds_read_b128 v[222:225], v177 offset:54272
	ds_read_b128 v[226:229], v177 offset:55296
	ds_read_b128 v[230:233], v177 offset:56320
	global_load_lds_dwordx4 v[174:175], off
	s_add_i32 m0, s3, 0x2000
	s_add_u32 s6, s24, 0x20080
	v_lshl_add_u64 v[174:175], v[178:179], 0, s[30:31]
	s_addc_u32 s7, s25, 0
	s_add_i32 s3, s18, s74
	global_load_lds_dwordx4 v[174:175], off
	v_lshl_add_u64 v[174:175], s[6:7], 0, v[160:161]
	s_mov_b32 m0, s3
	s_nop 0
	global_load_lds_dwordx4 v[174:175], off
	v_lshl_add_u64 v[174:175], s[6:7], 0, v[164:165]
	s_add_i32 m0, s3, 0x2000
	s_nop 0
	global_load_lds_dwordx4 v[174:175], off
	v_lshl_add_u64 v[174:175], v[180:181], 0, s[30:31]
	s_mov_b32 m0, s97
	s_nop 0
	global_load_lds_dwordx4 v[174:175], off
	v_lshl_add_u64 v[174:175], v[194:195], 0, s[30:31]
	s_mov_b32 m0, s50
	s_nop 0
	global_load_lds_dwordx4 v[174:175], off
	s_waitcnt vmcnt(8)
	s_waitcnt lgkmcnt(0)
	v_mfma_f32_16x16x32_bf16 v[68:71], v[56:59], v[182:185], v[68:71]
	v_mfma_f32_16x16x32_bf16 v[64:67], v[138:141], v[182:185], v[64:67]
	s_barrier
	s_setprio 1
	s_waitcnt lgkmcnt(0)
	v_mfma_f32_16x16x32_bf16 v[44:47], v[56:59], v[190:193], v[44:47]
	v_mfma_f32_16x16x32_bf16 v[40:43], v[138:141], v[190:193], v[40:43]
	v_mfma_f32_16x16x32_bf16 v[28:31], v[56:59], v[218:221], v[28:31]
	v_mfma_f32_16x16x32_bf16 v[24:27], v[138:141], v[218:221], v[24:27]
	v_mfma_f32_16x16x32_bf16 v[12:15], v[56:59], v[226:229], v[12:15]
	v_mfma_f32_16x16x32_bf16 v[8:11], v[138:141], v[226:229], v[8:11]
	v_mfma_f32_16x16x32_bf16 v[68:71], v[60:63], v[186:189], v[68:71]
	v_mfma_f32_16x16x32_bf16 v[64:67], v[142:145], v[186:189], v[64:67]
	v_mfma_f32_16x16x32_bf16 v[44:47], v[60:63], v[214:217], v[44:47]
	v_mfma_f32_16x16x32_bf16 v[40:43], v[142:145], v[214:217], v[40:43]
	v_mfma_f32_16x16x32_bf16 v[28:31], v[60:63], v[222:225], v[28:31]
	v_mfma_f32_16x16x32_bf16 v[24:27], v[142:145], v[222:225], v[24:27]
	v_mfma_f32_16x16x32_bf16 v[12:15], v[60:63], v[230:233], v[12:15]
	v_mfma_f32_16x16x32_bf16 v[8:11], v[142:145], v[230:233], v[8:11]
	s_setprio 0
	s_setprio 1
	v_mfma_f32_16x16x32_bf16 v[52:55], v[146:149], v[182:185], v[52:55]
	v_mfma_f32_16x16x32_bf16 v[48:51], v[154:157], v[182:185], v[48:51]
	v_mfma_f32_16x16x32_bf16 v[36:39], v[146:149], v[190:193], v[36:39]
	v_mfma_f32_16x16x32_bf16 v[32:35], v[154:157], v[190:193], v[32:35]
	v_mfma_f32_16x16x32_bf16 v[20:23], v[146:149], v[218:221], v[20:23]
	v_mfma_f32_16x16x32_bf16 v[16:19], v[154:157], v[218:221], v[16:19]
	v_mfma_f32_16x16x32_bf16 v[4:7], v[146:149], v[226:229], v[4:7]
	v_mfma_f32_16x16x32_bf16 v[0:3], v[154:157], v[226:229], v[0:3]
	v_mfma_f32_16x16x32_bf16 v[52:55], v[150:153], v[186:189], v[52:55]
	v_mfma_f32_16x16x32_bf16 v[48:51], v[170:173], v[186:189], v[48:51]
	v_mfma_f32_16x16x32_bf16 v[36:39], v[150:153], v[214:217], v[36:39]
	v_mfma_f32_16x16x32_bf16 v[32:35], v[170:173], v[214:217], v[32:35]
	v_mfma_f32_16x16x32_bf16 v[20:23], v[150:153], v[222:225], v[20:23]
	v_mfma_f32_16x16x32_bf16 v[16:19], v[170:173], v[222:225], v[16:19]
	v_mfma_f32_16x16x32_bf16 v[4:7], v[150:153], v[230:233], v[4:7]
	v_mfma_f32_16x16x32_bf16 v[0:3], v[170:173], v[230:233], v[0:3]
	s_setprio 0
	s_barrier
	s_add_i32 s2, s2, 2
	s_add_u32 s22, s22, 0x100
	s_addc_u32 s23, s23, 0
	s_add_u32 s15, s15, 0x100
	s_addc_u32 s17, s17, 0
	s_cmp_gt_u32 s2, 5
	s_cbranch_scc0 .LBB0_421
	s_and_b64 vcc, exec, s[58:59]
	s_cbranch_vccz .LBB0_424
	s_barrier

.LBB0_680:
	s_ashr_i32 s35, s34, 31
	s_lshl_b64 s[2:3], s[34:35], 17
	v_readlane_b32 s6, v251, 63
	s_add_u32 s38, s6, s2
	v_readlane_b32 s2, v252, 0
	s_addc_u32 s39, s2, s3
	s_and_b64 s[2:3], s[0:1], exec
	s_cselect_b32 s59, s39, s49
	s_cselect_b32 s58, s38, s48
	s_ashr_i32 s25, s24, 31
	s_lshl_b64 s[2:3], s[24:25], 17
	s_add_u32 s42, s5, s2
	s_addc_u32 s43, s17, s3
	s_and_b64 s[2:3], s[0:1], exec
	s_cselect_b32 s51, s43, s53
	s_cselect_b32 s50, s42, s52
	s_add_i32 s25, 0, 0x10000
	s_add_i32 s6, 0, 0x14000
	v_add_u32_e32 v96, s25, v148
	v_add_u32_e32 v198, s6, v148
	ds_read_b128 v[0:3], v96
	ds_read_b128 v[4:7], v96 offset:1024
	ds_read_b128 v[8:11], v96 offset:2048
	ds_read_b128 v[12:15], v96 offset:3072
	ds_read_b128 v[16:19], v198
	ds_read_b128 v[20:23], v198 offset:1024
	ds_read_b128 v[24:27], v198 offset:2048
	ds_read_b128 v[28:31], v198 offset:3072
	s_add_u32 s2, s48, 0x10080
	s_addc_u32 s3, s49, 0
	s_add_i32 s56, s18, 0xc000
	v_lshl_add_u64 v[64:65], s[2:3], 0, v[138:139]
	s_mov_b32 m0, s56
	ds_read_b128 v[32:35], v149
	ds_read_b128 v[36:39], v149 offset:1024
	ds_read_b128 v[40:43], v149 offset:2048
	ds_read_b128 v[44:47], v149 offset:3072
	ds_read_b128 v[48:51], v149 offset:4096
	ds_read_b128 v[52:55], v149 offset:5120
	ds_read_b128 v[56:59], v149 offset:6144
	ds_read_b128 v[60:63], v149 offset:7168
	global_load_lds_dwordx4 v[64:65], off
	v_lshl_add_u64 v[64:65], s[2:3], 0, v[142:143]
	s_add_i32 s2, s18, 0xe000
	s_mov_b32 m0, s2
	s_nop 0
	global_load_lds_dwordx4 v[64:65], off
	s_waitcnt vmcnt(8)
	s_waitcnt lgkmcnt(0)
	v_mfma_f32_16x16x32_bf16 v[64:67], v[0:3], v[32:35], 0
	v_mfma_f32_16x16x32_bf16 v[68:71], v[8:11], v[32:35], 0
	s_barrier
	s_setprio 1
	s_waitcnt lgkmcnt(0)
	v_mfma_f32_16x16x32_bf16 v[72:75], v[0:3], v[40:43], 0
	v_mfma_f32_16x16x32_bf16 v[76:79], v[8:11], v[40:43], 0
	v_mfma_f32_16x16x32_bf16 v[80:83], v[0:3], v[48:51], 0
	v_mfma_f32_16x16x32_bf16 v[84:87], v[8:11], v[48:51], 0
	v_mfma_f32_16x16x32_bf16 v[88:91], v[0:3], v[56:59], 0
	v_mfma_f32_16x16x32_bf16 v[92:95], v[8:11], v[56:59], 0
	v_mfma_f32_16x16x32_bf16 v[64:67], v[4:7], v[36:39], v[64:67]
	v_mfma_f32_16x16x32_bf16 v[68:71], v[12:15], v[36:39], v[68:71]
	v_mfma_f32_16x16x32_bf16 v[72:75], v[4:7], v[44:47], v[72:75]
	v_mfma_f32_16x16x32_bf16 v[76:79], v[12:15], v[44:47], v[76:79]
	v_mfma_f32_16x16x32_bf16 v[80:83], v[4:7], v[52:55], v[80:83]
	v_mfma_f32_16x16x32_bf16 v[84:87], v[12:15], v[52:55], v[84:87]
	v_mfma_f32_16x16x32_bf16 v[88:91], v[4:7], v[60:63], v[88:91]
	v_mfma_f32_16x16x32_bf16 v[92:95], v[12:15], v[60:63], v[92:95]
	s_setprio 0
	s_setprio 1
	v_mfma_f32_16x16x32_bf16 v[98:101], v[16:19], v[32:35], 0
	v_mfma_f32_16x16x32_bf16 v[32:35], v[24:27], v[32:35], 0
	v_mfma_f32_16x16x32_bf16 v[98:101], v[20:23], v[36:39], v[98:101]
	v_mfma_f32_16x16x32_bf16 v[32:35], v[28:31], v[36:39], v[32:35]
	v_mfma_f32_16x16x32_bf16 v[36:39], v[16:19], v[40:43], 0
	v_mfma_f32_16x16x32_bf16 v[40:43], v[24:27], v[40:43], 0
	v_mfma_f32_16x16x32_bf16 v[36:39], v[20:23], v[44:47], v[36:39]
	v_mfma_f32_16x16x32_bf16 v[40:43], v[28:31], v[44:47], v[40:43]
	v_mfma_f32_16x16x32_bf16 v[44:47], v[16:19], v[48:51], 0
	v_mfma_f32_16x16x32_bf16 v[48:51], v[24:27], v[48:51], 0
	v_mfma_f32_16x16x32_bf16 v[44:47], v[20:23], v[52:55], v[44:47]
	v_mfma_f32_16x16x32_bf16 v[48:51], v[28:31], v[52:55], v[48:51]
	v_mfma_f32_16x16x32_bf16 v[52:55], v[16:19], v[56:59], 0
	v_mfma_f32_16x16x32_bf16 v[56:59], v[24:27], v[56:59], 0
	v_mfma_f32_16x16x32_bf16 v[52:55], v[20:23], v[60:63], v[52:55]
	v_mfma_f32_16x16x32_bf16 v[56:59], v[28:31], v[60:63], v[56:59]
	s_setprio 0
	s_barrier
	s_add_i32 s25, s25, s4
	v_lshl_add_u64 v[146:147], s[52:53], 0, v[140:141]
	s_mov_b64 vcc, 0x100
	s_add_i32 s3, s25, 0x2000
	v_lshl_add_u64 v[130:131], v[146:147], 0, vcc
	s_mov_b32 m0, s25
	v_lshl_add_u64 v[178:179], s[52:53], 0, v[144:145]
	s_add_u32 s60, s52, 0x10100
	ds_read_b128 v[60:63], v149 offset:16384
	ds_read_b128 v[102:105], v149 offset:17408
	ds_read_b128 v[106:109], v149 offset:18432
	ds_read_b128 v[110:113], v149 offset:19456
	ds_read_b128 v[114:117], v149 offset:20480
	ds_read_b128 v[118:121], v149 offset:21504
	ds_read_b128 v[122:125], v149 offset:22528
	ds_read_b128 v[126:129], v149 offset:23552
	global_load_lds_dwordx4 v[130:131], off
	v_lshl_add_u64 v[130:131], v[178:179], 0, vcc
	s_mov_b32 m0, s3
	s_addc_u32 s61, s53, 0
	s_add_i32 s6, s6, s4
	global_load_lds_dwordx4 v[130:131], off
	v_lshl_add_u64 v[130:131], s[60:61], 0, v[140:141]
	s_mov_b32 m0, s6
	s_add_i32 s7, s6, 0x2000
	global_load_lds_dwordx4 v[130:131], off
	v_lshl_add_u64 v[130:131], s[60:61], 0, v[144:145]
	s_mov_b32 m0, s7
	v_lshl_add_u64 v[180:181], s[48:49], 0, v[138:139]
	global_load_lds_dwordx4 v[130:131], off
	v_lshl_add_u64 v[130:131], v[180:181], 0, vcc
	s_mov_b32 m0, s18
	v_lshl_add_u64 v[194:195], s[48:49], 0, v[142:143]
	global_load_lds_dwordx4 v[130:131], off
	v_lshl_add_u64 v[130:131], v[194:195], 0, vcc
	s_mov_b32 m0, s19
	s_nop 0
	global_load_lds_dwordx4 v[130:131], off
	s_waitcnt vmcnt(8)
	s_waitcnt lgkmcnt(0)
	v_mfma_f32_16x16x32_bf16 v[130:133], v[0:3], v[60:63], 0
	v_mfma_f32_16x16x32_bf16 v[150:153], v[0:3], v[106:109], 0
	s_barrier
	s_setprio 1
	s_waitcnt lgkmcnt(0)
	v_mfma_f32_16x16x32_bf16 v[158:161], v[0:3], v[114:117], 0
	v_mfma_f32_16x16x32_bf16 v[0:3], v[0:3], v[122:125], 0
	v_mfma_f32_16x16x32_bf16 v[130:133], v[4:7], v[102:105], v[130:133]
	v_mfma_f32_16x16x32_bf16 v[134:137], v[8:11], v[60:63], 0
	v_mfma_f32_16x16x32_bf16 v[150:153], v[4:7], v[110:113], v[150:153]
	v_mfma_f32_16x16x32_bf16 v[158:161], v[4:7], v[118:121], v[158:161]
	v_mfma_f32_16x16x32_bf16 v[0:3], v[4:7], v[126:129], v[0:3]
	v_mfma_f32_16x16x32_bf16 v[4:7], v[8:11], v[122:125], 0
	v_mfma_f32_16x16x32_bf16 v[134:137], v[12:15], v[102:105], v[134:137]
	v_mfma_f32_16x16x32_bf16 v[154:157], v[8:11], v[106:109], 0
	v_mfma_f32_16x16x32_bf16 v[162:165], v[8:11], v[114:117], 0
	v_mfma_f32_16x16x32_bf16 v[4:7], v[12:15], v[126:129], v[4:7]
	v_mfma_f32_16x16x32_bf16 v[154:157], v[12:15], v[110:113], v[154:157]
	v_mfma_f32_16x16x32_bf16 v[162:165], v[12:15], v[118:121], v[162:165]
	s_setprio 0
	s_setprio 1
	v_mfma_f32_16x16x32_bf16 v[8:11], v[16:19], v[60:63], 0
	v_mfma_f32_16x16x32_bf16 v[12:15], v[24:27], v[60:63], 0
	v_mfma_f32_16x16x32_bf16 v[8:11], v[20:23], v[102:105], v[8:11]
	v_mfma_f32_16x16x32_bf16 v[12:15], v[28:31], v[102:105], v[12:15]
	v_mfma_f32_16x16x32_bf16 v[60:63], v[16:19], v[106:109], 0
	v_mfma_f32_16x16x32_bf16 v[102:105], v[24:27], v[106:109], 0
	v_mfma_f32_16x16x32_bf16 v[106:109], v[16:19], v[114:117], 0
	v_mfma_f32_16x16x32_bf16 v[16:19], v[16:19], v[122:125], 0
	v_mfma_f32_16x16x32_bf16 v[60:63], v[20:23], v[110:113], v[60:63]
	v_mfma_f32_16x16x32_bf16 v[106:109], v[20:23], v[118:121], v[106:109]
	v_mfma_f32_16x16x32_bf16 v[16:19], v[20:23], v[126:129], v[16:19]
	v_mfma_f32_16x16x32_bf16 v[20:23], v[24:27], v[122:125], 0
	v_mfma_f32_16x16x32_bf16 v[102:105], v[28:31], v[110:113], v[102:105]
	v_mfma_f32_16x16x32_bf16 v[110:113], v[24:27], v[114:117], 0
	v_mfma_f32_16x16x32_bf16 v[20:23], v[28:31], v[126:129], v[20:23]
	v_mfma_f32_16x16x32_bf16 v[110:113], v[28:31], v[118:121], v[110:113]
	s_setprio 0
	s_barrier
	s_add_i32 s57, 0, 0x18000
	s_add_i32 s62, 0, 0x1c000
	v_add_u32_e32 v204, s57, v148
	v_add_u32_e32 v205, s62, v148
	ds_read_b128 v[24:27], v204
	ds_read_b128 v[28:31], v204 offset:1024
	ds_read_b128 v[114:117], v204 offset:2048
	ds_read_b128 v[118:121], v204 offset:3072
	ds_read_b128 v[122:125], v205
	ds_read_b128 v[126:129], v205 offset:1024
	ds_read_b128 v[166:169], v205 offset:2048
	ds_read_b128 v[170:173], v205 offset:3072
	s_add_u32 s60, s48, 0x10100
	s_addc_u32 s61, s49, 0
	s_mov_b32 m0, s20
	v_lshl_add_u64 v[202:203], s[60:61], 0, v[138:139]
	ds_read_b128 v[174:177], v149 offset:32768
	ds_read_b128 v[182:185], v149 offset:33792
	ds_read_b128 v[186:189], v149 offset:34816
	ds_read_b128 v[190:193], v149 offset:35840
	ds_read_b128 v[214:217], v149 offset:36864
	ds_read_b128 v[218:221], v149 offset:37888
	ds_read_b128 v[222:225], v149 offset:38912
	ds_read_b128 v[226:229], v149 offset:39936
	global_load_lds_dwordx4 v[202:203], off
	v_lshl_add_u64 v[202:203], s[60:61], 0, v[142:143]
	s_mov_b32 m0, s36
	s_nop 0
	global_load_lds_dwordx4 v[202:203], off
	s_waitcnt vmcnt(8)
	s_waitcnt lgkmcnt(0)
	v_mfma_f32_16x16x32_bf16 v[64:67], v[24:27], v[174:177], v[64:67]
	v_mfma_f32_16x16x32_bf16 v[68:71], v[114:117], v[174:177], v[68:71]
	s_barrier
	s_setprio 1
	s_waitcnt lgkmcnt(0)
	v_mfma_f32_16x16x32_bf16 v[72:75], v[24:27], v[186:189], v[72:75]
	v_mfma_f32_16x16x32_bf16 v[76:79], v[114:117], v[186:189], v[76:79]
	v_mfma_f32_16x16x32_bf16 v[80:83], v[24:27], v[214:217], v[80:83]
	v_mfma_f32_16x16x32_bf16 v[84:87], v[114:117], v[214:217], v[84:87]
	v_mfma_f32_16x16x32_bf16 v[88:91], v[24:27], v[222:225], v[88:91]
	v_mfma_f32_16x16x32_bf16 v[92:95], v[114:117], v[222:225], v[92:95]
	v_mfma_f32_16x16x32_bf16 v[64:67], v[28:31], v[182:185], v[64:67]
	v_mfma_f32_16x16x32_bf16 v[68:71], v[118:121], v[182:185], v[68:71]
	v_mfma_f32_16x16x32_bf16 v[72:75], v[28:31], v[190:193], v[72:75]
	v_mfma_f32_16x16x32_bf16 v[76:79], v[118:121], v[190:193], v[76:79]
	v_mfma_f32_16x16x32_bf16 v[80:83], v[28:31], v[218:221], v[80:83]
	v_mfma_f32_16x16x32_bf16 v[84:87], v[118:121], v[218:221], v[84:87]
	v_mfma_f32_16x16x32_bf16 v[88:91], v[28:31], v[226:229], v[88:91]
	v_mfma_f32_16x16x32_bf16 v[92:95], v[118:121], v[226:229], v[92:95]
	s_setprio 0
	s_setprio 1
	v_mfma_f32_16x16x32_bf16 v[98:101], v[122:125], v[174:177], v[98:101]
	v_mfma_f32_16x16x32_bf16 v[32:35], v[166:169], v[174:177], v[32:35]
	v_mfma_f32_16x16x32_bf16 v[36:39], v[122:125], v[186:189], v[36:39]
	v_mfma_f32_16x16x32_bf16 v[40:43], v[166:169], v[186:189], v[40:43]
	v_mfma_f32_16x16x32_bf16 v[44:47], v[122:125], v[214:217], v[44:47]
	v_mfma_f32_16x16x32_bf16 v[48:51], v[166:169], v[214:217], v[48:51]
	v_mfma_f32_16x16x32_bf16 v[52:55], v[122:125], v[222:225], v[52:55]
	v_mfma_f32_16x16x32_bf16 v[56:59], v[166:169], v[222:225], v[56:59]
	v_mfma_f32_16x16x32_bf16 v[98:101], v[126:129], v[182:185], v[98:101]
	v_mfma_f32_16x16x32_bf16 v[32:35], v[170:173], v[182:185], v[32:35]
	v_mfma_f32_16x16x32_bf16 v[36:39], v[126:129], v[190:193], v[36:39]
	v_mfma_f32_16x16x32_bf16 v[40:43], v[170:173], v[190:193], v[40:43]
	v_mfma_f32_16x16x32_bf16 v[44:47], v[126:129], v[218:221], v[44:47]
	v_mfma_f32_16x16x32_bf16 v[48:51], v[170:173], v[218:221], v[48:51]
	v_mfma_f32_16x16x32_bf16 v[52:55], v[126:129], v[226:229], v[52:55]
	v_mfma_f32_16x16x32_bf16 v[56:59], v[170:173], v[226:229], v[56:59]
	s_setprio 0
	s_barrier
	s_add_i32 s57, s57, s4
	s_mov_b64 vcc, 0x180
	s_add_i32 s35, s57, 0x2000
	v_lshl_add_u64 v[146:147], v[146:147], 0, vcc
	s_mov_b32 m0, s57
	s_add_u32 s60, s52, 0x10180
	ds_read_b128 v[174:177], v149 offset:49152
	ds_read_b128 v[182:185], v149 offset:50176
	ds_read_b128 v[186:189], v149 offset:51200
	ds_read_b128 v[190:193], v149 offset:52224
	ds_read_b128 v[214:217], v149 offset:53248
	ds_read_b128 v[218:221], v149 offset:54272
	ds_read_b128 v[222:225], v149 offset:55296
	ds_read_b128 v[226:229], v149 offset:56320
	global_load_lds_dwordx4 v[146:147], off
	v_lshl_add_u64 v[146:147], v[178:179], 0, vcc
	s_mov_b32 m0, s35
	s_addc_u32 s61, s53, 0
	s_add_i32 s52, s62, s4
	global_load_lds_dwordx4 v[146:147], off
	v_lshl_add_u64 v[146:147], s[60:61], 0, v[140:141]
	s_mov_b32 m0, s52
	s_add_i32 s53, s52, 0x2000
	global_load_lds_dwordx4 v[146:147], off
	v_lshl_add_u64 v[146:147], s[60:61], 0, v[144:145]
	s_mov_b32 m0, s53
	s_nop 0
	global_load_lds_dwordx4 v[146:147], off
	v_lshl_add_u64 v[146:147], v[180:181], 0, vcc
	s_mov_b32 m0, s45
	s_nop 0
	global_load_lds_dwordx4 v[146:147], off
	v_lshl_add_u64 v[146:147], v[194:195], 0, vcc
	s_mov_b32 m0, s47
	s_nop 0
	global_load_lds_dwordx4 v[146:147], off
	s_waitcnt vmcnt(8)
	s_waitcnt lgkmcnt(0)
	v_mfma_f32_16x16x32_bf16 v[130:133], v[24:27], v[174:177], v[130:133]
	v_mfma_f32_16x16x32_bf16 v[134:137], v[114:117], v[174:177], v[134:137]
	s_barrier
	s_setprio 1
	s_waitcnt lgkmcnt(0)
	v_mfma_f32_16x16x32_bf16 v[0:3], v[24:27], v[222:225], v[0:3]
	v_mfma_f32_16x16x32_bf16 v[4:7], v[114:117], v[222:225], v[4:7]
	v_mfma_f32_16x16x32_bf16 v[130:133], v[28:31], v[182:185], v[130:133]
	v_mfma_f32_16x16x32_bf16 v[134:137], v[118:121], v[182:185], v[134:137]
	v_mfma_f32_16x16x32_bf16 v[150:153], v[24:27], v[186:189], v[150:153]
	v_mfma_f32_16x16x32_bf16 v[154:157], v[114:117], v[186:189], v[154:157]
	v_mfma_f32_16x16x32_bf16 v[158:161], v[24:27], v[214:217], v[158:161]
	v_mfma_f32_16x16x32_bf16 v[162:165], v[114:117], v[214:217], v[162:165]
	v_mfma_f32_16x16x32_bf16 v[0:3], v[28:31], v[226:229], v[0:3]
	v_mfma_f32_16x16x32_bf16 v[4:7], v[118:121], v[226:229], v[4:7]
	v_mfma_f32_16x16x32_bf16 v[150:153], v[28:31], v[190:193], v[150:153]
	v_mfma_f32_16x16x32_bf16 v[154:157], v[118:121], v[190:193], v[154:157]
	v_mfma_f32_16x16x32_bf16 v[158:161], v[28:31], v[218:221], v[158:161]
	v_mfma_f32_16x16x32_bf16 v[162:165], v[118:121], v[218:221], v[162:165]
	s_setprio 0
	s_setprio 1
	v_mfma_f32_16x16x32_bf16 v[8:11], v[122:125], v[174:177], v[8:11]
	v_mfma_f32_16x16x32_bf16 v[12:15], v[166:169], v[174:177], v[12:15]
	v_mfma_f32_16x16x32_bf16 v[24:27], v[122:125], v[186:189], v[60:63]
	v_mfma_f32_16x16x32_bf16 v[28:31], v[166:169], v[186:189], v[102:105]
	v_mfma_f32_16x16x32_bf16 v[60:63], v[122:125], v[214:217], v[106:109]
	v_mfma_f32_16x16x32_bf16 v[102:105], v[166:169], v[214:217], v[110:113]
	v_mfma_f32_16x16x32_bf16 v[16:19], v[122:125], v[222:225], v[16:19]
	v_mfma_f32_16x16x32_bf16 v[20:23], v[166:169], v[222:225], v[20:23]
	v_mfma_f32_16x16x32_bf16 v[8:11], v[126:129], v[182:185], v[8:11]
	v_mfma_f32_16x16x32_bf16 v[12:15], v[170:173], v[182:185], v[12:15]
	v_mfma_f32_16x16x32_bf16 v[24:27], v[126:129], v[190:193], v[24:27]
	v_mfma_f32_16x16x32_bf16 v[28:31], v[170:173], v[190:193], v[28:31]
	v_mfma_f32_16x16x32_bf16 v[60:63], v[126:129], v[218:221], v[60:63]
	v_mfma_f32_16x16x32_bf16 v[102:105], v[170:173], v[218:221], v[102:105]
	v_mfma_f32_16x16x32_bf16 v[16:19], v[126:129], v[226:229], v[16:19]
	v_mfma_f32_16x16x32_bf16 v[20:23], v[170:173], v[226:229], v[20:23]
	s_setprio 0
	s_barrier
	ds_read_b128 v[106:109], v96
	ds_read_b128 v[110:113], v96 offset:1024
	ds_read_b128 v[114:117], v96 offset:2048
	ds_read_b128 v[118:121], v96 offset:3072
	ds_read_b128 v[122:125], v198
	ds_read_b128 v[126:129], v198 offset:1024
	ds_read_b128 v[166:169], v198 offset:2048
	ds_read_b128 v[170:173], v198 offset:3072
	s_add_u32 s48, s48, 0x10180
	s_addc_u32 s49, s49, 0
	s_mov_b32 m0, s56
	v_lshl_add_u64 v[146:147], s[48:49], 0, v[138:139]
	ds_read_b128 v[174:177], v149
	ds_read_b128 v[182:185], v149 offset:1024
	ds_read_b128 v[186:189], v149 offset:2048
	ds_read_b128 v[190:193], v149 offset:3072
	ds_read_b128 v[214:217], v149 offset:4096
	ds_read_b128 v[218:221], v149 offset:5120
	ds_read_b128 v[222:225], v149 offset:6144
	ds_read_b128 v[226:229], v149 offset:7168
	global_load_lds_dwordx4 v[146:147], off
	v_lshl_add_u64 v[146:147], s[48:49], 0, v[142:143]
	s_mov_b32 m0, s2
	s_nop 0
	global_load_lds_dwordx4 v[146:147], off
	s_waitcnt vmcnt(8)
	s_waitcnt lgkmcnt(0)
	v_mfma_f32_16x16x32_bf16 v[64:67], v[106:109], v[174:177], v[64:67]
	v_mfma_f32_16x16x32_bf16 v[68:71], v[114:117], v[174:177], v[68:71]
	s_barrier
	s_setprio 1
	s_waitcnt lgkmcnt(0)
	v_mfma_f32_16x16x32_bf16 v[72:75], v[106:109], v[186:189], v[72:75]
	v_mfma_f32_16x16x32_bf16 v[76:79], v[114:117], v[186:189], v[76:79]
	v_mfma_f32_16x16x32_bf16 v[80:83], v[106:109], v[214:217], v[80:83]
	v_mfma_f32_16x16x32_bf16 v[84:87], v[114:117], v[214:217], v[84:87]
	v_mfma_f32_16x16x32_bf16 v[88:91], v[106:109], v[222:225], v[88:91]
	v_mfma_f32_16x16x32_bf16 v[92:95], v[114:117], v[222:225], v[92:95]
	v_mfma_f32_16x16x32_bf16 v[64:67], v[110:113], v[182:185], v[64:67]
	v_mfma_f32_16x16x32_bf16 v[68:71], v[118:121], v[182:185], v[68:71]
	v_mfma_f32_16x16x32_bf16 v[72:75], v[110:113], v[190:193], v[72:75]
	v_mfma_f32_16x16x32_bf16 v[76:79], v[118:121], v[190:193], v[76:79]
	v_mfma_f32_16x16x32_bf16 v[80:83], v[110:113], v[218:221], v[80:83]
	v_mfma_f32_16x16x32_bf16 v[84:87], v[118:121], v[218:221], v[84:87]
	v_mfma_f32_16x16x32_bf16 v[88:91], v[110:113], v[226:229], v[88:91]
	v_mfma_f32_16x16x32_bf16 v[92:95], v[118:121], v[226:229], v[92:95]
	s_setprio 0
	s_setprio 1
	v_mfma_f32_16x16x32_bf16 v[32:35], v[166:169], v[174:177], v[32:35]
	v_mfma_f32_16x16x32_bf16 v[36:39], v[122:125], v[186:189], v[36:39]
	v_mfma_f32_16x16x32_bf16 v[40:43], v[166:169], v[186:189], v[40:43]
	v_mfma_f32_16x16x32_bf16 v[44:47], v[122:125], v[214:217], v[44:47]
	v_mfma_f32_16x16x32_bf16 v[48:51], v[166:169], v[214:217], v[48:51]
	v_mfma_f32_16x16x32_bf16 v[52:55], v[122:125], v[222:225], v[52:55]
	v_mfma_f32_16x16x32_bf16 v[56:59], v[166:169], v[222:225], v[56:59]
	v_mfma_f32_16x16x32_bf16 v[98:101], v[122:125], v[174:177], v[98:101]
	v_mfma_f32_16x16x32_bf16 v[32:35], v[170:173], v[182:185], v[32:35]
	v_mfma_f32_16x16x32_bf16 v[36:39], v[126:129], v[190:193], v[36:39]
	v_mfma_f32_16x16x32_bf16 v[40:43], v[170:173], v[190:193], v[40:43]
	v_mfma_f32_16x16x32_bf16 v[44:47], v[126:129], v[218:221], v[44:47]
	v_mfma_f32_16x16x32_bf16 v[48:51], v[170:173], v[218:221], v[48:51]
	v_mfma_f32_16x16x32_bf16 v[52:55], v[126:129], v[226:229], v[52:55]
	v_mfma_f32_16x16x32_bf16 v[56:59], v[170:173], v[226:229], v[56:59]
	v_mfma_f32_16x16x32_bf16 v[230:233], v[126:129], v[182:185], v[98:101]
	s_setprio 0
	s_barrier
	s_mov_b32 m0, s25
	v_lshl_add_u64 v[146:147], s[50:51], 0, v[140:141]
	s_add_u32 s2, s50, 0x10000
	ds_read_b128 v[98:101], v149 offset:16384
	ds_read_b128 v[174:177], v149 offset:17408
	ds_read_b128 v[182:185], v149 offset:18432
	ds_read_b128 v[186:189], v149 offset:19456
	ds_read_b128 v[190:193], v149 offset:20480
	ds_read_b128 v[214:217], v149 offset:21504
	ds_read_b128 v[218:221], v149 offset:22528
	ds_read_b128 v[222:225], v149 offset:23552
	global_load_lds_dwordx4 v[146:147], off
	v_lshl_add_u64 v[194:195], s[50:51], 0, v[144:145]
	s_mov_b32 m0, s3
	s_addc_u32 s3, s51, 0
	global_load_lds_dwordx4 v[194:195], off
	v_lshl_add_u64 v[178:179], s[2:3], 0, v[140:141]
	s_mov_b32 m0, s6
	v_lshl_add_u64 v[198:199], s[58:59], 0, v[138:139]
	global_load_lds_dwordx4 v[178:179], off
	v_lshl_add_u64 v[178:179], s[2:3], 0, v[144:145]
	s_mov_b32 m0, s7
	v_lshl_add_u64 v[200:201], s[58:59], 0, v[142:143]
	global_load_lds_dwordx4 v[178:179], off
	s_mov_b32 m0, s18
	s_nop 0
	global_load_lds_dwordx4 v[198:199], off
	s_mov_b32 m0, s19
	s_nop 0
	global_load_lds_dwordx4 v[200:201], off
	s_waitcnt vmcnt(8)
	s_waitcnt lgkmcnt(0)
	v_mfma_f32_16x16x32_bf16 v[130:133], v[106:109], v[98:101], v[130:133]
	v_mfma_f32_16x16x32_bf16 v[226:229], v[110:113], v[174:177], v[130:133]
	s_barrier
	s_setprio 1
	s_waitcnt lgkmcnt(0)
	v_mfma_f32_16x16x32_bf16 v[130:133], v[114:117], v[98:101], v[134:137]
	v_mfma_f32_16x16x32_bf16 v[234:237], v[118:121], v[174:177], v[130:133]
	v_mfma_f32_16x16x32_bf16 v[130:133], v[106:109], v[182:185], v[150:153]
	v_mfma_f32_16x16x32_bf16 v[150:153], v[110:113], v[186:189], v[130:133]
	v_mfma_f32_16x16x32_bf16 v[130:133], v[114:117], v[182:185], v[154:157]
	v_mfma_f32_16x16x32_bf16 v[154:157], v[118:121], v[186:189], v[130:133]
	v_mfma_f32_16x16x32_bf16 v[130:133], v[106:109], v[190:193], v[158:161]
	v_mfma_f32_16x16x32_bf16 v[0:3], v[106:109], v[218:221], v[0:3]
	v_mfma_f32_16x16x32_bf16 v[4:7], v[114:117], v[218:221], v[4:7]
	v_mfma_f32_16x16x32_bf16 v[158:161], v[110:113], v[214:217], v[130:133]
	v_mfma_f32_16x16x32_bf16 v[130:133], v[114:117], v[190:193], v[162:165]
	v_mfma_f32_16x16x32_bf16 v[0:3], v[110:113], v[222:225], v[0:3]
	v_mfma_f32_16x16x32_bf16 v[4:7], v[118:121], v[222:225], v[4:7]
	v_mfma_f32_16x16x32_bf16 v[162:165], v[118:121], v[214:217], v[130:133]
	s_setprio 0
	s_setprio 1
	v_mfma_f32_16x16x32_bf16 v[8:11], v[122:125], v[98:101], v[8:11]
	v_mfma_f32_16x16x32_bf16 v[12:15], v[166:169], v[98:101], v[12:15]
	v_mfma_f32_16x16x32_bf16 v[24:27], v[122:125], v[182:185], v[24:27]
	v_mfma_f32_16x16x32_bf16 v[28:31], v[166:169], v[182:185], v[28:31]
	v_mfma_f32_16x16x32_bf16 v[60:63], v[122:125], v[190:193], v[60:63]
	v_mfma_f32_16x16x32_bf16 v[16:19], v[122:125], v[218:221], v[16:19]
	v_mfma_f32_16x16x32_bf16 v[8:11], v[126:129], v[174:177], v[8:11]
	v_mfma_f32_16x16x32_bf16 v[12:15], v[170:173], v[174:177], v[12:15]
	v_mfma_f32_16x16x32_bf16 v[24:27], v[126:129], v[186:189], v[24:27]
	v_mfma_f32_16x16x32_bf16 v[28:31], v[170:173], v[186:189], v[28:31]
	v_mfma_f32_16x16x32_bf16 v[106:109], v[126:129], v[214:217], v[60:63]
	v_mfma_f32_16x16x32_bf16 v[60:63], v[166:169], v[190:193], v[102:105]
	v_mfma_f32_16x16x32_bf16 v[174:177], v[126:129], v[222:225], v[16:19]
	v_mfma_f32_16x16x32_bf16 v[16:19], v[166:169], v[218:221], v[20:23]
	v_mfma_f32_16x16x32_bf16 v[110:113], v[170:173], v[214:217], v[60:63]
	v_mfma_f32_16x16x32_bf16 v[166:169], v[170:173], v[222:225], v[16:19]
	s_setprio 0
	s_barrier
	s_nop 3
	ds_read_b128 v[16:19], v204
	ds_read_b128 v[20:23], v204 offset:1024
	ds_read_b128 v[170:173], v204 offset:2048
	ds_read_b128 v[182:185], v204 offset:3072
	ds_read_b128 v[186:189], v205
	ds_read_b128 v[190:193], v205 offset:1024
	ds_read_b128 v[214:217], v205 offset:2048
	ds_read_b128 v[218:221], v205 offset:3072
	s_add_u32 s2, s58, 0x10000
	s_addc_u32 s3, s59, 0
	s_mov_b32 m0, s20
	v_lshl_add_u64 v[98:99], s[2:3], 0, v[138:139]
	ds_read_b128 v[60:63], v149 offset:32768
	ds_read_b128 v[222:225], v149 offset:33792
	ds_read_b128 v[238:241], v149 offset:34816
	ds_read_b128 v[242:245], v149 offset:35840
	ds_read_b128 v[246:249], v149 offset:36864
	ds_read_b128 v[202:205], v149 offset:37888
	ds_read_b128 v[178:181], v149 offset:38912
	ds_read_b128 v[206:209], v149 offset:39936
	global_load_lds_dwordx4 v[98:99], off
	v_lshl_add_u64 v[98:99], s[2:3], 0, v[142:143]
	s_mov_b32 m0, s36
	s_nop 0
	global_load_lds_dwordx4 v[98:99], off
	s_waitcnt vmcnt(8)
	s_waitcnt lgkmcnt(0)
	v_mfma_f32_16x16x32_bf16 v[64:67], v[16:19], v[60:63], v[64:67]
	v_mfma_f32_16x16x32_bf16 v[134:137], v[20:23], v[222:225], v[64:67]
	s_barrier
	s_setprio 1
	s_waitcnt lgkmcnt(0)
	v_mfma_f32_16x16x32_bf16 v[64:67], v[170:173], v[60:63], v[68:71]
	v_mfma_f32_16x16x32_bf16 v[130:133], v[182:185], v[222:225], v[64:67]
	v_mfma_f32_16x16x32_bf16 v[64:67], v[16:19], v[238:241], v[72:75]
	v_mfma_f32_16x16x32_bf16 v[126:129], v[20:23], v[242:245], v[64:67]
	v_mfma_f32_16x16x32_bf16 v[64:67], v[170:173], v[238:241], v[76:79]
	v_mfma_f32_16x16x32_bf16 v[122:125], v[182:185], v[242:245], v[64:67]
	v_mfma_f32_16x16x32_bf16 v[64:67], v[16:19], v[246:249], v[80:83]
	v_mfma_f32_16x16x32_bf16 v[118:121], v[20:23], v[202:205], v[64:67]
	v_mfma_f32_16x16x32_bf16 v[64:67], v[170:173], v[246:249], v[84:87]
	v_mfma_f32_16x16x32_bf16 v[114:117], v[182:185], v[202:205], v[64:67]
	v_mfma_f32_16x16x32_bf16 v[64:67], v[16:19], v[178:181], v[88:91]
	v_mfma_f32_16x16x32_bf16 v[102:105], v[20:23], v[206:209], v[64:67]
	v_mfma_f32_16x16x32_bf16 v[64:67], v[170:173], v[178:181], v[92:95]
	v_mfma_f32_16x16x32_bf16 v[98:101], v[182:185], v[206:209], v[64:67]
	s_setprio 0
	s_setprio 1
	v_mfma_f32_16x16x32_bf16 v[64:67], v[186:189], v[60:63], v[230:233]
	v_mfma_f32_16x16x32_bf16 v[32:35], v[214:217], v[60:63], v[32:35]
	v_mfma_f32_16x16x32_bf16 v[68:71], v[190:193], v[222:225], v[64:67]
	v_mfma_f32_16x16x32_bf16 v[64:67], v[218:221], v[222:225], v[32:35]
	v_mfma_f32_16x16x32_bf16 v[32:35], v[186:189], v[238:241], v[36:39]
	v_mfma_f32_16x16x32_bf16 v[80:83], v[190:193], v[242:245], v[32:35]
	v_mfma_f32_16x16x32_bf16 v[32:35], v[214:217], v[238:241], v[40:43]
	v_mfma_f32_16x16x32_bf16 v[72:75], v[218:221], v[242:245], v[32:35]
	v_mfma_f32_16x16x32_bf16 v[32:35], v[186:189], v[246:249], v[44:47]
	v_mfma_f32_16x16x32_bf16 v[84:87], v[190:193], v[202:205], v[32:35]
	v_mfma_f32_16x16x32_bf16 v[32:35], v[214:217], v[246:249], v[48:51]
	v_mfma_f32_16x16x32_bf16 v[76:79], v[218:221], v[202:205], v[32:35]
	v_mfma_f32_16x16x32_bf16 v[32:35], v[186:189], v[178:181], v[52:55]
	v_mfma_f32_16x16x32_bf16 v[92:95], v[190:193], v[206:209], v[32:35]
	v_mfma_f32_16x16x32_bf16 v[32:35], v[214:217], v[178:181], v[56:59]
	v_mfma_f32_16x16x32_bf16 v[88:91], v[218:221], v[206:209], v[32:35]
	s_setprio 0
	s_barrier
	s_mov_b32 m0, s57
	s_nop 3
	v_lshl_add_u64 v[32:33], v[146:147], 0, s[30:31]
	s_add_u32 s2, s50, 0x10080
	ds_read_b128 v[178:181], v149 offset:49152
	ds_read_b128 v[202:205], v149 offset:50176
	ds_read_b128 v[206:209], v149 offset:51200
	ds_read_b128 v[222:225], v149 offset:52224
	ds_read_b128 v[230:233], v149 offset:53248
	ds_read_b128 v[238:241], v149 offset:54272
	ds_read_b128 v[242:245], v149 offset:55296
	ds_read_b128 v[246:249], v149 offset:56320
	global_load_lds_dwordx4 v[32:33], off
	v_lshl_add_u64 v[32:33], v[194:195], 0, s[30:31]
	s_mov_b32 m0, s35
	s_addc_u32 s3, s51, 0
	global_load_lds_dwordx4 v[32:33], off
	v_lshl_add_u64 v[32:33], s[2:3], 0, v[140:141]
	s_mov_b32 m0, s52
	s_nop 0
	global_load_lds_dwordx4 v[32:33], off
	v_lshl_add_u64 v[32:33], s[2:3], 0, v[144:145]
	s_mov_b32 m0, s53
	s_nop 0
	global_load_lds_dwordx4 v[32:33], off
	v_lshl_add_u64 v[32:33], v[198:199], 0, s[30:31]
	s_mov_b32 m0, s45
	s_nop 0
	global_load_lds_dwordx4 v[32:33], off
	v_lshl_add_u64 v[32:33], v[200:201], 0, s[30:31]
	s_mov_b32 m0, s47
	s_nop 0
	global_load_lds_dwordx4 v[32:33], off
	s_waitcnt vmcnt(8)
	s_waitcnt lgkmcnt(0)
	v_mfma_f32_16x16x32_bf16 v[32:35], v[16:19], v[178:181], v[226:229]
	v_mfma_f32_16x16x32_bf16 v[60:63], v[20:23], v[202:205], v[32:35]
	s_barrier
	s_setprio 1
	s_waitcnt lgkmcnt(0)
	v_mfma_f32_16x16x32_bf16 v[32:35], v[170:173], v[178:181], v[234:237]
	v_mfma_f32_16x16x32_bf16 v[56:59], v[182:185], v[202:205], v[32:35]
	v_mfma_f32_16x16x32_bf16 v[32:35], v[16:19], v[206:209], v[150:153]
	v_mfma_f32_16x16x32_bf16 v[52:55], v[20:23], v[222:225], v[32:35]
	v_mfma_f32_16x16x32_bf16 v[32:35], v[170:173], v[206:209], v[154:157]
	v_mfma_f32_16x16x32_bf16 v[48:51], v[182:185], v[222:225], v[32:35]
	v_mfma_f32_16x16x32_bf16 v[32:35], v[16:19], v[230:233], v[158:161]
	v_mfma_f32_16x16x32_bf16 v[0:3], v[16:19], v[242:245], v[0:3]
	v_mfma_f32_16x16x32_bf16 v[44:47], v[20:23], v[238:241], v[32:35]
	v_mfma_f32_16x16x32_bf16 v[32:35], v[170:173], v[230:233], v[162:165]
	v_mfma_f32_16x16x32_bf16 v[36:39], v[20:23], v[246:249], v[0:3]
	v_mfma_f32_16x16x32_bf16 v[0:3], v[170:173], v[242:245], v[4:7]
	v_mfma_f32_16x16x32_bf16 v[40:43], v[182:185], v[238:241], v[32:35]
	v_mfma_f32_16x16x32_bf16 v[32:35], v[182:185], v[246:249], v[0:3]
	s_setprio 0
	s_setprio 1
	v_mfma_f32_16x16x32_bf16 v[0:3], v[186:189], v[178:181], v[8:11]
	v_mfma_f32_16x16x32_bf16 v[4:7], v[190:193], v[202:205], v[0:3]
	v_mfma_f32_16x16x32_bf16 v[0:3], v[214:217], v[178:181], v[12:15]
	v_mfma_f32_16x16x32_bf16 v[8:11], v[186:189], v[206:209], v[24:27]
	v_mfma_f32_16x16x32_bf16 v[12:15], v[186:189], v[230:233], v[106:109]
	v_mfma_f32_16x16x32_bf16 v[24:27], v[186:189], v[242:245], v[174:177]
	v_mfma_f32_16x16x32_bf16 v[16:19], v[190:193], v[222:225], v[8:11]
	v_mfma_f32_16x16x32_bf16 v[8:11], v[214:217], v[206:209], v[28:31]
	v_mfma_f32_16x16x32_bf16 v[20:23], v[190:193], v[238:241], v[12:15]
	v_mfma_f32_16x16x32_bf16 v[12:15], v[214:217], v[230:233], v[110:113]
	v_mfma_f32_16x16x32_bf16 v[28:31], v[190:193], v[246:249], v[24:27]
	v_mfma_f32_16x16x32_bf16 v[24:27], v[214:217], v[242:245], v[166:169]
	v_mfma_f32_16x16x32_bf16 v[0:3], v[218:221], v[202:205], v[0:3]
	v_mfma_f32_16x16x32_bf16 v[8:11], v[218:221], v[222:225], v[8:11]
	v_mfma_f32_16x16x32_bf16 v[12:15], v[218:221], v[238:241], v[12:15]
	v_mfma_f32_16x16x32_bf16 v[24:27], v[218:221], v[246:249], v[24:27]
	s_setprio 0
	s_barrier
	s_andn2_b64 vcc, exec, s[14:15]
	s_cbranch_vccnz .LBB0_682
	s_barrier

.LBB0_717:
	s_add_u32 s3, s42, 0xfffe0080
	s_addc_u32 s6, s43, -1
	s_add_i32 s7, 0, 0x10000
	s_cmp_eq_u32 s2, 4
	s_cselect_b32 s47, s23, s6
	s_cselect_b32 s46, s51, s3
	v_add_u32_e32 v140, s7, v143
	s_cselect_b32 s45, s15, s54
	s_cselect_b32 s44, s52, s53
	s_add_i32 s3, 0, 0x14000
	ds_read_b128 v[146:149], v140
	ds_read_b128 v[150:153], v140 offset:1024
	ds_read_b128 v[154:157], v140 offset:2048
	ds_read_b128 v[158:161], v140 offset:3072
	v_add_u32_e32 v140, s3, v143
	ds_read_b128 v[162:165], v140
	ds_read_b128 v[166:169], v140 offset:1024
	ds_read_b128 v[170:173], v140 offset:2048
	ds_read_b128 v[174:177], v140 offset:3072
	v_lshl_add_u64 v[140:141], s[42:43], 0, v[136:137]
	s_add_i32 m0, s20, 0xc000
	ds_read_b128 v[178:181], v145
	ds_read_b128 v[182:185], v145 offset:1024
	ds_read_b128 v[186:189], v145 offset:2048
	ds_read_b128 v[190:193], v145 offset:3072
	ds_read_b128 v[202:205], v145 offset:4096
	ds_read_b128 v[206:209], v145 offset:5120
	ds_read_b128 v[214:217], v145 offset:6144
	ds_read_b128 v[218:221], v145 offset:7168
	global_load_lds_dwordx4 v[140:141], off
	v_lshl_add_u64 v[140:141], s[42:43], 0, v[138:139]
	s_add_i32 m0, s20, 0xe000
	s_nop 0
	global_load_lds_dwordx4 v[140:141], off
	s_waitcnt vmcnt(8)
	s_waitcnt lgkmcnt(0)
	v_mfma_f32_16x16x32_bf16 v[126:129], v[146:149], v[178:181], v[126:129]
	v_mfma_f32_16x16x32_bf16 v[122:125], v[154:157], v[178:181], v[122:125]
	s_barrier
	s_setprio 1
	s_waitcnt lgkmcnt(0)
	v_mfma_f32_16x16x32_bf16 v[118:121], v[146:149], v[186:189], v[118:121]
	v_mfma_f32_16x16x32_bf16 v[110:113], v[154:157], v[186:189], v[110:113]
	v_mfma_f32_16x16x32_bf16 v[102:105], v[146:149], v[202:205], v[102:105]
	v_mfma_f32_16x16x32_bf16 v[92:95], v[154:157], v[202:205], v[92:95]
	v_mfma_f32_16x16x32_bf16 v[84:87], v[146:149], v[214:217], v[84:87]
	v_mfma_f32_16x16x32_bf16 v[76:79], v[154:157], v[214:217], v[76:79]
	v_mfma_f32_16x16x32_bf16 v[126:129], v[150:153], v[182:185], v[126:129]
	v_mfma_f32_16x16x32_bf16 v[122:125], v[158:161], v[182:185], v[122:125]
	v_mfma_f32_16x16x32_bf16 v[118:121], v[150:153], v[190:193], v[118:121]
	v_mfma_f32_16x16x32_bf16 v[110:113], v[158:161], v[190:193], v[110:113]
	v_mfma_f32_16x16x32_bf16 v[102:105], v[150:153], v[206:209], v[102:105]
	v_mfma_f32_16x16x32_bf16 v[92:95], v[158:161], v[206:209], v[92:95]
	v_mfma_f32_16x16x32_bf16 v[84:87], v[150:153], v[218:221], v[84:87]
	v_mfma_f32_16x16x32_bf16 v[76:79], v[158:161], v[218:221], v[76:79]
	s_setprio 0
	s_setprio 1
	v_mfma_f32_16x16x32_bf16 v[114:117], v[162:165], v[178:181], v[114:117]
	v_mfma_f32_16x16x32_bf16 v[106:109], v[170:173], v[178:181], v[106:109]
	v_mfma_f32_16x16x32_bf16 v[98:101], v[162:165], v[186:189], v[98:101]
	v_mfma_f32_16x16x32_bf16 v[88:91], v[170:173], v[186:189], v[88:91]
	v_mfma_f32_16x16x32_bf16 v[80:83], v[162:165], v[202:205], v[80:83]
	v_mfma_f32_16x16x32_bf16 v[72:75], v[170:173], v[202:205], v[72:75]
	v_mfma_f32_16x16x32_bf16 v[68:71], v[162:165], v[214:217], v[68:71]
	v_mfma_f32_16x16x32_bf16 v[64:67], v[170:173], v[214:217], v[64:67]
	v_mfma_f32_16x16x32_bf16 v[114:117], v[166:169], v[182:185], v[114:117]
	v_mfma_f32_16x16x32_bf16 v[106:109], v[174:177], v[182:185], v[106:109]
	v_mfma_f32_16x16x32_bf16 v[98:101], v[166:169], v[190:193], v[98:101]
	v_mfma_f32_16x16x32_bf16 v[88:91], v[174:177], v[190:193], v[88:91]
	v_mfma_f32_16x16x32_bf16 v[80:83], v[166:169], v[206:209], v[80:83]
	v_mfma_f32_16x16x32_bf16 v[72:75], v[174:177], v[206:209], v[72:75]
	v_mfma_f32_16x16x32_bf16 v[68:71], v[166:169], v[218:221], v[68:71]
	v_mfma_f32_16x16x32_bf16 v[64:67], v[174:177], v[218:221], v[64:67]
	s_setprio 0
	s_barrier
	s_add_i32 s6, s7, s4
	v_lshl_add_u64 v[140:141], s[44:45], 0, v[96:97]
	s_mov_b32 m0, s6
	ds_read_b128 v[178:181], v145 offset:16384
	ds_read_b128 v[182:185], v145 offset:17408
	ds_read_b128 v[186:189], v145 offset:18432
	ds_read_b128 v[190:193], v145 offset:19456
	ds_read_b128 v[202:205], v145 offset:20480
	ds_read_b128 v[206:209], v145 offset:21504
	ds_read_b128 v[214:217], v145 offset:22528
	ds_read_b128 v[218:221], v145 offset:23552
	global_load_lds_dwordx4 v[140:141], off
	s_add_i32 m0, s6, 0x2000
	s_add_u32 s6, s44, 0x20000
	v_lshl_add_u64 v[194:195], s[44:45], 0, v[134:135]
	s_addc_u32 s7, s45, 0
	s_add_i32 s3, s3, s4
	global_load_lds_dwordx4 v[194:195], off
	v_lshl_add_u64 v[198:199], s[6:7], 0, v[96:97]
	s_mov_b32 m0, s3
	v_lshl_add_u64 v[200:201], s[46:47], 0, v[132:133]
	global_load_lds_dwordx4 v[198:199], off
	v_lshl_add_u64 v[198:199], s[6:7], 0, v[134:135]
	s_add_i32 m0, s3, 0x2000
	s_nop 0
	global_load_lds_dwordx4 v[198:199], off
	v_lshl_add_u64 v[198:199], s[46:47], 0, v[130:131]
	s_mov_b32 m0, s20
	s_nop 0
	global_load_lds_dwordx4 v[198:199], off
	s_mov_b32 m0, s25
	s_nop 0
	global_load_lds_dwordx4 v[200:201], off
	s_waitcnt vmcnt(8)
	s_waitcnt lgkmcnt(0)
	v_mfma_f32_16x16x32_bf16 v[60:63], v[146:149], v[178:181], v[60:63]
	v_mfma_f32_16x16x32_bf16 v[56:59], v[154:157], v[178:181], v[56:59]
	s_barrier
	s_setprio 1
	s_waitcnt lgkmcnt(0)
	v_mfma_f32_16x16x32_bf16 v[52:55], v[146:149], v[186:189], v[52:55]
	v_mfma_f32_16x16x32_bf16 v[44:47], v[154:157], v[186:189], v[44:47]
	v_mfma_f32_16x16x32_bf16 v[36:39], v[146:149], v[202:205], v[36:39]
	v_mfma_f32_16x16x32_bf16 v[28:31], v[154:157], v[202:205], v[28:31]
	v_mfma_f32_16x16x32_bf16 v[20:23], v[146:149], v[214:217], v[20:23]
	v_mfma_f32_16x16x32_bf16 v[12:15], v[154:157], v[214:217], v[12:15]
	v_mfma_f32_16x16x32_bf16 v[60:63], v[150:153], v[182:185], v[60:63]
	v_mfma_f32_16x16x32_bf16 v[56:59], v[158:161], v[182:185], v[56:59]
	v_mfma_f32_16x16x32_bf16 v[52:55], v[150:153], v[190:193], v[52:55]
	v_mfma_f32_16x16x32_bf16 v[44:47], v[158:161], v[190:193], v[44:47]
	v_mfma_f32_16x16x32_bf16 v[36:39], v[150:153], v[206:209], v[36:39]
	v_mfma_f32_16x16x32_bf16 v[28:31], v[158:161], v[206:209], v[28:31]
	v_mfma_f32_16x16x32_bf16 v[20:23], v[150:153], v[218:221], v[20:23]
	v_mfma_f32_16x16x32_bf16 v[12:15], v[158:161], v[218:221], v[12:15]
	s_setprio 0
	s_setprio 1
	v_mfma_f32_16x16x32_bf16 v[48:51], v[162:165], v[178:181], v[48:51]
	v_mfma_f32_16x16x32_bf16 v[40:43], v[170:173], v[178:181], v[40:43]
	v_mfma_f32_16x16x32_bf16 v[32:35], v[162:165], v[186:189], v[32:35]
	v_mfma_f32_16x16x32_bf16 v[24:27], v[170:173], v[186:189], v[24:27]
	v_mfma_f32_16x16x32_bf16 v[16:19], v[162:165], v[202:205], v[16:19]
	v_mfma_f32_16x16x32_bf16 v[8:11], v[170:173], v[202:205], v[8:11]
	v_mfma_f32_16x16x32_bf16 v[4:7], v[162:165], v[214:217], v[4:7]
	v_mfma_f32_16x16x32_bf16 v[0:3], v[170:173], v[214:217], v[0:3]
	v_mfma_f32_16x16x32_bf16 v[48:51], v[166:169], v[182:185], v[48:51]
	v_mfma_f32_16x16x32_bf16 v[40:43], v[174:177], v[182:185], v[40:43]
	v_mfma_f32_16x16x32_bf16 v[32:35], v[166:169], v[190:193], v[32:35]
	v_mfma_f32_16x16x32_bf16 v[24:27], v[174:177], v[190:193], v[24:27]
	v_mfma_f32_16x16x32_bf16 v[16:19], v[166:169], v[206:209], v[16:19]
	v_mfma_f32_16x16x32_bf16 v[8:11], v[174:177], v[206:209], v[8:11]
	v_mfma_f32_16x16x32_bf16 v[4:7], v[166:169], v[218:221], v[4:7]
	v_mfma_f32_16x16x32_bf16 v[0:3], v[174:177], v[218:221], v[0:3]
	s_setprio 0
	s_barrier
	s_add_i32 s3, 0, 0x18000
	s_add_i32 s55, 0, 0x1c000
	v_add_u32_e32 v158, s3, v143
	v_add_u32_e32 v174, s55, v143
	ds_read_b128 v[146:149], v158
	ds_read_b128 v[150:153], v158 offset:1024
	ds_read_b128 v[154:157], v158 offset:2048
	ds_read_b128 v[158:161], v158 offset:3072
	ds_read_b128 v[162:165], v174
	ds_read_b128 v[166:169], v174 offset:1024
	ds_read_b128 v[170:173], v174 offset:2048
	ds_read_b128 v[174:177], v174 offset:3072
	s_add_u32 s6, s46, 0x20000
	s_addc_u32 s7, s47, 0
	s_mov_b32 m0, s36
	v_lshl_add_u64 v[222:223], s[6:7], 0, v[130:131]
	ds_read_b128 v[178:181], v145 offset:32768
	ds_read_b128 v[182:185], v145 offset:33792
	ds_read_b128 v[186:189], v145 offset:34816
	ds_read_b128 v[190:193], v145 offset:35840
	ds_read_b128 v[202:205], v145 offset:36864
	ds_read_b128 v[206:209], v145 offset:37888
	ds_read_b128 v[214:217], v145 offset:38912
	ds_read_b128 v[218:221], v145 offset:39936
	global_load_lds_dwordx4 v[222:223], off
	v_lshl_add_u64 v[222:223], s[6:7], 0, v[132:133]
	s_mov_b32 m0, s37
	s_nop 0
	global_load_lds_dwordx4 v[222:223], off
	s_waitcnt vmcnt(8)
	s_waitcnt lgkmcnt(0)
	v_mfma_f32_16x16x32_bf16 v[126:129], v[146:149], v[178:181], v[126:129]
	v_mfma_f32_16x16x32_bf16 v[122:125], v[154:157], v[178:181], v[122:125]
	s_barrier
	s_setprio 1
	s_waitcnt lgkmcnt(0)
	v_mfma_f32_16x16x32_bf16 v[118:121], v[146:149], v[186:189], v[118:121]
	v_mfma_f32_16x16x32_bf16 v[110:113], v[154:157], v[186:189], v[110:113]
	v_mfma_f32_16x16x32_bf16 v[102:105], v[146:149], v[202:205], v[102:105]
	v_mfma_f32_16x16x32_bf16 v[92:95], v[154:157], v[202:205], v[92:95]
	v_mfma_f32_16x16x32_bf16 v[84:87], v[146:149], v[214:217], v[84:87]
	v_mfma_f32_16x16x32_bf16 v[76:79], v[154:157], v[214:217], v[76:79]
	v_mfma_f32_16x16x32_bf16 v[126:129], v[150:153], v[182:185], v[126:129]
	v_mfma_f32_16x16x32_bf16 v[122:125], v[158:161], v[182:185], v[122:125]
	v_mfma_f32_16x16x32_bf16 v[118:121], v[150:153], v[190:193], v[118:121]
	v_mfma_f32_16x16x32_bf16 v[110:113], v[158:161], v[190:193], v[110:113]
	v_mfma_f32_16x16x32_bf16 v[102:105], v[150:153], v[206:209], v[102:105]
	v_mfma_f32_16x16x32_bf16 v[92:95], v[158:161], v[206:209], v[92:95]
	v_mfma_f32_16x16x32_bf16 v[84:87], v[150:153], v[218:221], v[84:87]
	v_mfma_f32_16x16x32_bf16 v[76:79], v[158:161], v[218:221], v[76:79]
	s_setprio 0
	s_setprio 1
	v_mfma_f32_16x16x32_bf16 v[114:117], v[162:165], v[178:181], v[114:117]
	v_mfma_f32_16x16x32_bf16 v[106:109], v[170:173], v[178:181], v[106:109]
	v_mfma_f32_16x16x32_bf16 v[98:101], v[162:165], v[186:189], v[98:101]
	v_mfma_f32_16x16x32_bf16 v[88:91], v[170:173], v[186:189], v[88:91]
	v_mfma_f32_16x16x32_bf16 v[80:83], v[162:165], v[202:205], v[80:83]
	v_mfma_f32_16x16x32_bf16 v[72:75], v[170:173], v[202:205], v[72:75]
	v_mfma_f32_16x16x32_bf16 v[68:71], v[162:165], v[214:217], v[68:71]
	v_mfma_f32_16x16x32_bf16 v[64:67], v[170:173], v[214:217], v[64:67]
	v_mfma_f32_16x16x32_bf16 v[114:117], v[166:169], v[182:185], v[114:117]
	v_mfma_f32_16x16x32_bf16 v[106:109], v[174:177], v[182:185], v[106:109]
	v_mfma_f32_16x16x32_bf16 v[98:101], v[166:169], v[190:193], v[98:101]
	v_mfma_f32_16x16x32_bf16 v[88:91], v[174:177], v[190:193], v[88:91]
	v_mfma_f32_16x16x32_bf16 v[80:83], v[166:169], v[206:209], v[80:83]
	v_mfma_f32_16x16x32_bf16 v[72:75], v[174:177], v[206:209], v[72:75]
	v_mfma_f32_16x16x32_bf16 v[68:71], v[166:169], v[218:221], v[68:71]
	v_mfma_f32_16x16x32_bf16 v[64:67], v[174:177], v[218:221], v[64:67]
	s_setprio 0
	s_barrier
	s_add_i32 s3, s3, s4
	v_lshl_add_u64 v[140:141], v[140:141], 0, s[30:31]
	s_mov_b32 m0, s3
	ds_read_b128 v[178:181], v145 offset:49152
	ds_read_b128 v[182:185], v145 offset:50176
	ds_read_b128 v[186:189], v145 offset:51200
	ds_read_b128 v[190:193], v145 offset:52224
	ds_read_b128 v[202:205], v145 offset:53248
	ds_read_b128 v[206:209], v145 offset:54272
	ds_read_b128 v[214:217], v145 offset:55296
	ds_read_b128 v[218:221], v145 offset:56320
	global_load_lds_dwordx4 v[140:141], off
	s_add_i32 m0, s3, 0x2000
	s_add_u32 s6, s44, 0x20080
	v_lshl_add_u64 v[140:141], v[194:195], 0, s[30:31]
	s_addc_u32 s7, s45, 0
	s_add_i32 s3, s55, s4
	global_load_lds_dwordx4 v[140:141], off
	v_lshl_add_u64 v[140:141], s[6:7], 0, v[96:97]
	s_mov_b32 m0, s3
	s_nop 0
	global_load_lds_dwordx4 v[140:141], off
	v_lshl_add_u64 v[140:141], s[6:7], 0, v[134:135]
	s_add_i32 m0, s3, 0x2000
	s_nop 0
	global_load_lds_dwordx4 v[140:141], off
	v_lshl_add_u64 v[140:141], v[198:199], 0, s[30:31]
	s_mov_b32 m0, s40
	s_nop 0
	global_load_lds_dwordx4 v[140:141], off
	v_lshl_add_u64 v[140:141], v[200:201], 0, s[30:31]
	s_mov_b32 m0, s48
	s_nop 0
	global_load_lds_dwordx4 v[140:141], off
	s_waitcnt vmcnt(8)
	s_waitcnt lgkmcnt(0)
	v_mfma_f32_16x16x32_bf16 v[60:63], v[146:149], v[178:181], v[60:63]
	v_mfma_f32_16x16x32_bf16 v[56:59], v[154:157], v[178:181], v[56:59]
	s_barrier
	s_setprio 1
	s_waitcnt lgkmcnt(0)
	v_mfma_f32_16x16x32_bf16 v[52:55], v[146:149], v[186:189], v[52:55]
	v_mfma_f32_16x16x32_bf16 v[44:47], v[154:157], v[186:189], v[44:47]
	v_mfma_f32_16x16x32_bf16 v[36:39], v[146:149], v[202:205], v[36:39]
	v_mfma_f32_16x16x32_bf16 v[28:31], v[154:157], v[202:205], v[28:31]
	v_mfma_f32_16x16x32_bf16 v[20:23], v[146:149], v[214:217], v[20:23]
	v_mfma_f32_16x16x32_bf16 v[12:15], v[154:157], v[214:217], v[12:15]
	v_mfma_f32_16x16x32_bf16 v[60:63], v[150:153], v[182:185], v[60:63]
	v_mfma_f32_16x16x32_bf16 v[56:59], v[158:161], v[182:185], v[56:59]
	v_mfma_f32_16x16x32_bf16 v[52:55], v[150:153], v[190:193], v[52:55]
	v_mfma_f32_16x16x32_bf16 v[44:47], v[158:161], v[190:193], v[44:47]
	v_mfma_f32_16x16x32_bf16 v[36:39], v[150:153], v[206:209], v[36:39]
	v_mfma_f32_16x16x32_bf16 v[28:31], v[158:161], v[206:209], v[28:31]
	v_mfma_f32_16x16x32_bf16 v[20:23], v[150:153], v[218:221], v[20:23]
	v_mfma_f32_16x16x32_bf16 v[12:15], v[158:161], v[218:221], v[12:15]
	s_setprio 0
	s_setprio 1
	v_mfma_f32_16x16x32_bf16 v[48:51], v[162:165], v[178:181], v[48:51]
	v_mfma_f32_16x16x32_bf16 v[40:43], v[170:173], v[178:181], v[40:43]
	v_mfma_f32_16x16x32_bf16 v[32:35], v[162:165], v[186:189], v[32:35]
	v_mfma_f32_16x16x32_bf16 v[24:27], v[170:173], v[186:189], v[24:27]
	v_mfma_f32_16x16x32_bf16 v[16:19], v[162:165], v[202:205], v[16:19]
	v_mfma_f32_16x16x32_bf16 v[8:11], v[170:173], v[202:205], v[8:11]
	v_mfma_f32_16x16x32_bf16 v[4:7], v[162:165], v[214:217], v[4:7]
	v_mfma_f32_16x16x32_bf16 v[0:3], v[170:173], v[214:217], v[0:3]
	v_mfma_f32_16x16x32_bf16 v[48:51], v[166:169], v[182:185], v[48:51]
	v_mfma_f32_16x16x32_bf16 v[40:43], v[174:177], v[182:185], v[40:43]
	v_mfma_f32_16x16x32_bf16 v[32:35], v[166:169], v[190:193], v[32:35]
	v_mfma_f32_16x16x32_bf16 v[24:27], v[174:177], v[190:193], v[24:27]
	v_mfma_f32_16x16x32_bf16 v[16:19], v[166:169], v[206:209], v[16:19]
	v_mfma_f32_16x16x32_bf16 v[8:11], v[174:177], v[206:209], v[8:11]
	v_mfma_f32_16x16x32_bf16 v[4:7], v[166:169], v[218:221], v[4:7]
	v_mfma_f32_16x16x32_bf16 v[0:3], v[174:177], v[218:221], v[0:3]
	s_setprio 0
	s_barrier
	s_add_i32 s2, s2, 2
	s_add_u32 s42, s42, 0x100
	s_addc_u32 s43, s43, 0
	s_add_u32 s53, s53, 0x100
	s_addc_u32 s54, s54, 0
	s_cmp_gt_u32 s2, 5
	s_cbranch_scc0 .LBB0_717
	v_readlane_b32 s54, v254, 56
	s_and_b64 vcc, exec, s[10:11]
	v_readlane_b32 s55, v254, 57
	s_cbranch_vccz .LBB0_720
	s_barrier

.LBB0_973:
	s_add_u32 s6, s34, s2
	s_addc_u32 s13, s35, 0
	s_add_u32 s3, s6, 0x100
	s_addc_u32 s23, s13, 0
	s_and_b64 s[36:37], s[60:61], exec
	s_cselect_b32 s73, s43, s23
	s_cselect_b32 s72, s42, s3
	s_add_u32 s2, s24, s2
	s_addc_u32 s3, s25, 0
	s_add_u32 s23, s2, 0x100
	s_addc_u32 s36, s3, 0
	s_add_i32 s47, 0, 0x10000
	s_and_b64 s[2:3], s[60:61], exec
	s_cselect_b32 s75, s53, s36
	s_cselect_b32 s74, s52, s23
	s_add_i32 s49, 0, 0x14000
	s_add_u32 s86, s6, 0x80080
	s_addc_u32 s87, s13, 0
	s_add_i32 s40, s47, s4
	s_add_i32 m0, s5, 0xc000
	s_add_i32 s51, s5, 0xe000
	s_add_i32 s23, s40, 0x2000
	s_add_u32 s82, s74, 0x80000
	v_add_u32_e32 v148, s47, v132
	v_add_u32_e32 v164, s49, v132
	s_addc_u32 s83, s75, 0
	s_add_i32 s37, s49, s4
	ds_read_b128 v[136:139], v148
	ds_read_b128 v[140:143], v148 offset:1024
	ds_read_b128 v[144:147], v148 offset:2048
	ds_read_b128 v[148:151], v148 offset:3072
	ds_read_b128 v[152:155], v164
	ds_read_b128 v[156:159], v164 offset:1024
	ds_read_b128 v[160:163], v164 offset:2048
	ds_read_b128 v[164:167], v164 offset:3072
	s_add_i32 s36, s37, 0x2000
	s_add_i32 s13, 0, 0x18000
	s_add_i32 s6, 0, 0x1c000
	s_add_u32 s62, s72, 0x80000
	s_addc_u32 s63, s73, 0
	s_add_i32 s3, s13, s4
	s_add_i32 s2, s3, 0x2000
	s_add_u32 s60, s74, 0x80080
	s_addc_u32 s61, s75, 0
	s_add_i32 s49, s6, s4
	s_add_i32 s47, s49, 0x2000
	v_lshl_add_u64 v[198:199], s[86:87], 0, v[96:97]
	ds_read_b128 v[168:171], v135
	ds_read_b128 v[172:175], v135 offset:1024
	ds_read_b128 v[176:179], v135 offset:2048
	ds_read_b128 v[180:183], v135 offset:3072
	ds_read_b128 v[184:187], v135 offset:4096
	ds_read_b128 v[188:191], v135 offset:5120
	ds_read_b128 v[192:195], v135 offset:6144
	ds_read_b128 v[202:205], v135 offset:7168
	global_load_lds_dwordx4 v[198:199], off
	v_lshl_add_u64 v[198:199], s[86:87], 0, v[130:131]
	s_mov_b32 m0, s51
	s_nop 0
	global_load_lds_dwordx4 v[198:199], off
	s_waitcnt vmcnt(8)
	s_waitcnt lgkmcnt(0)
	v_mfma_f32_16x16x32_bf16 v[126:129], v[136:139], v[168:171], v[126:129]
	v_mfma_f32_16x16x32_bf16 v[122:125], v[144:147], v[168:171], v[122:125]
	s_barrier
	s_setprio 1
	s_waitcnt lgkmcnt(0)
	v_mfma_f32_16x16x32_bf16 v[118:121], v[136:139], v[176:179], v[118:121]
	v_mfma_f32_16x16x32_bf16 v[114:117], v[144:147], v[176:179], v[114:117]
	v_mfma_f32_16x16x32_bf16 v[106:109], v[136:139], v[184:187], v[106:109]
	v_mfma_f32_16x16x32_bf16 v[98:101], v[144:147], v[184:187], v[98:101]
	v_mfma_f32_16x16x32_bf16 v[88:91], v[136:139], v[192:195], v[88:91]
	v_mfma_f32_16x16x32_bf16 v[80:83], v[144:147], v[192:195], v[80:83]
	v_mfma_f32_16x16x32_bf16 v[126:129], v[140:143], v[172:175], v[126:129]
	v_mfma_f32_16x16x32_bf16 v[122:125], v[148:151], v[172:175], v[122:125]
	v_mfma_f32_16x16x32_bf16 v[118:121], v[140:143], v[180:183], v[118:121]
	v_mfma_f32_16x16x32_bf16 v[114:117], v[148:151], v[180:183], v[114:117]
	v_mfma_f32_16x16x32_bf16 v[106:109], v[140:143], v[188:191], v[106:109]
	v_mfma_f32_16x16x32_bf16 v[98:101], v[148:151], v[188:191], v[98:101]
	v_mfma_f32_16x16x32_bf16 v[88:91], v[140:143], v[202:205], v[88:91]
	v_mfma_f32_16x16x32_bf16 v[80:83], v[148:151], v[202:205], v[80:83]
	s_setprio 0
	s_setprio 1
	v_mfma_f32_16x16x32_bf16 v[110:113], v[152:155], v[168:171], v[110:113]
	v_mfma_f32_16x16x32_bf16 v[102:105], v[160:163], v[168:171], v[102:105]
	v_mfma_f32_16x16x32_bf16 v[92:95], v[152:155], v[176:179], v[92:95]
	v_mfma_f32_16x16x32_bf16 v[84:87], v[160:163], v[176:179], v[84:87]
	v_mfma_f32_16x16x32_bf16 v[76:79], v[152:155], v[184:187], v[76:79]
	v_mfma_f32_16x16x32_bf16 v[72:75], v[160:163], v[184:187], v[72:75]
	v_mfma_f32_16x16x32_bf16 v[68:71], v[152:155], v[192:195], v[68:71]
	v_mfma_f32_16x16x32_bf16 v[64:67], v[160:163], v[192:195], v[64:67]
	v_mfma_f32_16x16x32_bf16 v[110:113], v[156:159], v[172:175], v[110:113]
	v_mfma_f32_16x16x32_bf16 v[102:105], v[164:167], v[172:175], v[102:105]
	v_mfma_f32_16x16x32_bf16 v[92:95], v[156:159], v[180:183], v[92:95]
	v_mfma_f32_16x16x32_bf16 v[84:87], v[164:167], v[180:183], v[84:87]
	v_mfma_f32_16x16x32_bf16 v[76:79], v[156:159], v[188:191], v[76:79]
	v_mfma_f32_16x16x32_bf16 v[72:75], v[164:167], v[188:191], v[72:75]
	v_mfma_f32_16x16x32_bf16 v[68:71], v[156:159], v[202:205], v[68:71]
	v_mfma_f32_16x16x32_bf16 v[64:67], v[164:167], v[202:205], v[64:67]
	s_setprio 0
	s_barrier
	s_mov_b32 m0, s40
	v_lshl_add_u64 v[198:199], s[74:75], 0, v[96:97]
	ds_read_b128 v[168:171], v135 offset:16384
	ds_read_b128 v[172:175], v135 offset:17408
	ds_read_b128 v[176:179], v135 offset:18432
	ds_read_b128 v[180:183], v135 offset:19456
	ds_read_b128 v[184:187], v135 offset:20480
	ds_read_b128 v[188:191], v135 offset:21504
	ds_read_b128 v[192:195], v135 offset:22528
	ds_read_b128 v[202:205], v135 offset:23552
	global_load_lds_dwordx4 v[198:199], off
	v_lshl_add_u64 v[200:201], s[74:75], 0, v[130:131]
	s_mov_b32 m0, s23
	v_lshl_add_u64 v[206:207], s[82:83], 0, v[96:97]
	global_load_lds_dwordx4 v[200:201], off
	s_mov_b32 m0, s37
	v_lshl_add_u64 v[208:209], s[72:73], 0, v[130:131]
	global_load_lds_dwordx4 v[206:207], off
	v_lshl_add_u64 v[206:207], s[82:83], 0, v[130:131]
	s_mov_b32 m0, s36
	s_nop 0
	global_load_lds_dwordx4 v[206:207], off
	v_lshl_add_u64 v[206:207], s[72:73], 0, v[96:97]
	s_mov_b32 m0, s5
	s_nop 0
	global_load_lds_dwordx4 v[206:207], off
	s_mov_b32 m0, s7
	s_nop 0
	global_load_lds_dwordx4 v[208:209], off
	s_waitcnt vmcnt(8)
	s_waitcnt lgkmcnt(0)
	v_mfma_f32_16x16x32_bf16 v[60:63], v[136:139], v[168:171], v[60:63]
	v_mfma_f32_16x16x32_bf16 v[56:59], v[144:147], v[168:171], v[56:59]
	s_barrier
	s_setprio 1
	s_waitcnt lgkmcnt(0)
	v_mfma_f32_16x16x32_bf16 v[52:55], v[136:139], v[176:179], v[52:55]
	v_mfma_f32_16x16x32_bf16 v[48:51], v[144:147], v[176:179], v[48:51]
	v_mfma_f32_16x16x32_bf16 v[36:39], v[136:139], v[184:187], v[36:39]
	v_mfma_f32_16x16x32_bf16 v[32:35], v[144:147], v[184:187], v[32:35]
	v_mfma_f32_16x16x32_bf16 v[20:23], v[136:139], v[192:195], v[20:23]
	v_mfma_f32_16x16x32_bf16 v[16:19], v[144:147], v[192:195], v[16:19]
	v_mfma_f32_16x16x32_bf16 v[60:63], v[140:143], v[172:175], v[60:63]
	v_mfma_f32_16x16x32_bf16 v[56:59], v[148:151], v[172:175], v[56:59]
	v_mfma_f32_16x16x32_bf16 v[52:55], v[140:143], v[180:183], v[52:55]
	v_mfma_f32_16x16x32_bf16 v[48:51], v[148:151], v[180:183], v[48:51]
	v_mfma_f32_16x16x32_bf16 v[36:39], v[140:143], v[188:191], v[36:39]
	v_mfma_f32_16x16x32_bf16 v[32:35], v[148:151], v[188:191], v[32:35]
	v_mfma_f32_16x16x32_bf16 v[20:23], v[140:143], v[202:205], v[20:23]
	v_mfma_f32_16x16x32_bf16 v[16:19], v[148:151], v[202:205], v[16:19]
	s_setprio 0
	s_setprio 1
	v_mfma_f32_16x16x32_bf16 v[44:47], v[152:155], v[168:171], v[44:47]
	v_mfma_f32_16x16x32_bf16 v[40:43], v[160:163], v[168:171], v[40:43]
	v_mfma_f32_16x16x32_bf16 v[28:31], v[152:155], v[176:179], v[28:31]
	v_mfma_f32_16x16x32_bf16 v[24:27], v[160:163], v[176:179], v[24:27]
	v_mfma_f32_16x16x32_bf16 v[12:15], v[152:155], v[184:187], v[12:15]
	v_mfma_f32_16x16x32_bf16 v[8:11], v[160:163], v[184:187], v[8:11]
	v_mfma_f32_16x16x32_bf16 v[4:7], v[152:155], v[192:195], v[4:7]
	v_mfma_f32_16x16x32_bf16 v[0:3], v[160:163], v[192:195], v[0:3]
	v_mfma_f32_16x16x32_bf16 v[44:47], v[156:159], v[172:175], v[44:47]
	v_mfma_f32_16x16x32_bf16 v[40:43], v[164:167], v[172:175], v[40:43]
	v_mfma_f32_16x16x32_bf16 v[28:31], v[156:159], v[180:183], v[28:31]
	v_mfma_f32_16x16x32_bf16 v[24:27], v[164:167], v[180:183], v[24:27]
	v_mfma_f32_16x16x32_bf16 v[12:15], v[156:159], v[188:191], v[12:15]
	v_mfma_f32_16x16x32_bf16 v[8:11], v[164:167], v[188:191], v[8:11]
	v_mfma_f32_16x16x32_bf16 v[4:7], v[156:159], v[202:205], v[4:7]
	v_mfma_f32_16x16x32_bf16 v[0:3], v[164:167], v[202:205], v[0:3]
	s_setprio 0
	s_barrier
	v_add_u32_e32 v148, s13, v132
	v_add_u32_e32 v164, s6, v132
	ds_read_b128 v[136:139], v148
	ds_read_b128 v[140:143], v148 offset:1024
	ds_read_b128 v[144:147], v148 offset:2048
	ds_read_b128 v[148:151], v148 offset:3072
	ds_read_b128 v[152:155], v164
	ds_read_b128 v[156:159], v164 offset:1024
	ds_read_b128 v[160:163], v164 offset:2048
	ds_read_b128 v[164:167], v164 offset:3072
	s_mov_b32 m0, s15
	v_lshl_add_u64 v[214:215], s[62:63], 0, v[96:97]
	ds_read_b128 v[168:171], v135 offset:32768
	ds_read_b128 v[172:175], v135 offset:33792
	ds_read_b128 v[176:179], v135 offset:34816
	ds_read_b128 v[180:183], v135 offset:35840
	ds_read_b128 v[184:187], v135 offset:36864
	ds_read_b128 v[188:191], v135 offset:37888
	ds_read_b128 v[192:195], v135 offset:38912
	ds_read_b128 v[202:205], v135 offset:39936
	global_load_lds_dwordx4 v[214:215], off
	v_lshl_add_u64 v[214:215], s[62:63], 0, v[130:131]
	s_mov_b32 m0, s17
	s_nop 0
	global_load_lds_dwordx4 v[214:215], off
	s_waitcnt vmcnt(8)
	s_waitcnt lgkmcnt(0)
	v_mfma_f32_16x16x32_bf16 v[126:129], v[136:139], v[168:171], v[126:129]
	v_mfma_f32_16x16x32_bf16 v[122:125], v[144:147], v[168:171], v[122:125]
	s_barrier
	s_setprio 1
	s_waitcnt lgkmcnt(0)
	v_mfma_f32_16x16x32_bf16 v[118:121], v[136:139], v[176:179], v[118:121]
	v_mfma_f32_16x16x32_bf16 v[114:117], v[144:147], v[176:179], v[114:117]
	v_mfma_f32_16x16x32_bf16 v[106:109], v[136:139], v[184:187], v[106:109]
	v_mfma_f32_16x16x32_bf16 v[98:101], v[144:147], v[184:187], v[98:101]
	v_mfma_f32_16x16x32_bf16 v[88:91], v[136:139], v[192:195], v[88:91]
	v_mfma_f32_16x16x32_bf16 v[80:83], v[144:147], v[192:195], v[80:83]
	v_mfma_f32_16x16x32_bf16 v[126:129], v[140:143], v[172:175], v[126:129]
	v_mfma_f32_16x16x32_bf16 v[122:125], v[148:151], v[172:175], v[122:125]
	v_mfma_f32_16x16x32_bf16 v[118:121], v[140:143], v[180:183], v[118:121]
	v_mfma_f32_16x16x32_bf16 v[114:117], v[148:151], v[180:183], v[114:117]
	v_mfma_f32_16x16x32_bf16 v[106:109], v[140:143], v[188:191], v[106:109]
	v_mfma_f32_16x16x32_bf16 v[98:101], v[148:151], v[188:191], v[98:101]
	v_mfma_f32_16x16x32_bf16 v[88:91], v[140:143], v[202:205], v[88:91]
	v_mfma_f32_16x16x32_bf16 v[80:83], v[148:151], v[202:205], v[80:83]
	s_setprio 0
	s_setprio 1
	v_mfma_f32_16x16x32_bf16 v[110:113], v[152:155], v[168:171], v[110:113]
	v_mfma_f32_16x16x32_bf16 v[102:105], v[160:163], v[168:171], v[102:105]
	v_mfma_f32_16x16x32_bf16 v[92:95], v[152:155], v[176:179], v[92:95]
	v_mfma_f32_16x16x32_bf16 v[84:87], v[160:163], v[176:179], v[84:87]
	v_mfma_f32_16x16x32_bf16 v[76:79], v[152:155], v[184:187], v[76:79]
	v_mfma_f32_16x16x32_bf16 v[72:75], v[160:163], v[184:187], v[72:75]
	v_mfma_f32_16x16x32_bf16 v[68:71], v[152:155], v[192:195], v[68:71]
	v_mfma_f32_16x16x32_bf16 v[64:67], v[160:163], v[192:195], v[64:67]
	v_mfma_f32_16x16x32_bf16 v[110:113], v[156:159], v[172:175], v[110:113]
	v_mfma_f32_16x16x32_bf16 v[102:105], v[164:167], v[172:175], v[102:105]
	v_mfma_f32_16x16x32_bf16 v[92:95], v[156:159], v[180:183], v[92:95]
	v_mfma_f32_16x16x32_bf16 v[84:87], v[164:167], v[180:183], v[84:87]
	v_mfma_f32_16x16x32_bf16 v[76:79], v[156:159], v[188:191], v[76:79]
	v_mfma_f32_16x16x32_bf16 v[72:75], v[164:167], v[188:191], v[72:75]
	v_mfma_f32_16x16x32_bf16 v[68:71], v[156:159], v[202:205], v[68:71]
	v_mfma_f32_16x16x32_bf16 v[64:67], v[164:167], v[202:205], v[64:67]
	s_setprio 0
	s_barrier
	s_mov_b32 m0, s3
	v_lshl_add_u64 v[198:199], v[198:199], 0, s[30:31]
	ds_read_b128 v[168:171], v135 offset:49152
	ds_read_b128 v[172:175], v135 offset:50176
	ds_read_b128 v[176:179], v135 offset:51200
	ds_read_b128 v[180:183], v135 offset:52224
	ds_read_b128 v[184:187], v135 offset:53248
	ds_read_b128 v[188:191], v135 offset:54272
	ds_read_b128 v[192:195], v135 offset:55296
	ds_read_b128 v[202:205], v135 offset:56320
	global_load_lds_dwordx4 v[198:199], off
	v_lshl_add_u64 v[198:199], v[200:201], 0, s[30:31]
	s_mov_b32 m0, s2
	s_nop 0
	global_load_lds_dwordx4 v[198:199], off
	v_lshl_add_u64 v[198:199], s[60:61], 0, v[96:97]
	s_mov_b32 m0, s49
	s_nop 0
	global_load_lds_dwordx4 v[198:199], off
	v_lshl_add_u64 v[198:199], s[60:61], 0, v[130:131]
	s_mov_b32 m0, s47
	s_nop 0
	global_load_lds_dwordx4 v[198:199], off
	v_lshl_add_u64 v[198:199], v[206:207], 0, s[30:31]
	s_mov_b32 m0, s18
	s_nop 0
	global_load_lds_dwordx4 v[198:199], off
	v_lshl_add_u64 v[198:199], v[208:209], 0, s[30:31]
	s_mov_b32 m0, s19
	s_nop 0
	global_load_lds_dwordx4 v[198:199], off
	s_waitcnt vmcnt(8)
	s_waitcnt lgkmcnt(0)
	v_mfma_f32_16x16x32_bf16 v[60:63], v[136:139], v[168:171], v[60:63]
	v_mfma_f32_16x16x32_bf16 v[56:59], v[144:147], v[168:171], v[56:59]
	s_barrier
	s_setprio 1
	s_waitcnt lgkmcnt(0)
	v_mfma_f32_16x16x32_bf16 v[52:55], v[136:139], v[176:179], v[52:55]
	v_mfma_f32_16x16x32_bf16 v[48:51], v[144:147], v[176:179], v[48:51]
	v_mfma_f32_16x16x32_bf16 v[36:39], v[136:139], v[184:187], v[36:39]
	v_mfma_f32_16x16x32_bf16 v[32:35], v[144:147], v[184:187], v[32:35]
	v_mfma_f32_16x16x32_bf16 v[20:23], v[136:139], v[192:195], v[20:23]
	v_mfma_f32_16x16x32_bf16 v[16:19], v[144:147], v[192:195], v[16:19]
	v_mfma_f32_16x16x32_bf16 v[60:63], v[140:143], v[172:175], v[60:63]
	v_mfma_f32_16x16x32_bf16 v[56:59], v[148:151], v[172:175], v[56:59]
	v_mfma_f32_16x16x32_bf16 v[52:55], v[140:143], v[180:183], v[52:55]
	v_mfma_f32_16x16x32_bf16 v[48:51], v[148:151], v[180:183], v[48:51]
	v_mfma_f32_16x16x32_bf16 v[36:39], v[140:143], v[188:191], v[36:39]
	v_mfma_f32_16x16x32_bf16 v[32:35], v[148:151], v[188:191], v[32:35]
	v_mfma_f32_16x16x32_bf16 v[20:23], v[140:143], v[202:205], v[20:23]
	v_mfma_f32_16x16x32_bf16 v[16:19], v[148:151], v[202:205], v[16:19]
	s_setprio 0
	s_setprio 1
	v_mfma_f32_16x16x32_bf16 v[44:47], v[152:155], v[168:171], v[44:47]
	v_mfma_f32_16x16x32_bf16 v[40:43], v[160:163], v[168:171], v[40:43]
	v_mfma_f32_16x16x32_bf16 v[28:31], v[152:155], v[176:179], v[28:31]
	v_mfma_f32_16x16x32_bf16 v[24:27], v[160:163], v[176:179], v[24:27]
	v_mfma_f32_16x16x32_bf16 v[12:15], v[152:155], v[184:187], v[12:15]
	v_mfma_f32_16x16x32_bf16 v[8:11], v[160:163], v[184:187], v[8:11]
	v_mfma_f32_16x16x32_bf16 v[4:7], v[152:155], v[192:195], v[4:7]
	v_mfma_f32_16x16x32_bf16 v[0:3], v[160:163], v[192:195], v[0:3]
	v_mfma_f32_16x16x32_bf16 v[44:47], v[156:159], v[172:175], v[44:47]
	v_mfma_f32_16x16x32_bf16 v[40:43], v[164:167], v[172:175], v[40:43]
	v_mfma_f32_16x16x32_bf16 v[28:31], v[156:159], v[180:183], v[28:31]
	v_mfma_f32_16x16x32_bf16 v[24:27], v[164:167], v[180:183], v[24:27]
	v_mfma_f32_16x16x32_bf16 v[12:15], v[156:159], v[188:191], v[12:15]
	v_mfma_f32_16x16x32_bf16 v[8:11], v[164:167], v[188:191], v[8:11]
	v_mfma_f32_16x16x32_bf16 v[4:7], v[156:159], v[202:205], v[4:7]
	v_mfma_f32_16x16x32_bf16 v[0:3], v[164:167], v[202:205], v[0:3]
	s_setprio 0
	s_barrier
	s_movk_i32 s2, 0x100
	s_andn2_b64 vcc, exec, s[58:59]
	s_mov_b64 s[60:61], -1
	s_mov_b64 s[58:59], 0
	s_cbranch_vccz .LBB0_973
	s_and_b64 vcc, exec, s[38:39]
	s_cbranch_vccz .LBB0_976
	s_barrier

.LBB0_993:
	s_add_u32 s3, s24, s46
	s_addc_u32 s6, s25, s47
	s_add_u32 s3, s3, 0x100
	s_addc_u32 s6, s6, 0
	s_add_u32 s48, s59, s46
	s_addc_u32 s49, s60, s47
	s_add_i32 s63, 0, 0x10000
	s_cmpk_eq_i32 s46, 0xf00
	s_cselect_b32 s51, s23, s6
	s_cselect_b32 s50, s61, s3
	v_add_u32_e32 v146, s63, v144
	s_cselect_b32 s49, s15, s49
	s_cselect_b32 s48, s62, s48
	s_add_i32 s3, 0, 0x14000
	ds_read_b128 v[154:157], v146
	ds_read_b128 v[158:161], v146 offset:1024
	ds_read_b128 v[162:165], v146 offset:2048
	ds_read_b128 v[166:169], v146 offset:3072
	v_add_u32_e32 v146, s3, v144
	ds_read_b128 v[174:177], v146
	ds_read_b128 v[178:181], v146 offset:1024
	ds_read_b128 v[182:185], v146 offset:2048
	ds_read_b128 v[186:189], v146 offset:3072
	v_lshl_add_u64 v[146:147], v[140:141], 0, s[46:47]
	s_add_i32 m0, s17, 0xc000
	ds_read_b128 v[190:193], v145
	ds_read_b128 v[202:205], v145 offset:1024
	ds_read_b128 v[206:209], v145 offset:2048
	ds_read_b128 v[214:217], v145 offset:3072
	ds_read_b128 v[218:221], v145 offset:4096
	ds_read_b128 v[222:225], v145 offset:5120
	ds_read_b128 v[226:229], v145 offset:6144
	ds_read_b128 v[230:233], v145 offset:7168
	global_load_lds_dwordx4 v[146:147], off
	v_lshl_add_u64 v[146:147], v[142:143], 0, s[46:47]
	s_add_i32 m0, s17, 0xe000
	s_nop 0
	global_load_lds_dwordx4 v[146:147], off
	s_waitcnt vmcnt(8)
	s_waitcnt lgkmcnt(0)
	v_mfma_f32_16x16x32_bf16 v[110:113], v[154:157], v[190:193], v[110:113]
	v_mfma_f32_16x16x32_bf16 v[106:109], v[162:165], v[190:193], v[106:109]
	s_barrier
	s_setprio 1
	s_waitcnt lgkmcnt(0)
	v_mfma_f32_16x16x32_bf16 v[118:121], v[154:157], v[206:209], v[118:121]
	v_mfma_f32_16x16x32_bf16 v[114:117], v[162:165], v[206:209], v[114:117]
	v_mfma_f32_16x16x32_bf16 v[126:129], v[154:157], v[218:221], v[126:129]
	v_mfma_f32_16x16x32_bf16 v[122:125], v[162:165], v[218:221], v[122:125]
	v_mfma_f32_16x16x32_bf16 v[92:95], v[154:157], v[226:229], v[92:95]
	v_mfma_f32_16x16x32_bf16 v[88:91], v[162:165], v[226:229], v[88:91]
	v_mfma_f32_16x16x32_bf16 v[110:113], v[158:161], v[202:205], v[110:113]
	v_mfma_f32_16x16x32_bf16 v[106:109], v[166:169], v[202:205], v[106:109]
	v_mfma_f32_16x16x32_bf16 v[118:121], v[158:161], v[214:217], v[118:121]
	v_mfma_f32_16x16x32_bf16 v[114:117], v[166:169], v[214:217], v[114:117]
	v_mfma_f32_16x16x32_bf16 v[126:129], v[158:161], v[222:225], v[126:129]
	v_mfma_f32_16x16x32_bf16 v[122:125], v[166:169], v[222:225], v[122:125]
	v_mfma_f32_16x16x32_bf16 v[92:95], v[158:161], v[230:233], v[92:95]
	v_mfma_f32_16x16x32_bf16 v[88:91], v[166:169], v[230:233], v[88:91]
	s_setprio 0
	s_setprio 1
	v_mfma_f32_16x16x32_bf16 v[4:7], v[174:177], v[190:193], v[4:7]
	v_mfma_f32_16x16x32_bf16 v[0:3], v[182:185], v[190:193], v[0:3]
	v_mfma_f32_16x16x32_bf16 v[12:15], v[174:177], v[206:209], v[12:15]
	v_mfma_f32_16x16x32_bf16 v[8:11], v[182:185], v[206:209], v[8:11]
	v_mfma_f32_16x16x32_bf16 v[24:27], v[174:177], v[218:221], v[24:27]
	v_mfma_f32_16x16x32_bf16 v[20:23], v[182:185], v[218:221], v[20:23]
	v_mfma_f32_16x16x32_bf16 v[40:43], v[174:177], v[226:229], v[40:43]
	v_mfma_f32_16x16x32_bf16 v[32:35], v[182:185], v[226:229], v[32:35]
	v_mfma_f32_16x16x32_bf16 v[4:7], v[178:181], v[202:205], v[4:7]
	v_mfma_f32_16x16x32_bf16 v[0:3], v[186:189], v[202:205], v[0:3]
	v_mfma_f32_16x16x32_bf16 v[12:15], v[178:181], v[214:217], v[12:15]
	v_mfma_f32_16x16x32_bf16 v[8:11], v[186:189], v[214:217], v[8:11]
	v_mfma_f32_16x16x32_bf16 v[24:27], v[178:181], v[222:225], v[24:27]
	v_mfma_f32_16x16x32_bf16 v[20:23], v[186:189], v[222:225], v[20:23]
	v_mfma_f32_16x16x32_bf16 v[40:43], v[178:181], v[230:233], v[40:43]
	v_mfma_f32_16x16x32_bf16 v[32:35], v[186:189], v[230:233], v[32:35]
	s_setprio 0
	s_barrier
	s_add_i32 s6, s63, s5
	v_lshl_add_u64 v[146:147], s[48:49], 0, v[96:97]
	s_mov_b32 m0, s6
	ds_read_b128 v[190:193], v145 offset:16384
	ds_read_b128 v[202:205], v145 offset:17408
	ds_read_b128 v[206:209], v145 offset:18432
	ds_read_b128 v[214:217], v145 offset:19456
	ds_read_b128 v[218:221], v145 offset:20480
	ds_read_b128 v[222:225], v145 offset:21504
	ds_read_b128 v[226:229], v145 offset:22528
	ds_read_b128 v[230:233], v145 offset:23552
	global_load_lds_dwordx4 v[146:147], off
	s_add_i32 m0, s6, 0x2000
	s_add_u32 s72, s48, 0x80000
	v_lshl_add_u64 v[150:151], s[48:49], 0, v[130:131]
	s_addc_u32 s73, s49, 0
	s_add_i32 s3, s3, s5
	global_load_lds_dwordx4 v[150:151], off
	v_lshl_add_u64 v[170:171], s[72:73], 0, v[96:97]
	s_mov_b32 m0, s3
	v_lshl_add_u64 v[194:195], s[50:51], 0, v[132:133]
	global_load_lds_dwordx4 v[170:171], off
	v_lshl_add_u64 v[170:171], s[72:73], 0, v[130:131]
	s_add_i32 m0, s3, 0x2000
	s_nop 0
	global_load_lds_dwordx4 v[170:171], off
	v_lshl_add_u64 v[170:171], s[50:51], 0, v[134:135]
	s_mov_b32 m0, s17
	s_nop 0
	global_load_lds_dwordx4 v[170:171], off
	s_mov_b32 m0, s18
	s_nop 0
	global_load_lds_dwordx4 v[194:195], off
	s_waitcnt vmcnt(8)
	s_waitcnt lgkmcnt(0)
	v_mfma_f32_16x16x32_bf16 v[102:105], v[154:157], v[190:193], v[102:105]
	v_mfma_f32_16x16x32_bf16 v[98:101], v[162:165], v[190:193], v[98:101]
	s_barrier
	s_setprio 1
	s_waitcnt lgkmcnt(0)
	v_mfma_f32_16x16x32_bf16 v[84:87], v[154:157], v[206:209], v[84:87]
	v_mfma_f32_16x16x32_bf16 v[80:83], v[162:165], v[206:209], v[80:83]
	v_mfma_f32_16x16x32_bf16 v[68:71], v[154:157], v[218:221], v[68:71]
	v_mfma_f32_16x16x32_bf16 v[64:67], v[162:165], v[218:221], v[64:67]
	v_mfma_f32_16x16x32_bf16 v[44:47], v[154:157], v[226:229], v[44:47]
	v_mfma_f32_16x16x32_bf16 v[36:39], v[162:165], v[226:229], v[36:39]
	v_mfma_f32_16x16x32_bf16 v[102:105], v[158:161], v[202:205], v[102:105]
	v_mfma_f32_16x16x32_bf16 v[98:101], v[166:169], v[202:205], v[98:101]
	v_mfma_f32_16x16x32_bf16 v[84:87], v[158:161], v[214:217], v[84:87]
	v_mfma_f32_16x16x32_bf16 v[80:83], v[166:169], v[214:217], v[80:83]
	v_mfma_f32_16x16x32_bf16 v[68:71], v[158:161], v[222:225], v[68:71]
	v_mfma_f32_16x16x32_bf16 v[64:67], v[166:169], v[222:225], v[64:67]
	v_mfma_f32_16x16x32_bf16 v[44:47], v[158:161], v[230:233], v[44:47]
	v_mfma_f32_16x16x32_bf16 v[36:39], v[166:169], v[230:233], v[36:39]
	s_setprio 0
	s_setprio 1
	v_mfma_f32_16x16x32_bf16 v[60:63], v[174:177], v[190:193], v[60:63]
	v_mfma_f32_16x16x32_bf16 v[56:59], v[182:185], v[190:193], v[56:59]
	v_mfma_f32_16x16x32_bf16 v[76:79], v[174:177], v[206:209], v[76:79]
	v_mfma_f32_16x16x32_bf16 v[72:75], v[182:185], v[206:209], v[72:75]
	v_mfma_f32_16x16x32_bf16 v[52:55], v[174:177], v[218:221], v[52:55]
	v_mfma_f32_16x16x32_bf16 v[48:51], v[182:185], v[218:221], v[48:51]
	v_mfma_f32_16x16x32_bf16 v[28:31], v[174:177], v[226:229], v[28:31]
	v_mfma_f32_16x16x32_bf16 v[16:19], v[182:185], v[226:229], v[16:19]
	v_mfma_f32_16x16x32_bf16 v[60:63], v[178:181], v[202:205], v[60:63]
	v_mfma_f32_16x16x32_bf16 v[56:59], v[186:189], v[202:205], v[56:59]
	v_mfma_f32_16x16x32_bf16 v[76:79], v[178:181], v[214:217], v[76:79]
	v_mfma_f32_16x16x32_bf16 v[72:75], v[186:189], v[214:217], v[72:75]
	v_mfma_f32_16x16x32_bf16 v[52:55], v[178:181], v[222:225], v[52:55]
	v_mfma_f32_16x16x32_bf16 v[48:51], v[186:189], v[222:225], v[48:51]
	v_mfma_f32_16x16x32_bf16 v[28:31], v[178:181], v[230:233], v[28:31]
	v_mfma_f32_16x16x32_bf16 v[16:19], v[186:189], v[230:233], v[16:19]
	s_setprio 0
	s_barrier
	s_add_i32 s3, 0, 0x18000
	v_add_u32_e32 v149, s3, v144
	s_add_i32 s6, 0, 0x1c000
	ds_read_b128 v[154:157], v149
	ds_read_b128 v[158:161], v149 offset:1024
	ds_read_b128 v[162:165], v149 offset:2048
	ds_read_b128 v[166:169], v149 offset:3072
	v_add_u32_e32 v149, s6, v144
	ds_read_b128 v[174:177], v149
	ds_read_b128 v[178:181], v149 offset:1024
	ds_read_b128 v[182:185], v149 offset:2048
	ds_read_b128 v[186:189], v149 offset:3072
	s_add_u32 s50, s50, 0x80000
	s_addc_u32 s51, s51, 0
	s_mov_b32 m0, s19
	v_lshl_add_u64 v[198:199], s[50:51], 0, v[134:135]
	ds_read_b128 v[190:193], v145 offset:32768
	ds_read_b128 v[202:205], v145 offset:33792
	ds_read_b128 v[206:209], v145 offset:34816
	ds_read_b128 v[214:217], v145 offset:35840
	ds_read_b128 v[218:221], v145 offset:36864
	ds_read_b128 v[222:225], v145 offset:37888
	ds_read_b128 v[226:229], v145 offset:38912
	ds_read_b128 v[230:233], v145 offset:39936
	global_load_lds_dwordx4 v[198:199], off
	v_lshl_add_u64 v[198:199], s[50:51], 0, v[132:133]
	s_mov_b32 m0, s20
	s_nop 0
	global_load_lds_dwordx4 v[198:199], off
	s_waitcnt vmcnt(8)
	s_waitcnt lgkmcnt(0)
	v_mfma_f32_16x16x32_bf16 v[110:113], v[154:157], v[190:193], v[110:113]
	v_mfma_f32_16x16x32_bf16 v[106:109], v[162:165], v[190:193], v[106:109]
	s_barrier
	s_setprio 1
	s_waitcnt lgkmcnt(0)
	v_mfma_f32_16x16x32_bf16 v[118:121], v[154:157], v[206:209], v[118:121]
	v_mfma_f32_16x16x32_bf16 v[114:117], v[162:165], v[206:209], v[114:117]
	v_mfma_f32_16x16x32_bf16 v[126:129], v[154:157], v[218:221], v[126:129]
	v_mfma_f32_16x16x32_bf16 v[122:125], v[162:165], v[218:221], v[122:125]
	v_mfma_f32_16x16x32_bf16 v[92:95], v[154:157], v[226:229], v[92:95]
	v_mfma_f32_16x16x32_bf16 v[88:91], v[162:165], v[226:229], v[88:91]
	v_mfma_f32_16x16x32_bf16 v[110:113], v[158:161], v[202:205], v[110:113]
	v_mfma_f32_16x16x32_bf16 v[106:109], v[166:169], v[202:205], v[106:109]
	v_mfma_f32_16x16x32_bf16 v[118:121], v[158:161], v[214:217], v[118:121]
	v_mfma_f32_16x16x32_bf16 v[114:117], v[166:169], v[214:217], v[114:117]
	v_mfma_f32_16x16x32_bf16 v[126:129], v[158:161], v[222:225], v[126:129]
	v_mfma_f32_16x16x32_bf16 v[122:125], v[166:169], v[222:225], v[122:125]
	v_mfma_f32_16x16x32_bf16 v[92:95], v[158:161], v[230:233], v[92:95]
	v_mfma_f32_16x16x32_bf16 v[88:91], v[166:169], v[230:233], v[88:91]
	s_setprio 0
	s_setprio 1
	v_mfma_f32_16x16x32_bf16 v[4:7], v[174:177], v[190:193], v[4:7]
	v_mfma_f32_16x16x32_bf16 v[0:3], v[182:185], v[190:193], v[0:3]
	v_mfma_f32_16x16x32_bf16 v[12:15], v[174:177], v[206:209], v[12:15]
	v_mfma_f32_16x16x32_bf16 v[8:11], v[182:185], v[206:209], v[8:11]
	v_mfma_f32_16x16x32_bf16 v[24:27], v[174:177], v[218:221], v[24:27]
	v_mfma_f32_16x16x32_bf16 v[20:23], v[182:185], v[218:221], v[20:23]
	v_mfma_f32_16x16x32_bf16 v[40:43], v[174:177], v[226:229], v[40:43]
	v_mfma_f32_16x16x32_bf16 v[32:35], v[182:185], v[226:229], v[32:35]
	v_mfma_f32_16x16x32_bf16 v[4:7], v[178:181], v[202:205], v[4:7]
	v_mfma_f32_16x16x32_bf16 v[0:3], v[186:189], v[202:205], v[0:3]
	v_mfma_f32_16x16x32_bf16 v[12:15], v[178:181], v[214:217], v[12:15]
	v_mfma_f32_16x16x32_bf16 v[8:11], v[186:189], v[214:217], v[8:11]
	v_mfma_f32_16x16x32_bf16 v[24:27], v[178:181], v[222:225], v[24:27]
	v_mfma_f32_16x16x32_bf16 v[20:23], v[186:189], v[222:225], v[20:23]
	v_mfma_f32_16x16x32_bf16 v[40:43], v[178:181], v[230:233], v[40:43]
	v_mfma_f32_16x16x32_bf16 v[32:35], v[186:189], v[230:233], v[32:35]
	s_setprio 0
	s_barrier
	s_add_i32 s3, s3, s5
	v_lshl_add_u64 v[146:147], v[146:147], 0, s[30:31]
	s_mov_b32 m0, s3
	ds_read_b128 v[190:193], v145 offset:49152
	ds_read_b128 v[202:205], v145 offset:50176
	ds_read_b128 v[206:209], v145 offset:51200
	ds_read_b128 v[214:217], v145 offset:52224
	ds_read_b128 v[218:221], v145 offset:53248
	ds_read_b128 v[222:225], v145 offset:54272
	ds_read_b128 v[226:229], v145 offset:55296
	ds_read_b128 v[230:233], v145 offset:56320
	global_load_lds_dwordx4 v[146:147], off
	s_add_i32 m0, s3, 0x2000
	s_add_u32 s48, s48, 0x80080
	v_lshl_add_u64 v[146:147], v[150:151], 0, s[30:31]
	s_addc_u32 s49, s49, 0
	s_add_i32 s3, s6, s5
	global_load_lds_dwordx4 v[146:147], off
	v_lshl_add_u64 v[146:147], s[48:49], 0, v[96:97]
	s_mov_b32 m0, s3
	s_nop 0
	global_load_lds_dwordx4 v[146:147], off
	v_lshl_add_u64 v[146:147], s[48:49], 0, v[130:131]
	s_add_i32 m0, s3, 0x2000
	s_nop 0
	global_load_lds_dwordx4 v[146:147], off
	v_lshl_add_u64 v[146:147], v[170:171], 0, s[30:31]
	s_mov_b32 m0, s37
	s_nop 0
	global_load_lds_dwordx4 v[146:147], off
	v_lshl_add_u64 v[146:147], v[194:195], 0, s[30:31]
	s_mov_b32 m0, s56
	s_nop 0
	global_load_lds_dwordx4 v[146:147], off
	s_waitcnt vmcnt(8)
	s_waitcnt lgkmcnt(0)
	v_mfma_f32_16x16x32_bf16 v[102:105], v[154:157], v[190:193], v[102:105]
	v_mfma_f32_16x16x32_bf16 v[98:101], v[162:165], v[190:193], v[98:101]
	s_barrier
	s_setprio 1
	s_waitcnt lgkmcnt(0)
	v_mfma_f32_16x16x32_bf16 v[84:87], v[154:157], v[206:209], v[84:87]
	v_mfma_f32_16x16x32_bf16 v[80:83], v[162:165], v[206:209], v[80:83]
	v_mfma_f32_16x16x32_bf16 v[68:71], v[154:157], v[218:221], v[68:71]
	v_mfma_f32_16x16x32_bf16 v[64:67], v[162:165], v[218:221], v[64:67]
	v_mfma_f32_16x16x32_bf16 v[44:47], v[154:157], v[226:229], v[44:47]
	v_mfma_f32_16x16x32_bf16 v[36:39], v[162:165], v[226:229], v[36:39]
	v_mfma_f32_16x16x32_bf16 v[102:105], v[158:161], v[202:205], v[102:105]
	v_mfma_f32_16x16x32_bf16 v[98:101], v[166:169], v[202:205], v[98:101]
	v_mfma_f32_16x16x32_bf16 v[84:87], v[158:161], v[214:217], v[84:87]
	v_mfma_f32_16x16x32_bf16 v[80:83], v[166:169], v[214:217], v[80:83]
	v_mfma_f32_16x16x32_bf16 v[68:71], v[158:161], v[222:225], v[68:71]
	v_mfma_f32_16x16x32_bf16 v[64:67], v[166:169], v[222:225], v[64:67]
	v_mfma_f32_16x16x32_bf16 v[44:47], v[158:161], v[230:233], v[44:47]
	v_mfma_f32_16x16x32_bf16 v[36:39], v[166:169], v[230:233], v[36:39]
	s_setprio 0
	s_setprio 1
	v_mfma_f32_16x16x32_bf16 v[60:63], v[174:177], v[190:193], v[60:63]
	v_mfma_f32_16x16x32_bf16 v[56:59], v[182:185], v[190:193], v[56:59]
	v_mfma_f32_16x16x32_bf16 v[76:79], v[174:177], v[206:209], v[76:79]
	v_mfma_f32_16x16x32_bf16 v[72:75], v[182:185], v[206:209], v[72:75]
	v_mfma_f32_16x16x32_bf16 v[52:55], v[174:177], v[218:221], v[52:55]
	v_mfma_f32_16x16x32_bf16 v[48:51], v[182:185], v[218:221], v[48:51]
	v_mfma_f32_16x16x32_bf16 v[28:31], v[174:177], v[226:229], v[28:31]
	v_mfma_f32_16x16x32_bf16 v[16:19], v[182:185], v[226:229], v[16:19]
	v_mfma_f32_16x16x32_bf16 v[60:63], v[178:181], v[202:205], v[60:63]
	v_mfma_f32_16x16x32_bf16 v[56:59], v[186:189], v[202:205], v[56:59]
	v_mfma_f32_16x16x32_bf16 v[76:79], v[178:181], v[214:217], v[76:79]
	v_mfma_f32_16x16x32_bf16 v[72:75], v[186:189], v[214:217], v[72:75]
	v_mfma_f32_16x16x32_bf16 v[52:55], v[178:181], v[222:225], v[52:55]
	v_mfma_f32_16x16x32_bf16 v[48:51], v[186:189], v[222:225], v[48:51]
	v_mfma_f32_16x16x32_bf16 v[28:31], v[178:181], v[230:233], v[28:31]
	v_mfma_f32_16x16x32_bf16 v[16:19], v[186:189], v[230:233], v[16:19]
	s_setprio 0
	s_barrier
	s_add_i32 s2, s2, 2
	s_add_u32 s46, s46, 0x100
	s_addc_u32 s47, s47, 0
	s_cmp_gt_u32 s2, 29
	s_cbranch_scc0 .LBB0_993
	s_and_b64 vcc, exec, s[12:13]
	s_cbranch_vccz .LBB0_996
	s_barrier

.LBB0_1158:
	s_add_u32 s34, s62, 0x100
	s_addc_u32 s35, s63, 0
	s_add_i32 s67, 0, 0x10000
	s_cmp_eq_u32 s6, 28
	s_cselect_b32 s89, s23, s35
	s_cselect_b32 s88, s61, s34
	s_cselect_b32 vcc_hi, s91, s3
	s_cselect_b32 vcc_lo, s93, s2
	s_add_i32 s76, 0, 0x14000
	v_add_u32_e32 v142, s67, v191
	v_add_u32_e32 v158, s76, v191
	ds_read_b128 v[130:133], v142
	ds_read_b128 v[134:137], v142 offset:1024
	ds_read_b128 v[138:141], v142 offset:2048
	ds_read_b128 v[142:145], v142 offset:3072
	ds_read_b128 v[146:149], v158
	ds_read_b128 v[150:153], v158 offset:1024
	ds_read_b128 v[154:157], v158 offset:2048
	ds_read_b128 v[158:161], v158 offset:3072
	v_lshl_add_u64 v[188:189], s[62:63], 0, v[184:185]
	s_add_i32 m0, s17, 0xc000
	ds_read_b128 v[162:165], v224
	ds_read_b128 v[166:169], v224 offset:1024
	ds_read_b128 v[170:173], v224 offset:2048
	ds_read_b128 v[178:181], v224 offset:3072
	ds_read_b128 v[202:205], v224 offset:4096
	ds_read_b128 v[206:209], v224 offset:5120
	ds_read_b128 v[226:229], v224 offset:6144
	ds_read_b128 v[230:233], v224 offset:7168
	global_load_lds_dwordx4 v[188:189], off
	v_lshl_add_u64 v[188:189], s[62:63], 0, v[186:187]
	s_add_i32 m0, s17, 0xe000
	s_nop 0
	global_load_lds_dwordx4 v[188:189], off
	s_waitcnt vmcnt(8)
	s_waitcnt lgkmcnt(0)
	v_mfma_f32_16x16x32_bf16 v[126:129], v[130:133], v[162:165], v[126:129]
	v_mfma_f32_16x16x32_bf16 v[56:59], v[138:141], v[162:165], v[56:59]
	s_barrier
	s_setprio 1
	s_waitcnt lgkmcnt(0)
	v_mfma_f32_16x16x32_bf16 v[122:125], v[130:133], v[170:173], v[122:125]
	v_mfma_f32_16x16x32_bf16 v[52:55], v[138:141], v[170:173], v[52:55]
	v_mfma_f32_16x16x32_bf16 v[118:121], v[130:133], v[202:205], v[118:121]
	v_mfma_f32_16x16x32_bf16 v[60:63], v[138:141], v[202:205], v[60:63]
	v_mfma_f32_16x16x32_bf16 v[114:117], v[130:133], v[226:229], v[114:117]
	v_mfma_f32_16x16x32_bf16 v[44:47], v[138:141], v[226:229], v[44:47]
	v_mfma_f32_16x16x32_bf16 v[126:129], v[134:137], v[166:169], v[126:129]
	v_mfma_f32_16x16x32_bf16 v[56:59], v[142:145], v[166:169], v[56:59]
	v_mfma_f32_16x16x32_bf16 v[122:125], v[134:137], v[178:181], v[122:125]
	v_mfma_f32_16x16x32_bf16 v[52:55], v[142:145], v[178:181], v[52:55]
	v_mfma_f32_16x16x32_bf16 v[118:121], v[134:137], v[206:209], v[118:121]
	v_mfma_f32_16x16x32_bf16 v[60:63], v[142:145], v[206:209], v[60:63]
	v_mfma_f32_16x16x32_bf16 v[114:117], v[134:137], v[230:233], v[114:117]
	v_mfma_f32_16x16x32_bf16 v[44:47], v[142:145], v[230:233], v[44:47]
	s_setprio 0
	s_setprio 1
	v_mfma_f32_16x16x32_bf16 v[110:113], v[146:149], v[162:165], v[110:113]
	v_mfma_f32_16x16x32_bf16 v[40:43], v[154:157], v[162:165], v[40:43]
	v_mfma_f32_16x16x32_bf16 v[106:109], v[146:149], v[170:173], v[106:109]
	v_mfma_f32_16x16x32_bf16 v[36:39], v[154:157], v[170:173], v[36:39]
	v_mfma_f32_16x16x32_bf16 v[102:105], v[146:149], v[202:205], v[102:105]
	v_mfma_f32_16x16x32_bf16 v[48:51], v[154:157], v[202:205], v[48:51]
	v_mfma_f32_16x16x32_bf16 v[98:101], v[146:149], v[226:229], v[98:101]
	v_mfma_f32_16x16x32_bf16 v[32:35], v[154:157], v[226:229], v[32:35]
	v_mfma_f32_16x16x32_bf16 v[110:113], v[150:153], v[166:169], v[110:113]
	v_mfma_f32_16x16x32_bf16 v[40:43], v[158:161], v[166:169], v[40:43]
	v_mfma_f32_16x16x32_bf16 v[106:109], v[150:153], v[178:181], v[106:109]
	v_mfma_f32_16x16x32_bf16 v[36:39], v[158:161], v[178:181], v[36:39]
	v_mfma_f32_16x16x32_bf16 v[102:105], v[150:153], v[206:209], v[102:105]
	v_mfma_f32_16x16x32_bf16 v[48:51], v[158:161], v[206:209], v[48:51]
	v_mfma_f32_16x16x32_bf16 v[98:101], v[150:153], v[230:233], v[98:101]
	v_mfma_f32_16x16x32_bf16 v[32:35], v[158:161], v[230:233], v[32:35]
	s_setprio 0
	s_barrier
	s_add_i32 s62, s67, s5
	v_lshl_add_u64 v[188:189], vcc, 0, v[96:97]
	s_mov_b32 m0, s62
	ds_read_b128 v[162:165], v224 offset:16384
	ds_read_b128 v[166:169], v224 offset:17408
	ds_read_b128 v[170:173], v224 offset:18432
	ds_read_b128 v[178:181], v224 offset:19456
	ds_read_b128 v[202:205], v224 offset:20480
	ds_read_b128 v[206:209], v224 offset:21504
	ds_read_b128 v[226:229], v224 offset:22528
	ds_read_b128 v[230:233], v224 offset:23552
	global_load_lds_dwordx4 v[188:189], off
	s_add_i32 m0, s62, 0x2000
	s_add_u32 s62, vcc_lo, 0x80000
	v_lshl_add_u64 v[198:199], vcc, 0, v[182:183]
	s_addc_u32 s63, vcc_hi, 0
	s_add_i32 s67, s76, s5
	global_load_lds_dwordx4 v[198:199], off
	v_lshl_add_u64 v[200:201], s[62:63], 0, v[96:97]
	s_mov_b32 m0, s67
	v_lshl_add_u64 v[234:235], s[88:89], 0, v[176:177]
	global_load_lds_dwordx4 v[200:201], off
	v_lshl_add_u64 v[200:201], s[62:63], 0, v[182:183]
	s_add_i32 m0, s67, 0x2000
	s_nop 0
	global_load_lds_dwordx4 v[200:201], off
	v_lshl_add_u64 v[200:201], s[88:89], 0, v[174:175]
	s_mov_b32 m0, s17
	s_nop 0
	global_load_lds_dwordx4 v[200:201], off
	s_mov_b32 m0, s18
	s_nop 0
	global_load_lds_dwordx4 v[234:235], off
	s_waitcnt vmcnt(8)
	s_waitcnt lgkmcnt(0)
	v_mfma_f32_16x16x32_bf16 v[92:95], v[130:133], v[162:165], v[92:95]
	v_mfma_f32_16x16x32_bf16 v[24:27], v[138:141], v[162:165], v[24:27]
	s_barrier
	s_setprio 1
	s_waitcnt lgkmcnt(0)
	v_mfma_f32_16x16x32_bf16 v[88:91], v[130:133], v[170:173], v[88:91]
	v_mfma_f32_16x16x32_bf16 v[28:31], v[138:141], v[170:173], v[28:31]
	v_mfma_f32_16x16x32_bf16 v[84:87], v[130:133], v[202:205], v[84:87]
	v_mfma_f32_16x16x32_bf16 v[16:19], v[138:141], v[202:205], v[16:19]
	v_mfma_f32_16x16x32_bf16 v[80:83], v[130:133], v[226:229], v[80:83]
	v_mfma_f32_16x16x32_bf16 v[20:23], v[138:141], v[226:229], v[20:23]
	v_mfma_f32_16x16x32_bf16 v[92:95], v[134:137], v[166:169], v[92:95]
	v_mfma_f32_16x16x32_bf16 v[24:27], v[142:145], v[166:169], v[24:27]
	v_mfma_f32_16x16x32_bf16 v[88:91], v[134:137], v[178:181], v[88:91]
	v_mfma_f32_16x16x32_bf16 v[28:31], v[142:145], v[178:181], v[28:31]
	v_mfma_f32_16x16x32_bf16 v[84:87], v[134:137], v[206:209], v[84:87]
	v_mfma_f32_16x16x32_bf16 v[16:19], v[142:145], v[206:209], v[16:19]
	v_mfma_f32_16x16x32_bf16 v[80:83], v[134:137], v[230:233], v[80:83]
	v_mfma_f32_16x16x32_bf16 v[20:23], v[142:145], v[230:233], v[20:23]
	s_setprio 0
	s_setprio 1
	v_mfma_f32_16x16x32_bf16 v[76:79], v[146:149], v[162:165], v[76:79]
	v_mfma_f32_16x16x32_bf16 v[12:15], v[154:157], v[162:165], v[12:15]
	v_mfma_f32_16x16x32_bf16 v[72:75], v[146:149], v[170:173], v[72:75]
	v_mfma_f32_16x16x32_bf16 v[8:11], v[154:157], v[170:173], v[8:11]
	v_mfma_f32_16x16x32_bf16 v[68:71], v[146:149], v[202:205], v[68:71]
	v_mfma_f32_16x16x32_bf16 v[0:3], v[154:157], v[202:205], v[0:3]
	v_mfma_f32_16x16x32_bf16 v[64:67], v[146:149], v[226:229], v[64:67]
	v_mfma_f32_16x16x32_bf16 v[4:7], v[154:157], v[226:229], v[4:7]
	v_mfma_f32_16x16x32_bf16 v[76:79], v[150:153], v[166:169], v[76:79]
	v_mfma_f32_16x16x32_bf16 v[12:15], v[158:161], v[166:169], v[12:15]
	v_mfma_f32_16x16x32_bf16 v[72:75], v[150:153], v[178:181], v[72:75]
	v_mfma_f32_16x16x32_bf16 v[8:11], v[158:161], v[178:181], v[8:11]
	v_mfma_f32_16x16x32_bf16 v[68:71], v[150:153], v[206:209], v[68:71]
	v_mfma_f32_16x16x32_bf16 v[0:3], v[158:161], v[206:209], v[0:3]
	v_mfma_f32_16x16x32_bf16 v[64:67], v[150:153], v[230:233], v[64:67]
	v_mfma_f32_16x16x32_bf16 v[4:7], v[158:161], v[230:233], v[4:7]
	s_setprio 0
	s_barrier
	s_add_i32 s67, 0, 0x18000
	s_add_i32 s76, 0, 0x1c000
	v_add_u32_e32 v142, s67, v191
	v_add_u32_e32 v158, s76, v191
	ds_read_b128 v[130:133], v142
	ds_read_b128 v[134:137], v142 offset:1024
	ds_read_b128 v[138:141], v142 offset:2048
	ds_read_b128 v[142:145], v142 offset:3072
	ds_read_b128 v[146:149], v158
	ds_read_b128 v[150:153], v158 offset:1024
	ds_read_b128 v[154:157], v158 offset:2048
	ds_read_b128 v[158:161], v158 offset:3072
	s_add_u32 s62, s88, 0x80000
	s_addc_u32 s63, s89, 0
	s_mov_b32 m0, s19
	v_lshl_add_u64 v[236:237], s[62:63], 0, v[174:175]
	ds_read_b128 v[162:165], v224 offset:32768
	ds_read_b128 v[166:169], v224 offset:33792
	ds_read_b128 v[170:173], v224 offset:34816
	ds_read_b128 v[178:181], v224 offset:35840
	ds_read_b128 v[202:205], v224 offset:36864
	ds_read_b128 v[206:209], v224 offset:37888
	ds_read_b128 v[226:229], v224 offset:38912
	ds_read_b128 v[230:233], v224 offset:39936
	global_load_lds_dwordx4 v[236:237], off
	v_lshl_add_u64 v[236:237], s[62:63], 0, v[176:177]
	s_mov_b32 m0, s20
	s_nop 0
	global_load_lds_dwordx4 v[236:237], off
	s_waitcnt vmcnt(8)
	s_waitcnt lgkmcnt(0)
	v_mfma_f32_16x16x32_bf16 v[126:129], v[130:133], v[162:165], v[126:129]
	v_mfma_f32_16x16x32_bf16 v[56:59], v[138:141], v[162:165], v[56:59]
	s_barrier
	s_setprio 1
	s_waitcnt lgkmcnt(0)
	v_mfma_f32_16x16x32_bf16 v[122:125], v[130:133], v[170:173], v[122:125]
	v_mfma_f32_16x16x32_bf16 v[52:55], v[138:141], v[170:173], v[52:55]
	v_mfma_f32_16x16x32_bf16 v[118:121], v[130:133], v[202:205], v[118:121]
	v_mfma_f32_16x16x32_bf16 v[60:63], v[138:141], v[202:205], v[60:63]
	v_mfma_f32_16x16x32_bf16 v[114:117], v[130:133], v[226:229], v[114:117]
	v_mfma_f32_16x16x32_bf16 v[44:47], v[138:141], v[226:229], v[44:47]
	v_mfma_f32_16x16x32_bf16 v[126:129], v[134:137], v[166:169], v[126:129]
	v_mfma_f32_16x16x32_bf16 v[56:59], v[142:145], v[166:169], v[56:59]
	v_mfma_f32_16x16x32_bf16 v[122:125], v[134:137], v[178:181], v[122:125]
	v_mfma_f32_16x16x32_bf16 v[52:55], v[142:145], v[178:181], v[52:55]
	v_mfma_f32_16x16x32_bf16 v[118:121], v[134:137], v[206:209], v[118:121]
	v_mfma_f32_16x16x32_bf16 v[60:63], v[142:145], v[206:209], v[60:63]
	v_mfma_f32_16x16x32_bf16 v[114:117], v[134:137], v[230:233], v[114:117]
	v_mfma_f32_16x16x32_bf16 v[44:47], v[142:145], v[230:233], v[44:47]
	s_setprio 0
	s_setprio 1
	v_mfma_f32_16x16x32_bf16 v[110:113], v[146:149], v[162:165], v[110:113]
	v_mfma_f32_16x16x32_bf16 v[40:43], v[154:157], v[162:165], v[40:43]
	v_mfma_f32_16x16x32_bf16 v[106:109], v[146:149], v[170:173], v[106:109]
	v_mfma_f32_16x16x32_bf16 v[36:39], v[154:157], v[170:173], v[36:39]
	v_mfma_f32_16x16x32_bf16 v[102:105], v[146:149], v[202:205], v[102:105]
	v_mfma_f32_16x16x32_bf16 v[48:51], v[154:157], v[202:205], v[48:51]
	v_mfma_f32_16x16x32_bf16 v[98:101], v[146:149], v[226:229], v[98:101]
	v_mfma_f32_16x16x32_bf16 v[32:35], v[154:157], v[226:229], v[32:35]
	v_mfma_f32_16x16x32_bf16 v[110:113], v[150:153], v[166:169], v[110:113]
	v_mfma_f32_16x16x32_bf16 v[40:43], v[158:161], v[166:169], v[40:43]
	v_mfma_f32_16x16x32_bf16 v[106:109], v[150:153], v[178:181], v[106:109]
	v_mfma_f32_16x16x32_bf16 v[36:39], v[158:161], v[178:181], v[36:39]
	v_mfma_f32_16x16x32_bf16 v[102:105], v[150:153], v[206:209], v[102:105]
	v_mfma_f32_16x16x32_bf16 v[48:51], v[158:161], v[206:209], v[48:51]
	v_mfma_f32_16x16x32_bf16 v[98:101], v[150:153], v[230:233], v[98:101]
	v_mfma_f32_16x16x32_bf16 v[32:35], v[158:161], v[230:233], v[32:35]
	s_setprio 0
	s_barrier
	s_add_i32 s62, s67, s5
	v_lshl_add_u64 v[188:189], v[188:189], 0, s[30:31]
	s_mov_b32 m0, s62
	ds_read_b128 v[162:165], v224 offset:49152
	ds_read_b128 v[166:169], v224 offset:50176
	ds_read_b128 v[170:173], v224 offset:51200
	ds_read_b128 v[178:181], v224 offset:52224
	ds_read_b128 v[202:205], v224 offset:53248
	ds_read_b128 v[206:209], v224 offset:54272
	ds_read_b128 v[226:229], v224 offset:55296
	ds_read_b128 v[230:233], v224 offset:56320
	global_load_lds_dwordx4 v[188:189], off
	s_add_i32 m0, s62, 0x2000
	s_add_u32 s62, vcc_lo, 0x80080
	v_lshl_add_u64 v[188:189], v[198:199], 0, s[30:31]
	s_addc_u32 s63, vcc_hi, 0
	s_add_i32 s67, s76, s5
	global_load_lds_dwordx4 v[188:189], off
	v_lshl_add_u64 v[188:189], s[62:63], 0, v[96:97]
	s_mov_b32 m0, s67
	s_nop 0
	global_load_lds_dwordx4 v[188:189], off
	v_lshl_add_u64 v[188:189], s[62:63], 0, v[182:183]
	s_add_i32 m0, s67, 0x2000
	s_nop 0
	global_load_lds_dwordx4 v[188:189], off
	v_lshl_add_u64 v[188:189], v[200:201], 0, s[30:31]
	s_mov_b32 m0, s36
	s_nop 0
	global_load_lds_dwordx4 v[188:189], off
	v_lshl_add_u64 v[188:189], v[234:235], 0, s[30:31]
	s_mov_b32 m0, s37
	s_nop 0
	global_load_lds_dwordx4 v[188:189], off
	s_waitcnt vmcnt(8)
	s_waitcnt lgkmcnt(0)
	v_mfma_f32_16x16x32_bf16 v[92:95], v[130:133], v[162:165], v[92:95]
	v_mfma_f32_16x16x32_bf16 v[24:27], v[138:141], v[162:165], v[24:27]
	s_barrier
	s_setprio 1
	s_waitcnt lgkmcnt(0)
	v_mfma_f32_16x16x32_bf16 v[88:91], v[130:133], v[170:173], v[88:91]
	v_mfma_f32_16x16x32_bf16 v[28:31], v[138:141], v[170:173], v[28:31]
	v_mfma_f32_16x16x32_bf16 v[84:87], v[130:133], v[202:205], v[84:87]
	v_mfma_f32_16x16x32_bf16 v[16:19], v[138:141], v[202:205], v[16:19]
	v_mfma_f32_16x16x32_bf16 v[80:83], v[130:133], v[226:229], v[80:83]
	v_mfma_f32_16x16x32_bf16 v[20:23], v[138:141], v[226:229], v[20:23]
	v_mfma_f32_16x16x32_bf16 v[92:95], v[134:137], v[166:169], v[92:95]
	v_mfma_f32_16x16x32_bf16 v[24:27], v[142:145], v[166:169], v[24:27]
	v_mfma_f32_16x16x32_bf16 v[88:91], v[134:137], v[178:181], v[88:91]
	v_mfma_f32_16x16x32_bf16 v[28:31], v[142:145], v[178:181], v[28:31]
	v_mfma_f32_16x16x32_bf16 v[84:87], v[134:137], v[206:209], v[84:87]
	v_mfma_f32_16x16x32_bf16 v[16:19], v[142:145], v[206:209], v[16:19]
	v_mfma_f32_16x16x32_bf16 v[80:83], v[134:137], v[230:233], v[80:83]
	v_mfma_f32_16x16x32_bf16 v[20:23], v[142:145], v[230:233], v[20:23]
	s_setprio 0
	s_setprio 1
	v_mfma_f32_16x16x32_bf16 v[76:79], v[146:149], v[162:165], v[76:79]
	v_mfma_f32_16x16x32_bf16 v[12:15], v[154:157], v[162:165], v[12:15]
	v_mfma_f32_16x16x32_bf16 v[72:75], v[146:149], v[170:173], v[72:75]
	v_mfma_f32_16x16x32_bf16 v[8:11], v[154:157], v[170:173], v[8:11]
	v_mfma_f32_16x16x32_bf16 v[68:71], v[146:149], v[202:205], v[68:71]
	v_mfma_f32_16x16x32_bf16 v[0:3], v[154:157], v[202:205], v[0:3]
	v_mfma_f32_16x16x32_bf16 v[64:67], v[146:149], v[226:229], v[64:67]
	v_mfma_f32_16x16x32_bf16 v[4:7], v[154:157], v[226:229], v[4:7]
	v_mfma_f32_16x16x32_bf16 v[76:79], v[150:153], v[166:169], v[76:79]
	v_mfma_f32_16x16x32_bf16 v[12:15], v[158:161], v[166:169], v[12:15]
	v_mfma_f32_16x16x32_bf16 v[72:75], v[150:153], v[178:181], v[72:75]
	v_mfma_f32_16x16x32_bf16 v[8:11], v[158:161], v[178:181], v[8:11]
	v_mfma_f32_16x16x32_bf16 v[68:71], v[150:153], v[206:209], v[68:71]
	v_mfma_f32_16x16x32_bf16 v[0:3], v[158:161], v[206:209], v[0:3]
	v_mfma_f32_16x16x32_bf16 v[64:67], v[150:153], v[230:233], v[64:67]
	v_mfma_f32_16x16x32_bf16 v[4:7], v[158:161], v[230:233], v[4:7]
	s_setprio 0
	s_barrier
	s_add_i32 s6, s6, 2
	s_add_u32 s2, s2, 0x100
	s_addc_u32 s3, s3, 0
	s_cmp_gt_u32 s6, 29
	s_mov_b64 s[62:63], s[34:35]
	s_cbranch_scc0 .LBB0_1158
	s_and_b64 vcc, exec, s[24:25]
	s_cbranch_vccz .LBB0_1161
	s_barrier

.LBB0_1333:
	s_add_u32 s38, s42, 0x100
	s_addc_u32 s39, s43, 0
	s_add_i32 s13, 0, 0x10000
	s_cmp_eq_u32 s6, 4
	s_cselect_b32 s47, s25, s39
	s_cselect_b32 s46, s24, s38
	s_cselect_b32 s45, s35, s3
	s_cselect_b32 s44, s34, s2
	s_add_i32 s23, 0, 0x14000
	v_add_u32_e32 v152, s13, v136
	v_add_u32_e32 v168, s23, v136
	ds_read_b128 v[140:143], v152
	ds_read_b128 v[144:147], v152 offset:1024
	ds_read_b128 v[148:151], v152 offset:2048
	ds_read_b128 v[152:155], v152 offset:3072
	ds_read_b128 v[156:159], v168
	ds_read_b128 v[160:163], v168 offset:1024
	ds_read_b128 v[164:167], v168 offset:2048
	ds_read_b128 v[168:171], v168 offset:3072
	v_lshl_add_u64 v[198:199], s[42:43], 0, v[132:133]
	s_add_i32 m0, s5, 0xc000
	ds_read_b128 v[172:175], v139
	ds_read_b128 v[176:179], v139 offset:1024
	ds_read_b128 v[180:183], v139 offset:2048
	ds_read_b128 v[184:187], v139 offset:3072
	ds_read_b128 v[188:191], v139 offset:4096
	ds_read_b128 v[192:195], v139 offset:5120
	ds_read_b128 v[202:205], v139 offset:6144
	ds_read_b128 v[206:209], v139 offset:7168
	global_load_lds_dwordx4 v[198:199], off
	v_lshl_add_u64 v[198:199], s[42:43], 0, v[134:135]
	s_add_i32 m0, s5, 0xe000
	s_nop 0
	global_load_lds_dwordx4 v[198:199], off
	s_waitcnt vmcnt(8)
	s_waitcnt lgkmcnt(0)
	v_mfma_f32_16x16x32_bf16 v[126:129], v[140:143], v[172:175], v[126:129]
	v_mfma_f32_16x16x32_bf16 v[122:125], v[148:151], v[172:175], v[122:125]
	s_barrier
	s_setprio 1
	s_waitcnt lgkmcnt(0)
	v_mfma_f32_16x16x32_bf16 v[118:121], v[140:143], v[180:183], v[118:121]
	v_mfma_f32_16x16x32_bf16 v[114:117], v[148:151], v[180:183], v[114:117]
	v_mfma_f32_16x16x32_bf16 v[106:109], v[140:143], v[188:191], v[106:109]
	v_mfma_f32_16x16x32_bf16 v[98:101], v[148:151], v[188:191], v[98:101]
	v_mfma_f32_16x16x32_bf16 v[88:91], v[140:143], v[202:205], v[88:91]
	v_mfma_f32_16x16x32_bf16 v[80:83], v[148:151], v[202:205], v[80:83]
	v_mfma_f32_16x16x32_bf16 v[126:129], v[144:147], v[176:179], v[126:129]
	v_mfma_f32_16x16x32_bf16 v[122:125], v[152:155], v[176:179], v[122:125]
	v_mfma_f32_16x16x32_bf16 v[118:121], v[144:147], v[184:187], v[118:121]
	v_mfma_f32_16x16x32_bf16 v[114:117], v[152:155], v[184:187], v[114:117]
	v_mfma_f32_16x16x32_bf16 v[106:109], v[144:147], v[192:195], v[106:109]
	v_mfma_f32_16x16x32_bf16 v[98:101], v[152:155], v[192:195], v[98:101]
	v_mfma_f32_16x16x32_bf16 v[88:91], v[144:147], v[206:209], v[88:91]
	v_mfma_f32_16x16x32_bf16 v[80:83], v[152:155], v[206:209], v[80:83]
	s_setprio 0
	s_setprio 1
	v_mfma_f32_16x16x32_bf16 v[110:113], v[156:159], v[172:175], v[110:113]
	v_mfma_f32_16x16x32_bf16 v[102:105], v[164:167], v[172:175], v[102:105]
	v_mfma_f32_16x16x32_bf16 v[92:95], v[156:159], v[180:183], v[92:95]
	v_mfma_f32_16x16x32_bf16 v[84:87], v[164:167], v[180:183], v[84:87]
	v_mfma_f32_16x16x32_bf16 v[76:79], v[156:159], v[188:191], v[76:79]
	v_mfma_f32_16x16x32_bf16 v[72:75], v[164:167], v[188:191], v[72:75]
	v_mfma_f32_16x16x32_bf16 v[68:71], v[156:159], v[202:205], v[68:71]
	v_mfma_f32_16x16x32_bf16 v[64:67], v[164:167], v[202:205], v[64:67]
	v_mfma_f32_16x16x32_bf16 v[110:113], v[160:163], v[176:179], v[110:113]
	v_mfma_f32_16x16x32_bf16 v[102:105], v[168:171], v[176:179], v[102:105]
	v_mfma_f32_16x16x32_bf16 v[92:95], v[160:163], v[184:187], v[92:95]
	v_mfma_f32_16x16x32_bf16 v[84:87], v[168:171], v[184:187], v[84:87]
	v_mfma_f32_16x16x32_bf16 v[76:79], v[160:163], v[192:195], v[76:79]
	v_mfma_f32_16x16x32_bf16 v[72:75], v[168:171], v[192:195], v[72:75]
	v_mfma_f32_16x16x32_bf16 v[68:71], v[160:163], v[206:209], v[68:71]
	v_mfma_f32_16x16x32_bf16 v[64:67], v[168:171], v[206:209], v[64:67]
	s_setprio 0
	s_barrier
	s_add_i32 s13, s13, s4
	v_lshl_add_u64 v[198:199], s[44:45], 0, v[96:97]
	s_mov_b32 m0, s13
	ds_read_b128 v[172:175], v139 offset:16384
	ds_read_b128 v[176:179], v139 offset:17408
	ds_read_b128 v[180:183], v139 offset:18432
	ds_read_b128 v[184:187], v139 offset:19456
	ds_read_b128 v[188:191], v139 offset:20480
	ds_read_b128 v[192:195], v139 offset:21504
	ds_read_b128 v[202:205], v139 offset:22528
	ds_read_b128 v[206:209], v139 offset:23552
	global_load_lds_dwordx4 v[198:199], off
	s_add_i32 m0, s13, 0x2000
	s_add_u32 s42, s44, 0x160000
	v_lshl_add_u64 v[200:201], s[44:45], 0, v[130:131]
	s_addc_u32 s43, s45, 0
	s_add_i32 s13, s23, s4
	global_load_lds_dwordx4 v[200:201], off
	v_lshl_add_u64 v[214:215], s[42:43], 0, v[96:97]
	s_mov_b32 m0, s13
	v_lshl_add_u64 v[216:217], s[46:47], 0, v[130:131]
	global_load_lds_dwordx4 v[214:215], off
	v_lshl_add_u64 v[214:215], s[42:43], 0, v[130:131]
	s_add_i32 m0, s13, 0x2000
	s_nop 0
	global_load_lds_dwordx4 v[214:215], off
	v_lshl_add_u64 v[214:215], s[46:47], 0, v[96:97]
	s_mov_b32 m0, s5
	s_nop 0
	global_load_lds_dwordx4 v[214:215], off
	s_mov_b32 m0, s17
	s_nop 0
	global_load_lds_dwordx4 v[216:217], off
	s_waitcnt vmcnt(8)
	s_waitcnt lgkmcnt(0)
	v_mfma_f32_16x16x32_bf16 v[60:63], v[140:143], v[172:175], v[60:63]
	v_mfma_f32_16x16x32_bf16 v[56:59], v[148:151], v[172:175], v[56:59]
	s_barrier
	s_setprio 1
	s_waitcnt lgkmcnt(0)
	v_mfma_f32_16x16x32_bf16 v[52:55], v[140:143], v[180:183], v[52:55]
	v_mfma_f32_16x16x32_bf16 v[48:51], v[148:151], v[180:183], v[48:51]
	v_mfma_f32_16x16x32_bf16 v[36:39], v[140:143], v[188:191], v[36:39]
	v_mfma_f32_16x16x32_bf16 v[32:35], v[148:151], v[188:191], v[32:35]
	v_mfma_f32_16x16x32_bf16 v[20:23], v[140:143], v[202:205], v[20:23]
	v_mfma_f32_16x16x32_bf16 v[16:19], v[148:151], v[202:205], v[16:19]
	v_mfma_f32_16x16x32_bf16 v[60:63], v[144:147], v[176:179], v[60:63]
	v_mfma_f32_16x16x32_bf16 v[56:59], v[152:155], v[176:179], v[56:59]
	v_mfma_f32_16x16x32_bf16 v[52:55], v[144:147], v[184:187], v[52:55]
	v_mfma_f32_16x16x32_bf16 v[48:51], v[152:155], v[184:187], v[48:51]
	v_mfma_f32_16x16x32_bf16 v[36:39], v[144:147], v[192:195], v[36:39]
	v_mfma_f32_16x16x32_bf16 v[32:35], v[152:155], v[192:195], v[32:35]
	v_mfma_f32_16x16x32_bf16 v[20:23], v[144:147], v[206:209], v[20:23]
	v_mfma_f32_16x16x32_bf16 v[16:19], v[152:155], v[206:209], v[16:19]
	s_setprio 0
	s_setprio 1
	v_mfma_f32_16x16x32_bf16 v[44:47], v[156:159], v[172:175], v[44:47]
	v_mfma_f32_16x16x32_bf16 v[40:43], v[164:167], v[172:175], v[40:43]
	v_mfma_f32_16x16x32_bf16 v[28:31], v[156:159], v[180:183], v[28:31]
	v_mfma_f32_16x16x32_bf16 v[24:27], v[164:167], v[180:183], v[24:27]
	v_mfma_f32_16x16x32_bf16 v[12:15], v[156:159], v[188:191], v[12:15]
	v_mfma_f32_16x16x32_bf16 v[8:11], v[164:167], v[188:191], v[8:11]
	v_mfma_f32_16x16x32_bf16 v[4:7], v[156:159], v[202:205], v[4:7]
	v_mfma_f32_16x16x32_bf16 v[0:3], v[164:167], v[202:205], v[0:3]
	v_mfma_f32_16x16x32_bf16 v[44:47], v[160:163], v[176:179], v[44:47]
	v_mfma_f32_16x16x32_bf16 v[40:43], v[168:171], v[176:179], v[40:43]
	v_mfma_f32_16x16x32_bf16 v[28:31], v[160:163], v[184:187], v[28:31]
	v_mfma_f32_16x16x32_bf16 v[24:27], v[168:171], v[184:187], v[24:27]
	v_mfma_f32_16x16x32_bf16 v[12:15], v[160:163], v[192:195], v[12:15]
	v_mfma_f32_16x16x32_bf16 v[8:11], v[168:171], v[192:195], v[8:11]
	v_mfma_f32_16x16x32_bf16 v[4:7], v[160:163], v[206:209], v[4:7]
	v_mfma_f32_16x16x32_bf16 v[0:3], v[168:171], v[206:209], v[0:3]
	s_setprio 0
	s_barrier
	s_add_i32 s13, 0, 0x18000
	s_add_i32 s23, 0, 0x1c000
	v_add_u32_e32 v152, s13, v136
	v_add_u32_e32 v168, s23, v136
	ds_read_b128 v[140:143], v152
	ds_read_b128 v[144:147], v152 offset:1024
	ds_read_b128 v[148:151], v152 offset:2048
	ds_read_b128 v[152:155], v152 offset:3072
	ds_read_b128 v[156:159], v168
	ds_read_b128 v[160:163], v168 offset:1024
	ds_read_b128 v[164:167], v168 offset:2048
	ds_read_b128 v[168:171], v168 offset:3072
	s_add_u32 s42, s46, 0x160000
	s_addc_u32 s43, s47, 0
	s_mov_b32 m0, s18
	v_lshl_add_u64 v[218:219], s[42:43], 0, v[96:97]
	ds_read_b128 v[172:175], v139 offset:32768
	ds_read_b128 v[176:179], v139 offset:33792
	ds_read_b128 v[180:183], v139 offset:34816
	ds_read_b128 v[184:187], v139 offset:35840
	ds_read_b128 v[188:191], v139 offset:36864
	ds_read_b128 v[192:195], v139 offset:37888
	ds_read_b128 v[202:205], v139 offset:38912
	ds_read_b128 v[206:209], v139 offset:39936
	global_load_lds_dwordx4 v[218:219], off
	v_lshl_add_u64 v[218:219], s[42:43], 0, v[130:131]
	s_mov_b32 m0, s19
	s_nop 0
	global_load_lds_dwordx4 v[218:219], off
	s_waitcnt vmcnt(8)
	s_waitcnt lgkmcnt(0)
	v_mfma_f32_16x16x32_bf16 v[126:129], v[140:143], v[172:175], v[126:129]
	v_mfma_f32_16x16x32_bf16 v[122:125], v[148:151], v[172:175], v[122:125]
	s_barrier
	s_setprio 1
	s_waitcnt lgkmcnt(0)
	v_mfma_f32_16x16x32_bf16 v[118:121], v[140:143], v[180:183], v[118:121]
	v_mfma_f32_16x16x32_bf16 v[114:117], v[148:151], v[180:183], v[114:117]
	v_mfma_f32_16x16x32_bf16 v[106:109], v[140:143], v[188:191], v[106:109]
	v_mfma_f32_16x16x32_bf16 v[98:101], v[148:151], v[188:191], v[98:101]
	v_mfma_f32_16x16x32_bf16 v[88:91], v[140:143], v[202:205], v[88:91]
	v_mfma_f32_16x16x32_bf16 v[80:83], v[148:151], v[202:205], v[80:83]
	v_mfma_f32_16x16x32_bf16 v[126:129], v[144:147], v[176:179], v[126:129]
	v_mfma_f32_16x16x32_bf16 v[122:125], v[152:155], v[176:179], v[122:125]
	v_mfma_f32_16x16x32_bf16 v[118:121], v[144:147], v[184:187], v[118:121]
	v_mfma_f32_16x16x32_bf16 v[114:117], v[152:155], v[184:187], v[114:117]
	v_mfma_f32_16x16x32_bf16 v[106:109], v[144:147], v[192:195], v[106:109]
	v_mfma_f32_16x16x32_bf16 v[98:101], v[152:155], v[192:195], v[98:101]
	v_mfma_f32_16x16x32_bf16 v[88:91], v[144:147], v[206:209], v[88:91]
	v_mfma_f32_16x16x32_bf16 v[80:83], v[152:155], v[206:209], v[80:83]
	s_setprio 0
	s_setprio 1
	v_mfma_f32_16x16x32_bf16 v[110:113], v[156:159], v[172:175], v[110:113]
	v_mfma_f32_16x16x32_bf16 v[102:105], v[164:167], v[172:175], v[102:105]
	v_mfma_f32_16x16x32_bf16 v[92:95], v[156:159], v[180:183], v[92:95]
	v_mfma_f32_16x16x32_bf16 v[84:87], v[164:167], v[180:183], v[84:87]
	v_mfma_f32_16x16x32_bf16 v[76:79], v[156:159], v[188:191], v[76:79]
	v_mfma_f32_16x16x32_bf16 v[72:75], v[164:167], v[188:191], v[72:75]
	v_mfma_f32_16x16x32_bf16 v[68:71], v[156:159], v[202:205], v[68:71]
	v_mfma_f32_16x16x32_bf16 v[64:67], v[164:167], v[202:205], v[64:67]
	v_mfma_f32_16x16x32_bf16 v[110:113], v[160:163], v[176:179], v[110:113]
	v_mfma_f32_16x16x32_bf16 v[102:105], v[168:171], v[176:179], v[102:105]
	v_mfma_f32_16x16x32_bf16 v[92:95], v[160:163], v[184:187], v[92:95]
	v_mfma_f32_16x16x32_bf16 v[84:87], v[168:171], v[184:187], v[84:87]
	v_mfma_f32_16x16x32_bf16 v[76:79], v[160:163], v[192:195], v[76:79]
	v_mfma_f32_16x16x32_bf16 v[72:75], v[168:171], v[192:195], v[72:75]
	v_mfma_f32_16x16x32_bf16 v[68:71], v[160:163], v[206:209], v[68:71]
	v_mfma_f32_16x16x32_bf16 v[64:67], v[168:171], v[206:209], v[64:67]
	s_setprio 0
	s_barrier
	s_add_i32 s13, s13, s4
	v_lshl_add_u64 v[198:199], v[198:199], 0, s[30:31]
	s_mov_b32 m0, s13
	ds_read_b128 v[172:175], v139 offset:49152
	ds_read_b128 v[176:179], v139 offset:50176
	ds_read_b128 v[180:183], v139 offset:51200
	ds_read_b128 v[184:187], v139 offset:52224
	ds_read_b128 v[188:191], v139 offset:53248
	ds_read_b128 v[192:195], v139 offset:54272
	ds_read_b128 v[202:205], v139 offset:55296
	ds_read_b128 v[206:209], v139 offset:56320
	global_load_lds_dwordx4 v[198:199], off
	s_add_i32 m0, s13, 0x2000
	s_add_u32 s42, s44, 0x160080
	v_lshl_add_u64 v[198:199], v[200:201], 0, s[30:31]
	s_addc_u32 s43, s45, 0
	s_add_i32 s13, s23, s4
	global_load_lds_dwordx4 v[198:199], off
	v_lshl_add_u64 v[198:199], s[42:43], 0, v[96:97]
	s_mov_b32 m0, s13
	s_nop 0
	global_load_lds_dwordx4 v[198:199], off
	v_lshl_add_u64 v[198:199], s[42:43], 0, v[130:131]
	s_add_i32 m0, s13, 0x2000
	s_nop 0
	global_load_lds_dwordx4 v[198:199], off
	v_lshl_add_u64 v[198:199], v[214:215], 0, s[30:31]
	s_mov_b32 m0, s37
	s_nop 0
	global_load_lds_dwordx4 v[198:199], off
	v_lshl_add_u64 v[198:199], v[216:217], 0, s[30:31]
	s_mov_b32 m0, s40
	s_nop 0
	global_load_lds_dwordx4 v[198:199], off
	s_waitcnt vmcnt(8)
	s_waitcnt lgkmcnt(0)
	v_mfma_f32_16x16x32_bf16 v[60:63], v[140:143], v[172:175], v[60:63]
	v_mfma_f32_16x16x32_bf16 v[56:59], v[148:151], v[172:175], v[56:59]
	s_barrier
	s_setprio 1
	s_waitcnt lgkmcnt(0)
	v_mfma_f32_16x16x32_bf16 v[52:55], v[140:143], v[180:183], v[52:55]
	v_mfma_f32_16x16x32_bf16 v[48:51], v[148:151], v[180:183], v[48:51]
	v_mfma_f32_16x16x32_bf16 v[36:39], v[140:143], v[188:191], v[36:39]
	v_mfma_f32_16x16x32_bf16 v[32:35], v[148:151], v[188:191], v[32:35]
	v_mfma_f32_16x16x32_bf16 v[20:23], v[140:143], v[202:205], v[20:23]
	v_mfma_f32_16x16x32_bf16 v[16:19], v[148:151], v[202:205], v[16:19]
	v_mfma_f32_16x16x32_bf16 v[60:63], v[144:147], v[176:179], v[60:63]
	v_mfma_f32_16x16x32_bf16 v[56:59], v[152:155], v[176:179], v[56:59]
	v_mfma_f32_16x16x32_bf16 v[52:55], v[144:147], v[184:187], v[52:55]
	v_mfma_f32_16x16x32_bf16 v[48:51], v[152:155], v[184:187], v[48:51]
	v_mfma_f32_16x16x32_bf16 v[36:39], v[144:147], v[192:195], v[36:39]
	v_mfma_f32_16x16x32_bf16 v[32:35], v[152:155], v[192:195], v[32:35]
	v_mfma_f32_16x16x32_bf16 v[20:23], v[144:147], v[206:209], v[20:23]
	v_mfma_f32_16x16x32_bf16 v[16:19], v[152:155], v[206:209], v[16:19]
	s_setprio 0
	s_setprio 1
	v_mfma_f32_16x16x32_bf16 v[44:47], v[156:159], v[172:175], v[44:47]
	v_mfma_f32_16x16x32_bf16 v[40:43], v[164:167], v[172:175], v[40:43]
	v_mfma_f32_16x16x32_bf16 v[28:31], v[156:159], v[180:183], v[28:31]
	v_mfma_f32_16x16x32_bf16 v[24:27], v[164:167], v[180:183], v[24:27]
	v_mfma_f32_16x16x32_bf16 v[12:15], v[156:159], v[188:191], v[12:15]
	v_mfma_f32_16x16x32_bf16 v[8:11], v[164:167], v[188:191], v[8:11]
	v_mfma_f32_16x16x32_bf16 v[4:7], v[156:159], v[202:205], v[4:7]
	v_mfma_f32_16x16x32_bf16 v[0:3], v[164:167], v[202:205], v[0:3]
	v_mfma_f32_16x16x32_bf16 v[44:47], v[160:163], v[176:179], v[44:47]
	v_mfma_f32_16x16x32_bf16 v[40:43], v[168:171], v[176:179], v[40:43]
	v_mfma_f32_16x16x32_bf16 v[28:31], v[160:163], v[184:187], v[28:31]
	v_mfma_f32_16x16x32_bf16 v[24:27], v[168:171], v[184:187], v[24:27]
	v_mfma_f32_16x16x32_bf16 v[12:15], v[160:163], v[192:195], v[12:15]
	v_mfma_f32_16x16x32_bf16 v[8:11], v[168:171], v[192:195], v[8:11]
	v_mfma_f32_16x16x32_bf16 v[4:7], v[160:163], v[206:209], v[4:7]
	v_mfma_f32_16x16x32_bf16 v[0:3], v[168:171], v[206:209], v[0:3]
	s_setprio 0
	s_barrier
	s_add_i32 s6, s6, 2
	s_add_u32 s2, s2, 0x100
	s_addc_u32 s3, s3, 0
	s_cmp_gt_u32 s6, 5
	s_mov_b64 s[42:43], s[38:39]
	s_cbranch_scc0 .LBB0_1333
	s_and_b64 vcc, exec, s[14:15]
	s_cbranch_vccz .LBB0_1336
	s_barrier

.LBB0_1357:
	s_add_u32 s3, s14, s34
	s_addc_u32 s6, s15, s35
	s_add_u32 s3, s3, 0x100
	s_addc_u32 s6, s6, 0
	s_add_u32 s42, s57, s34
	s_addc_u32 s43, s58, s35
	s_add_i32 s59, 0, 0x10000
	s_cmpk_eq_i32 s34, 0x2b00
	s_cselect_b32 s45, s23, s6
	s_cselect_b32 s44, s22, s3
	v_add_u32_e32 v146, s59, v144
	s_cselect_b32 s43, s25, s43
	s_cselect_b32 s42, s24, s42
	s_add_i32 s3, 0, 0x14000
	ds_read_b128 v[154:157], v146
	ds_read_b128 v[158:161], v146 offset:1024
	ds_read_b128 v[162:165], v146 offset:2048
	ds_read_b128 v[166:169], v146 offset:3072
	v_add_u32_e32 v146, s3, v144
	ds_read_b128 v[174:177], v146
	ds_read_b128 v[178:181], v146 offset:1024
	ds_read_b128 v[182:185], v146 offset:2048
	ds_read_b128 v[186:189], v146 offset:3072
	v_lshl_add_u64 v[146:147], v[140:141], 0, s[34:35]
	s_add_i32 m0, s17, 0xc000
	ds_read_b128 v[190:193], v145
	ds_read_b128 v[202:205], v145 offset:1024
	ds_read_b128 v[206:209], v145 offset:2048
	ds_read_b128 v[214:217], v145 offset:3072
	ds_read_b128 v[218:221], v145 offset:4096
	ds_read_b128 v[222:225], v145 offset:5120
	ds_read_b128 v[226:229], v145 offset:6144
	ds_read_b128 v[230:233], v145 offset:7168
	global_load_lds_dwordx4 v[146:147], off
	v_lshl_add_u64 v[146:147], v[142:143], 0, s[34:35]
	s_add_i32 m0, s17, 0xe000
	s_nop 0
	global_load_lds_dwordx4 v[146:147], off
	s_waitcnt vmcnt(8)
	s_waitcnt lgkmcnt(0)
	v_mfma_f32_16x16x32_bf16 v[110:113], v[154:157], v[190:193], v[110:113]
	v_mfma_f32_16x16x32_bf16 v[106:109], v[162:165], v[190:193], v[106:109]
	s_barrier
	s_setprio 1
	s_waitcnt lgkmcnt(0)
	v_mfma_f32_16x16x32_bf16 v[118:121], v[154:157], v[206:209], v[118:121]
	v_mfma_f32_16x16x32_bf16 v[114:117], v[162:165], v[206:209], v[114:117]
	v_mfma_f32_16x16x32_bf16 v[126:129], v[154:157], v[218:221], v[126:129]
	v_mfma_f32_16x16x32_bf16 v[122:125], v[162:165], v[218:221], v[122:125]
	v_mfma_f32_16x16x32_bf16 v[92:95], v[154:157], v[226:229], v[92:95]
	v_mfma_f32_16x16x32_bf16 v[88:91], v[162:165], v[226:229], v[88:91]
	v_mfma_f32_16x16x32_bf16 v[110:113], v[158:161], v[202:205], v[110:113]
	v_mfma_f32_16x16x32_bf16 v[106:109], v[166:169], v[202:205], v[106:109]
	v_mfma_f32_16x16x32_bf16 v[118:121], v[158:161], v[214:217], v[118:121]
	v_mfma_f32_16x16x32_bf16 v[114:117], v[166:169], v[214:217], v[114:117]
	v_mfma_f32_16x16x32_bf16 v[126:129], v[158:161], v[222:225], v[126:129]
	v_mfma_f32_16x16x32_bf16 v[122:125], v[166:169], v[222:225], v[122:125]
	v_mfma_f32_16x16x32_bf16 v[92:95], v[158:161], v[230:233], v[92:95]
	v_mfma_f32_16x16x32_bf16 v[88:91], v[166:169], v[230:233], v[88:91]
	s_setprio 0
	s_setprio 1
	v_mfma_f32_16x16x32_bf16 v[4:7], v[174:177], v[190:193], v[4:7]
	v_mfma_f32_16x16x32_bf16 v[0:3], v[182:185], v[190:193], v[0:3]
	v_mfma_f32_16x16x32_bf16 v[12:15], v[174:177], v[206:209], v[12:15]
	v_mfma_f32_16x16x32_bf16 v[8:11], v[182:185], v[206:209], v[8:11]
	v_mfma_f32_16x16x32_bf16 v[24:27], v[174:177], v[218:221], v[24:27]
	v_mfma_f32_16x16x32_bf16 v[20:23], v[182:185], v[218:221], v[20:23]
	v_mfma_f32_16x16x32_bf16 v[40:43], v[174:177], v[226:229], v[40:43]
	v_mfma_f32_16x16x32_bf16 v[36:39], v[182:185], v[226:229], v[36:39]
	v_mfma_f32_16x16x32_bf16 v[4:7], v[178:181], v[202:205], v[4:7]
	v_mfma_f32_16x16x32_bf16 v[0:3], v[186:189], v[202:205], v[0:3]
	v_mfma_f32_16x16x32_bf16 v[12:15], v[178:181], v[214:217], v[12:15]
	v_mfma_f32_16x16x32_bf16 v[8:11], v[186:189], v[214:217], v[8:11]
	v_mfma_f32_16x16x32_bf16 v[24:27], v[178:181], v[222:225], v[24:27]
	v_mfma_f32_16x16x32_bf16 v[20:23], v[186:189], v[222:225], v[20:23]
	v_mfma_f32_16x16x32_bf16 v[40:43], v[178:181], v[230:233], v[40:43]
	v_mfma_f32_16x16x32_bf16 v[36:39], v[186:189], v[230:233], v[36:39]
	s_setprio 0
	s_barrier
	s_add_i32 s6, s59, s5
	v_lshl_add_u64 v[146:147], s[42:43], 0, v[96:97]
	s_mov_b32 m0, s6
	ds_read_b128 v[190:193], v145 offset:16384
	ds_read_b128 v[202:205], v145 offset:17408
	ds_read_b128 v[206:209], v145 offset:18432
	ds_read_b128 v[214:217], v145 offset:19456
	ds_read_b128 v[218:221], v145 offset:20480
	ds_read_b128 v[222:225], v145 offset:21504
	ds_read_b128 v[226:229], v145 offset:22528
	ds_read_b128 v[230:233], v145 offset:23552
	global_load_lds_dwordx4 v[146:147], off
	s_add_i32 m0, s6, 0x2000
	s_add_u32 s60, s42, 0x160000
	v_lshl_add_u64 v[150:151], s[42:43], 0, v[130:131]
	s_addc_u32 s61, s43, 0
	s_add_i32 s3, s3, s5
	global_load_lds_dwordx4 v[150:151], off
	v_lshl_add_u64 v[170:171], s[60:61], 0, v[96:97]
	s_mov_b32 m0, s3
	v_lshl_add_u64 v[194:195], s[44:45], 0, v[132:133]
	global_load_lds_dwordx4 v[170:171], off
	v_lshl_add_u64 v[170:171], s[60:61], 0, v[130:131]
	s_add_i32 m0, s3, 0x2000
	s_nop 0
	global_load_lds_dwordx4 v[170:171], off
	v_lshl_add_u64 v[170:171], s[44:45], 0, v[134:135]
	s_mov_b32 m0, s17
	s_nop 0
	global_load_lds_dwordx4 v[170:171], off
	s_mov_b32 m0, s18
	s_nop 0
	global_load_lds_dwordx4 v[194:195], off
	s_waitcnt vmcnt(8)
	s_waitcnt lgkmcnt(0)
	v_mfma_f32_16x16x32_bf16 v[102:105], v[154:157], v[190:193], v[102:105]
	v_mfma_f32_16x16x32_bf16 v[98:101], v[162:165], v[190:193], v[98:101]
	s_barrier
	s_setprio 1
	s_waitcnt lgkmcnt(0)
	v_mfma_f32_16x16x32_bf16 v[84:87], v[154:157], v[206:209], v[84:87]
	v_mfma_f32_16x16x32_bf16 v[80:83], v[162:165], v[206:209], v[80:83]
	v_mfma_f32_16x16x32_bf16 v[68:71], v[154:157], v[218:221], v[68:71]
	v_mfma_f32_16x16x32_bf16 v[64:67], v[162:165], v[218:221], v[64:67]
	v_mfma_f32_16x16x32_bf16 v[44:47], v[154:157], v[226:229], v[44:47]
	v_mfma_f32_16x16x32_bf16 v[32:35], v[162:165], v[226:229], v[32:35]
	v_mfma_f32_16x16x32_bf16 v[102:105], v[158:161], v[202:205], v[102:105]
	v_mfma_f32_16x16x32_bf16 v[98:101], v[166:169], v[202:205], v[98:101]
	v_mfma_f32_16x16x32_bf16 v[84:87], v[158:161], v[214:217], v[84:87]
	v_mfma_f32_16x16x32_bf16 v[80:83], v[166:169], v[214:217], v[80:83]
	v_mfma_f32_16x16x32_bf16 v[68:71], v[158:161], v[222:225], v[68:71]
	v_mfma_f32_16x16x32_bf16 v[64:67], v[166:169], v[222:225], v[64:67]
	v_mfma_f32_16x16x32_bf16 v[44:47], v[158:161], v[230:233], v[44:47]
	v_mfma_f32_16x16x32_bf16 v[32:35], v[166:169], v[230:233], v[32:35]
	s_setprio 0
	s_setprio 1
	v_mfma_f32_16x16x32_bf16 v[60:63], v[174:177], v[190:193], v[60:63]
	v_mfma_f32_16x16x32_bf16 v[56:59], v[182:185], v[190:193], v[56:59]
	v_mfma_f32_16x16x32_bf16 v[76:79], v[174:177], v[206:209], v[76:79]
	v_mfma_f32_16x16x32_bf16 v[72:75], v[182:185], v[206:209], v[72:75]
	v_mfma_f32_16x16x32_bf16 v[52:55], v[174:177], v[218:221], v[52:55]
	v_mfma_f32_16x16x32_bf16 v[48:51], v[182:185], v[218:221], v[48:51]
	v_mfma_f32_16x16x32_bf16 v[28:31], v[174:177], v[226:229], v[28:31]
	v_mfma_f32_16x16x32_bf16 v[16:19], v[182:185], v[226:229], v[16:19]
	v_mfma_f32_16x16x32_bf16 v[60:63], v[178:181], v[202:205], v[60:63]
	v_mfma_f32_16x16x32_bf16 v[56:59], v[186:189], v[202:205], v[56:59]
	v_mfma_f32_16x16x32_bf16 v[76:79], v[178:181], v[214:217], v[76:79]
	v_mfma_f32_16x16x32_bf16 v[72:75], v[186:189], v[214:217], v[72:75]
	v_mfma_f32_16x16x32_bf16 v[52:55], v[178:181], v[222:225], v[52:55]
	v_mfma_f32_16x16x32_bf16 v[48:51], v[186:189], v[222:225], v[48:51]
	v_mfma_f32_16x16x32_bf16 v[28:31], v[178:181], v[230:233], v[28:31]
	v_mfma_f32_16x16x32_bf16 v[16:19], v[186:189], v[230:233], v[16:19]
	s_setprio 0
	s_barrier
	s_add_i32 s3, 0, 0x18000
	v_add_u32_e32 v149, s3, v144
	s_add_i32 s6, 0, 0x1c000
	ds_read_b128 v[154:157], v149
	ds_read_b128 v[158:161], v149 offset:1024
	ds_read_b128 v[162:165], v149 offset:2048
	ds_read_b128 v[166:169], v149 offset:3072
	v_add_u32_e32 v149, s6, v144
	ds_read_b128 v[174:177], v149
	ds_read_b128 v[178:181], v149 offset:1024
	ds_read_b128 v[182:185], v149 offset:2048
	ds_read_b128 v[186:189], v149 offset:3072
	s_add_u32 s44, s44, 0x160000
	s_addc_u32 s45, s45, 0
	s_mov_b32 m0, s19
	v_lshl_add_u64 v[198:199], s[44:45], 0, v[134:135]
	ds_read_b128 v[190:193], v145 offset:32768
	ds_read_b128 v[202:205], v145 offset:33792
	ds_read_b128 v[206:209], v145 offset:34816
	ds_read_b128 v[214:217], v145 offset:35840
	ds_read_b128 v[218:221], v145 offset:36864
	ds_read_b128 v[222:225], v145 offset:37888
	ds_read_b128 v[226:229], v145 offset:38912
	ds_read_b128 v[230:233], v145 offset:39936
	global_load_lds_dwordx4 v[198:199], off
	v_lshl_add_u64 v[198:199], s[44:45], 0, v[132:133]
	s_mov_b32 m0, s20
	s_nop 0
	global_load_lds_dwordx4 v[198:199], off
	s_waitcnt vmcnt(8)
	s_waitcnt lgkmcnt(0)
	v_mfma_f32_16x16x32_bf16 v[110:113], v[154:157], v[190:193], v[110:113]
	v_mfma_f32_16x16x32_bf16 v[106:109], v[162:165], v[190:193], v[106:109]
	s_barrier
	s_setprio 1
	s_waitcnt lgkmcnt(0)
	v_mfma_f32_16x16x32_bf16 v[118:121], v[154:157], v[206:209], v[118:121]
	v_mfma_f32_16x16x32_bf16 v[114:117], v[162:165], v[206:209], v[114:117]
	v_mfma_f32_16x16x32_bf16 v[126:129], v[154:157], v[218:221], v[126:129]
	v_mfma_f32_16x16x32_bf16 v[122:125], v[162:165], v[218:221], v[122:125]
	v_mfma_f32_16x16x32_bf16 v[92:95], v[154:157], v[226:229], v[92:95]
	v_mfma_f32_16x16x32_bf16 v[88:91], v[162:165], v[226:229], v[88:91]
	v_mfma_f32_16x16x32_bf16 v[110:113], v[158:161], v[202:205], v[110:113]
	v_mfma_f32_16x16x32_bf16 v[106:109], v[166:169], v[202:205], v[106:109]
	v_mfma_f32_16x16x32_bf16 v[118:121], v[158:161], v[214:217], v[118:121]
	v_mfma_f32_16x16x32_bf16 v[114:117], v[166:169], v[214:217], v[114:117]
	v_mfma_f32_16x16x32_bf16 v[126:129], v[158:161], v[222:225], v[126:129]
	v_mfma_f32_16x16x32_bf16 v[122:125], v[166:169], v[222:225], v[122:125]
	v_mfma_f32_16x16x32_bf16 v[92:95], v[158:161], v[230:233], v[92:95]
	v_mfma_f32_16x16x32_bf16 v[88:91], v[166:169], v[230:233], v[88:91]
	s_setprio 0
	s_setprio 1
	v_mfma_f32_16x16x32_bf16 v[4:7], v[174:177], v[190:193], v[4:7]
	v_mfma_f32_16x16x32_bf16 v[0:3], v[182:185], v[190:193], v[0:3]
	v_mfma_f32_16x16x32_bf16 v[12:15], v[174:177], v[206:209], v[12:15]
	v_mfma_f32_16x16x32_bf16 v[8:11], v[182:185], v[206:209], v[8:11]
	v_mfma_f32_16x16x32_bf16 v[24:27], v[174:177], v[218:221], v[24:27]
	v_mfma_f32_16x16x32_bf16 v[20:23], v[182:185], v[218:221], v[20:23]
	v_mfma_f32_16x16x32_bf16 v[40:43], v[174:177], v[226:229], v[40:43]
	v_mfma_f32_16x16x32_bf16 v[36:39], v[182:185], v[226:229], v[36:39]
	v_mfma_f32_16x16x32_bf16 v[4:7], v[178:181], v[202:205], v[4:7]
	v_mfma_f32_16x16x32_bf16 v[0:3], v[186:189], v[202:205], v[0:3]
	v_mfma_f32_16x16x32_bf16 v[12:15], v[178:181], v[214:217], v[12:15]
	v_mfma_f32_16x16x32_bf16 v[8:11], v[186:189], v[214:217], v[8:11]
	v_mfma_f32_16x16x32_bf16 v[24:27], v[178:181], v[222:225], v[24:27]
	v_mfma_f32_16x16x32_bf16 v[20:23], v[186:189], v[222:225], v[20:23]
	v_mfma_f32_16x16x32_bf16 v[40:43], v[178:181], v[230:233], v[40:43]
	v_mfma_f32_16x16x32_bf16 v[36:39], v[186:189], v[230:233], v[36:39]
	s_setprio 0
	s_barrier
	s_add_i32 s3, s3, s5
	v_lshl_add_u64 v[146:147], v[146:147], 0, s[30:31]
	s_mov_b32 m0, s3
	ds_read_b128 v[190:193], v145 offset:49152
	ds_read_b128 v[202:205], v145 offset:50176
	ds_read_b128 v[206:209], v145 offset:51200
	ds_read_b128 v[214:217], v145 offset:52224
	ds_read_b128 v[218:221], v145 offset:53248
	ds_read_b128 v[222:225], v145 offset:54272
	ds_read_b128 v[226:229], v145 offset:55296
	ds_read_b128 v[230:233], v145 offset:56320
	global_load_lds_dwordx4 v[146:147], off
	s_add_i32 m0, s3, 0x2000
	s_add_u32 s42, s42, 0x160080
	v_lshl_add_u64 v[146:147], v[150:151], 0, s[30:31]
	s_addc_u32 s43, s43, 0
	s_add_i32 s3, s6, s5
	global_load_lds_dwordx4 v[146:147], off
	v_lshl_add_u64 v[146:147], s[42:43], 0, v[96:97]
	s_mov_b32 m0, s3
	s_nop 0
	global_load_lds_dwordx4 v[146:147], off
	v_lshl_add_u64 v[146:147], s[42:43], 0, v[130:131]
	s_add_i32 m0, s3, 0x2000
	s_nop 0
	global_load_lds_dwordx4 v[146:147], off
	v_lshl_add_u64 v[146:147], v[170:171], 0, s[30:31]
	s_mov_b32 m0, s37
	s_nop 0
	global_load_lds_dwordx4 v[146:147], off
	v_lshl_add_u64 v[146:147], v[194:195], 0, s[30:31]
	s_mov_b32 m0, s52
	s_nop 0
	global_load_lds_dwordx4 v[146:147], off
	s_waitcnt vmcnt(8)
	s_waitcnt lgkmcnt(0)
	v_mfma_f32_16x16x32_bf16 v[102:105], v[154:157], v[190:193], v[102:105]
	v_mfma_f32_16x16x32_bf16 v[98:101], v[162:165], v[190:193], v[98:101]
	s_barrier
	s_setprio 1
	s_waitcnt lgkmcnt(0)
	v_mfma_f32_16x16x32_bf16 v[84:87], v[154:157], v[206:209], v[84:87]
	v_mfma_f32_16x16x32_bf16 v[80:83], v[162:165], v[206:209], v[80:83]
	v_mfma_f32_16x16x32_bf16 v[68:71], v[154:157], v[218:221], v[68:71]
	v_mfma_f32_16x16x32_bf16 v[64:67], v[162:165], v[218:221], v[64:67]
	v_mfma_f32_16x16x32_bf16 v[44:47], v[154:157], v[226:229], v[44:47]
	v_mfma_f32_16x16x32_bf16 v[32:35], v[162:165], v[226:229], v[32:35]
	v_mfma_f32_16x16x32_bf16 v[102:105], v[158:161], v[202:205], v[102:105]
	v_mfma_f32_16x16x32_bf16 v[98:101], v[166:169], v[202:205], v[98:101]
	v_mfma_f32_16x16x32_bf16 v[84:87], v[158:161], v[214:217], v[84:87]
	v_mfma_f32_16x16x32_bf16 v[80:83], v[166:169], v[214:217], v[80:83]
	v_mfma_f32_16x16x32_bf16 v[68:71], v[158:161], v[222:225], v[68:71]
	v_mfma_f32_16x16x32_bf16 v[64:67], v[166:169], v[222:225], v[64:67]
	v_mfma_f32_16x16x32_bf16 v[44:47], v[158:161], v[230:233], v[44:47]
	v_mfma_f32_16x16x32_bf16 v[32:35], v[166:169], v[230:233], v[32:35]
	s_setprio 0
	s_setprio 1
	v_mfma_f32_16x16x32_bf16 v[60:63], v[174:177], v[190:193], v[60:63]
	v_mfma_f32_16x16x32_bf16 v[56:59], v[182:185], v[190:193], v[56:59]
	v_mfma_f32_16x16x32_bf16 v[76:79], v[174:177], v[206:209], v[76:79]
	v_mfma_f32_16x16x32_bf16 v[72:75], v[182:185], v[206:209], v[72:75]
	v_mfma_f32_16x16x32_bf16 v[52:55], v[174:177], v[218:221], v[52:55]
	v_mfma_f32_16x16x32_bf16 v[48:51], v[182:185], v[218:221], v[48:51]
	v_mfma_f32_16x16x32_bf16 v[28:31], v[174:177], v[226:229], v[28:31]
	v_mfma_f32_16x16x32_bf16 v[16:19], v[182:185], v[226:229], v[16:19]
	v_mfma_f32_16x16x32_bf16 v[60:63], v[178:181], v[202:205], v[60:63]
	v_mfma_f32_16x16x32_bf16 v[56:59], v[186:189], v[202:205], v[56:59]
	v_mfma_f32_16x16x32_bf16 v[76:79], v[178:181], v[214:217], v[76:79]
	v_mfma_f32_16x16x32_bf16 v[72:75], v[186:189], v[214:217], v[72:75]
	v_mfma_f32_16x16x32_bf16 v[52:55], v[178:181], v[222:225], v[52:55]
	v_mfma_f32_16x16x32_bf16 v[48:51], v[186:189], v[222:225], v[48:51]
	v_mfma_f32_16x16x32_bf16 v[28:31], v[178:181], v[230:233], v[28:31]
	v_mfma_f32_16x16x32_bf16 v[16:19], v[186:189], v[230:233], v[16:19]
	s_setprio 0
	s_barrier
	s_add_i32 s2, s2, 2
	s_add_u32 s34, s34, 0x100
	s_addc_u32 s35, s35, 0
	s_cmpk_gt_u32 s2, 0x55
	s_cbranch_scc0 .LBB0_1357
	s_and_b64 vcc, exec, s[12:13]
	s_cbranch_vccz .LBB0_1360
	s_barrier

.LBB0_1413:
	s_add_u32 s24, s22, 0x100
	s_addc_u32 s25, s23, 0
	s_add_i32 s45, 0, 0x10000
	s_cmpk_eq_i32 s6, 0x54
	s_cselect_b32 s39, s13, s25
	s_cselect_b32 s38, s12, s24
	s_cselect_b32 s35, s15, s3
	s_cselect_b32 s34, s14, s2
	s_add_i32 s46, 0, 0x14000
	v_add_u32_e32 v142, s45, v155
	v_add_u32_e32 v152, s46, v155
	ds_read_b128 v[130:133], v142
	ds_read_b128 v[134:137], v142 offset:1024
	ds_read_b128 v[138:141], v142 offset:2048
	ds_read_b128 v[142:145], v142 offset:3072
	ds_read_b128 v[158:161], v152
	ds_read_b128 v[162:165], v152 offset:1024
	ds_read_b128 v[166:169], v152 offset:2048
	ds_read_b128 v[170:173], v152 offset:3072
	v_lshl_add_u64 v[152:153], s[22:23], 0, v[148:149]
	s_add_i32 m0, s5, 0xc000
	ds_read_b128 v[174:177], v157
	ds_read_b128 v[178:181], v157 offset:1024
	ds_read_b128 v[182:185], v157 offset:2048
	ds_read_b128 v[186:189], v157 offset:3072
	ds_read_b128 v[190:193], v157 offset:4096
	ds_read_b128 v[202:205], v157 offset:5120
	ds_read_b128 v[206:209], v157 offset:6144
	ds_read_b128 v[214:217], v157 offset:7168
	global_load_lds_dwordx4 v[152:153], off
	v_lshl_add_u64 v[152:153], s[22:23], 0, v[150:151]
	s_add_i32 m0, s5, 0xe000
	s_nop 0
	global_load_lds_dwordx4 v[152:153], off
	s_waitcnt vmcnt(8)
	s_waitcnt lgkmcnt(0)
	v_mfma_f32_16x16x32_bf16 v[126:129], v[130:133], v[174:177], v[126:129]
	v_mfma_f32_16x16x32_bf16 v[122:125], v[138:141], v[174:177], v[122:125]
	s_barrier
	s_setprio 1
	s_waitcnt lgkmcnt(0)
	v_mfma_f32_16x16x32_bf16 v[114:117], v[130:133], v[182:185], v[114:117]
	v_mfma_f32_16x16x32_bf16 v[110:113], v[138:141], v[182:185], v[110:113]
	v_mfma_f32_16x16x32_bf16 v[98:101], v[130:133], v[190:193], v[98:101]
	v_mfma_f32_16x16x32_bf16 v[92:95], v[138:141], v[190:193], v[92:95]
	v_mfma_f32_16x16x32_bf16 v[80:83], v[130:133], v[206:209], v[80:83]
	v_mfma_f32_16x16x32_bf16 v[76:79], v[138:141], v[206:209], v[76:79]
	v_mfma_f32_16x16x32_bf16 v[126:129], v[134:137], v[178:181], v[126:129]
	v_mfma_f32_16x16x32_bf16 v[122:125], v[142:145], v[178:181], v[122:125]
	v_mfma_f32_16x16x32_bf16 v[114:117], v[134:137], v[186:189], v[114:117]
	v_mfma_f32_16x16x32_bf16 v[110:113], v[142:145], v[186:189], v[110:113]
	v_mfma_f32_16x16x32_bf16 v[98:101], v[134:137], v[202:205], v[98:101]
	v_mfma_f32_16x16x32_bf16 v[92:95], v[142:145], v[202:205], v[92:95]
	v_mfma_f32_16x16x32_bf16 v[80:83], v[134:137], v[214:217], v[80:83]
	v_mfma_f32_16x16x32_bf16 v[76:79], v[142:145], v[214:217], v[76:79]
	s_setprio 0
	s_setprio 1
	v_mfma_f32_16x16x32_bf16 v[118:121], v[158:161], v[174:177], v[118:121]
	v_mfma_f32_16x16x32_bf16 v[106:109], v[166:169], v[174:177], v[106:109]
	v_mfma_f32_16x16x32_bf16 v[102:105], v[158:161], v[182:185], v[102:105]
	v_mfma_f32_16x16x32_bf16 v[88:91], v[166:169], v[182:185], v[88:91]
	v_mfma_f32_16x16x32_bf16 v[84:87], v[158:161], v[190:193], v[84:87]
	v_mfma_f32_16x16x32_bf16 v[72:75], v[166:169], v[190:193], v[72:75]
	v_mfma_f32_16x16x32_bf16 v[68:71], v[158:161], v[206:209], v[68:71]
	v_mfma_f32_16x16x32_bf16 v[64:67], v[166:169], v[206:209], v[64:67]
	v_mfma_f32_16x16x32_bf16 v[118:121], v[162:165], v[178:181], v[118:121]
	v_mfma_f32_16x16x32_bf16 v[106:109], v[170:173], v[178:181], v[106:109]
	v_mfma_f32_16x16x32_bf16 v[102:105], v[162:165], v[186:189], v[102:105]
	v_mfma_f32_16x16x32_bf16 v[88:91], v[170:173], v[186:189], v[88:91]
	v_mfma_f32_16x16x32_bf16 v[84:87], v[162:165], v[202:205], v[84:87]
	v_mfma_f32_16x16x32_bf16 v[72:75], v[170:173], v[202:205], v[72:75]
	v_mfma_f32_16x16x32_bf16 v[68:71], v[162:165], v[214:217], v[68:71]
	v_mfma_f32_16x16x32_bf16 v[64:67], v[170:173], v[214:217], v[64:67]
	s_setprio 0
	s_barrier
	s_add_i32 s22, s45, s4
	v_lshl_add_u64 v[152:153], s[34:35], 0, v[96:97]
	s_mov_b32 m0, s22
	ds_read_b128 v[174:177], v157 offset:16384
	ds_read_b128 v[178:181], v157 offset:17408
	ds_read_b128 v[182:185], v157 offset:18432
	ds_read_b128 v[186:189], v157 offset:19456
	ds_read_b128 v[190:193], v157 offset:20480
	ds_read_b128 v[202:205], v157 offset:21504
	ds_read_b128 v[206:209], v157 offset:22528
	ds_read_b128 v[214:217], v157 offset:23552
	global_load_lds_dwordx4 v[152:153], off
	s_add_i32 m0, s22, 0x2000
	s_add_u32 s22, s34, 0x160000
	v_lshl_add_u64 v[194:195], s[34:35], 0, v[146:147]
	s_addc_u32 s23, s35, 0
	s_add_i32 s45, s46, s4
	global_load_lds_dwordx4 v[194:195], off
	v_lshl_add_u64 v[198:199], s[22:23], 0, v[96:97]
	s_mov_b32 m0, s45
	v_lshl_add_u64 v[200:201], s[38:39], 0, v[146:147]
	global_load_lds_dwordx4 v[198:199], off
	v_lshl_add_u64 v[198:199], s[22:23], 0, v[146:147]
	s_add_i32 m0, s45, 0x2000
	s_nop 0
	global_load_lds_dwordx4 v[198:199], off
	v_lshl_add_u64 v[198:199], s[38:39], 0, v[96:97]
	s_mov_b32 m0, s5
	s_nop 0
	global_load_lds_dwordx4 v[198:199], off
	s_mov_b32 m0, s17
	s_nop 0
	global_load_lds_dwordx4 v[200:201], off
	s_waitcnt vmcnt(8)
	s_waitcnt lgkmcnt(0)
	v_mfma_f32_16x16x32_bf16 v[60:63], v[130:133], v[174:177], v[60:63]
	v_mfma_f32_16x16x32_bf16 v[56:59], v[138:141], v[174:177], v[56:59]
	s_barrier
	s_setprio 1
	s_waitcnt lgkmcnt(0)
	v_mfma_f32_16x16x32_bf16 v[48:51], v[130:133], v[182:185], v[48:51]
	v_mfma_f32_16x16x32_bf16 v[44:47], v[138:141], v[182:185], v[44:47]
	v_mfma_f32_16x16x32_bf16 v[32:35], v[130:133], v[190:193], v[32:35]
	v_mfma_f32_16x16x32_bf16 v[28:31], v[138:141], v[190:193], v[28:31]
	v_mfma_f32_16x16x32_bf16 v[16:19], v[130:133], v[206:209], v[16:19]
	v_mfma_f32_16x16x32_bf16 v[12:15], v[138:141], v[206:209], v[12:15]
	v_mfma_f32_16x16x32_bf16 v[60:63], v[134:137], v[178:181], v[60:63]
	v_mfma_f32_16x16x32_bf16 v[56:59], v[142:145], v[178:181], v[56:59]
	v_mfma_f32_16x16x32_bf16 v[48:51], v[134:137], v[186:189], v[48:51]
	v_mfma_f32_16x16x32_bf16 v[44:47], v[142:145], v[186:189], v[44:47]
	v_mfma_f32_16x16x32_bf16 v[32:35], v[134:137], v[202:205], v[32:35]
	v_mfma_f32_16x16x32_bf16 v[28:31], v[142:145], v[202:205], v[28:31]
	v_mfma_f32_16x16x32_bf16 v[16:19], v[134:137], v[214:217], v[16:19]
	v_mfma_f32_16x16x32_bf16 v[12:15], v[142:145], v[214:217], v[12:15]
	s_setprio 0
	s_setprio 1
	v_mfma_f32_16x16x32_bf16 v[52:55], v[158:161], v[174:177], v[52:55]
	v_mfma_f32_16x16x32_bf16 v[40:43], v[166:169], v[174:177], v[40:43]
	v_mfma_f32_16x16x32_bf16 v[36:39], v[158:161], v[182:185], v[36:39]
	v_mfma_f32_16x16x32_bf16 v[24:27], v[166:169], v[182:185], v[24:27]
	v_mfma_f32_16x16x32_bf16 v[20:23], v[158:161], v[190:193], v[20:23]
	v_mfma_f32_16x16x32_bf16 v[8:11], v[166:169], v[190:193], v[8:11]
	v_mfma_f32_16x16x32_bf16 v[4:7], v[158:161], v[206:209], v[4:7]
	v_mfma_f32_16x16x32_bf16 v[0:3], v[166:169], v[206:209], v[0:3]
	v_mfma_f32_16x16x32_bf16 v[52:55], v[162:165], v[178:181], v[52:55]
	v_mfma_f32_16x16x32_bf16 v[40:43], v[170:173], v[178:181], v[40:43]
	v_mfma_f32_16x16x32_bf16 v[36:39], v[162:165], v[186:189], v[36:39]
	v_mfma_f32_16x16x32_bf16 v[24:27], v[170:173], v[186:189], v[24:27]
	v_mfma_f32_16x16x32_bf16 v[20:23], v[162:165], v[202:205], v[20:23]
	v_mfma_f32_16x16x32_bf16 v[8:11], v[170:173], v[202:205], v[8:11]
	v_mfma_f32_16x16x32_bf16 v[4:7], v[162:165], v[214:217], v[4:7]
	v_mfma_f32_16x16x32_bf16 v[0:3], v[170:173], v[214:217], v[0:3]
	s_setprio 0
	s_barrier
	s_add_i32 s45, 0, 0x18000
	s_add_i32 s46, 0, 0x1c000
	v_add_u32_e32 v142, s45, v155
	v_add_u32_e32 v170, s46, v155
	ds_read_b128 v[130:133], v142
	ds_read_b128 v[134:137], v142 offset:1024
	ds_read_b128 v[138:141], v142 offset:2048
	ds_read_b128 v[142:145], v142 offset:3072
	ds_read_b128 v[158:161], v170
	ds_read_b128 v[162:165], v170 offset:1024
	ds_read_b128 v[166:169], v170 offset:2048
	ds_read_b128 v[170:173], v170 offset:3072
	s_add_u32 s22, s38, 0x160000
	s_addc_u32 s23, s39, 0
	s_mov_b32 m0, s18
	v_lshl_add_u64 v[218:219], s[22:23], 0, v[96:97]
	ds_read_b128 v[174:177], v157 offset:32768
	ds_read_b128 v[178:181], v157 offset:33792
	ds_read_b128 v[182:185], v157 offset:34816
	ds_read_b128 v[186:189], v157 offset:35840
	ds_read_b128 v[190:193], v157 offset:36864
	ds_read_b128 v[202:205], v157 offset:37888
	ds_read_b128 v[206:209], v157 offset:38912
	ds_read_b128 v[214:217], v157 offset:39936
	global_load_lds_dwordx4 v[218:219], off
	v_lshl_add_u64 v[218:219], s[22:23], 0, v[146:147]
	s_mov_b32 m0, s19
	s_nop 0
	global_load_lds_dwordx4 v[218:219], off
	s_waitcnt vmcnt(8)
	s_waitcnt lgkmcnt(0)
	v_mfma_f32_16x16x32_bf16 v[126:129], v[130:133], v[174:177], v[126:129]
	v_mfma_f32_16x16x32_bf16 v[122:125], v[138:141], v[174:177], v[122:125]
	s_barrier
	s_setprio 1
	s_waitcnt lgkmcnt(0)
	v_mfma_f32_16x16x32_bf16 v[114:117], v[130:133], v[182:185], v[114:117]
	v_mfma_f32_16x16x32_bf16 v[110:113], v[138:141], v[182:185], v[110:113]
	v_mfma_f32_16x16x32_bf16 v[98:101], v[130:133], v[190:193], v[98:101]
	v_mfma_f32_16x16x32_bf16 v[92:95], v[138:141], v[190:193], v[92:95]
	v_mfma_f32_16x16x32_bf16 v[80:83], v[130:133], v[206:209], v[80:83]
	v_mfma_f32_16x16x32_bf16 v[76:79], v[138:141], v[206:209], v[76:79]
	v_mfma_f32_16x16x32_bf16 v[126:129], v[134:137], v[178:181], v[126:129]
	v_mfma_f32_16x16x32_bf16 v[122:125], v[142:145], v[178:181], v[122:125]
	v_mfma_f32_16x16x32_bf16 v[114:117], v[134:137], v[186:189], v[114:117]
	v_mfma_f32_16x16x32_bf16 v[110:113], v[142:145], v[186:189], v[110:113]
	v_mfma_f32_16x16x32_bf16 v[98:101], v[134:137], v[202:205], v[98:101]
	v_mfma_f32_16x16x32_bf16 v[92:95], v[142:145], v[202:205], v[92:95]
	v_mfma_f32_16x16x32_bf16 v[80:83], v[134:137], v[214:217], v[80:83]
	v_mfma_f32_16x16x32_bf16 v[76:79], v[142:145], v[214:217], v[76:79]
	s_setprio 0
	s_setprio 1
	v_mfma_f32_16x16x32_bf16 v[118:121], v[158:161], v[174:177], v[118:121]
	v_mfma_f32_16x16x32_bf16 v[106:109], v[166:169], v[174:177], v[106:109]
	v_mfma_f32_16x16x32_bf16 v[102:105], v[158:161], v[182:185], v[102:105]
	v_mfma_f32_16x16x32_bf16 v[88:91], v[166:169], v[182:185], v[88:91]
	v_mfma_f32_16x16x32_bf16 v[84:87], v[158:161], v[190:193], v[84:87]
	v_mfma_f32_16x16x32_bf16 v[72:75], v[166:169], v[190:193], v[72:75]
	v_mfma_f32_16x16x32_bf16 v[68:71], v[158:161], v[206:209], v[68:71]
	v_mfma_f32_16x16x32_bf16 v[64:67], v[166:169], v[206:209], v[64:67]
	v_mfma_f32_16x16x32_bf16 v[118:121], v[162:165], v[178:181], v[118:121]
	v_mfma_f32_16x16x32_bf16 v[106:109], v[170:173], v[178:181], v[106:109]
	v_mfma_f32_16x16x32_bf16 v[102:105], v[162:165], v[186:189], v[102:105]
	v_mfma_f32_16x16x32_bf16 v[88:91], v[170:173], v[186:189], v[88:91]
	v_mfma_f32_16x16x32_bf16 v[84:87], v[162:165], v[202:205], v[84:87]
	v_mfma_f32_16x16x32_bf16 v[72:75], v[170:173], v[202:205], v[72:75]
	v_mfma_f32_16x16x32_bf16 v[68:71], v[162:165], v[214:217], v[68:71]
	v_mfma_f32_16x16x32_bf16 v[64:67], v[170:173], v[214:217], v[64:67]
	s_setprio 0
	s_barrier
	s_add_i32 s22, s45, s4
	v_lshl_add_u64 v[152:153], v[152:153], 0, s[30:31]
	s_mov_b32 m0, s22
	ds_read_b128 v[174:177], v157 offset:49152
	ds_read_b128 v[178:181], v157 offset:50176
	ds_read_b128 v[182:185], v157 offset:51200
	ds_read_b128 v[186:189], v157 offset:52224
	ds_read_b128 v[190:193], v157 offset:53248
	ds_read_b128 v[202:205], v157 offset:54272
	ds_read_b128 v[206:209], v157 offset:55296
	ds_read_b128 v[214:217], v157 offset:56320
	global_load_lds_dwordx4 v[152:153], off
	s_add_i32 m0, s22, 0x2000
	s_add_u32 s22, s34, 0x160080
	v_lshl_add_u64 v[152:153], v[194:195], 0, s[30:31]
	s_addc_u32 s23, s35, 0
	s_add_i32 s34, s46, s4
	global_load_lds_dwordx4 v[152:153], off
	v_lshl_add_u64 v[152:153], s[22:23], 0, v[96:97]
	s_mov_b32 m0, s34
	s_nop 0
	global_load_lds_dwordx4 v[152:153], off
	v_lshl_add_u64 v[152:153], s[22:23], 0, v[146:147]
	s_add_i32 m0, s34, 0x2000
	s_nop 0
	global_load_lds_dwordx4 v[152:153], off
	v_lshl_add_u64 v[152:153], v[198:199], 0, s[30:31]
	s_mov_b32 m0, s20
	s_nop 0
	global_load_lds_dwordx4 v[152:153], off
	v_lshl_add_u64 v[152:153], v[200:201], 0, s[30:31]
	s_mov_b32 m0, s36
	s_nop 0
	global_load_lds_dwordx4 v[152:153], off
	s_waitcnt vmcnt(8)
	s_waitcnt lgkmcnt(0)
	v_mfma_f32_16x16x32_bf16 v[60:63], v[130:133], v[174:177], v[60:63]
	v_mfma_f32_16x16x32_bf16 v[56:59], v[138:141], v[174:177], v[56:59]
	s_barrier
	s_setprio 1
	s_waitcnt lgkmcnt(0)
	v_mfma_f32_16x16x32_bf16 v[48:51], v[130:133], v[182:185], v[48:51]
	v_mfma_f32_16x16x32_bf16 v[44:47], v[138:141], v[182:185], v[44:47]
	v_mfma_f32_16x16x32_bf16 v[32:35], v[130:133], v[190:193], v[32:35]
	v_mfma_f32_16x16x32_bf16 v[28:31], v[138:141], v[190:193], v[28:31]
	v_mfma_f32_16x16x32_bf16 v[16:19], v[130:133], v[206:209], v[16:19]
	v_mfma_f32_16x16x32_bf16 v[12:15], v[138:141], v[206:209], v[12:15]
	v_mfma_f32_16x16x32_bf16 v[60:63], v[134:137], v[178:181], v[60:63]
	v_mfma_f32_16x16x32_bf16 v[56:59], v[142:145], v[178:181], v[56:59]
	v_mfma_f32_16x16x32_bf16 v[48:51], v[134:137], v[186:189], v[48:51]
	v_mfma_f32_16x16x32_bf16 v[44:47], v[142:145], v[186:189], v[44:47]
	v_mfma_f32_16x16x32_bf16 v[32:35], v[134:137], v[202:205], v[32:35]
	v_mfma_f32_16x16x32_bf16 v[28:31], v[142:145], v[202:205], v[28:31]
	v_mfma_f32_16x16x32_bf16 v[16:19], v[134:137], v[214:217], v[16:19]
	v_mfma_f32_16x16x32_bf16 v[12:15], v[142:145], v[214:217], v[12:15]
	s_setprio 0
	s_setprio 1
	v_mfma_f32_16x16x32_bf16 v[52:55], v[158:161], v[174:177], v[52:55]
	v_mfma_f32_16x16x32_bf16 v[40:43], v[166:169], v[174:177], v[40:43]
	v_mfma_f32_16x16x32_bf16 v[36:39], v[158:161], v[182:185], v[36:39]
	v_mfma_f32_16x16x32_bf16 v[24:27], v[166:169], v[182:185], v[24:27]
	v_mfma_f32_16x16x32_bf16 v[20:23], v[158:161], v[190:193], v[20:23]
	v_mfma_f32_16x16x32_bf16 v[8:11], v[166:169], v[190:193], v[8:11]
	v_mfma_f32_16x16x32_bf16 v[4:7], v[158:161], v[206:209], v[4:7]
	v_mfma_f32_16x16x32_bf16 v[0:3], v[166:169], v[206:209], v[0:3]
	v_mfma_f32_16x16x32_bf16 v[52:55], v[162:165], v[178:181], v[52:55]
	v_mfma_f32_16x16x32_bf16 v[40:43], v[170:173], v[178:181], v[40:43]
	v_mfma_f32_16x16x32_bf16 v[36:39], v[162:165], v[186:189], v[36:39]
	v_mfma_f32_16x16x32_bf16 v[24:27], v[170:173], v[186:189], v[24:27]
	v_mfma_f32_16x16x32_bf16 v[20:23], v[162:165], v[202:205], v[20:23]
	v_mfma_f32_16x16x32_bf16 v[8:11], v[170:173], v[202:205], v[8:11]
	v_mfma_f32_16x16x32_bf16 v[4:7], v[162:165], v[214:217], v[4:7]
	v_mfma_f32_16x16x32_bf16 v[0:3], v[170:173], v[214:217], v[0:3]
	s_setprio 0
	s_barrier
	s_add_i32 s6, s6, 2
	s_add_u32 s2, s2, 0x100
	s_addc_u32 s3, s3, 0
	s_cmpk_gt_u32 s6, 0x55
	s_mov_b64 s[22:23], s[24:25]
	s_cbranch_scc0 .LBB0_1413
	s_and_b64 vcc, exec, s[10:11]
	s_cbranch_vccz .LBB0_1416
	s_barrier
